# plus weights also stored slice-major by P0 for 1KB-contiguous B LDS-DMA in wide GEMM K loops; E1a sample-tile rope staged in LDS; LayerNorm wave reductions via DPP row_ror + readlane
# speedup vs baseline: 1.0124x; 1.0124x over previous
;   DI u16* Wt_in_e() const { return (u16*)(ws + WS_Wt_in_e); }
;   DI u16* Wt_uv() const { return (u16*)(ws + WS_Wt_uv); }
;   DI u16* Wt_out_e() const { return (u16*)(ws + WS_Wt_out_e); }
;   DI u16* Wt_in_o() const { return (u16*)(ws + WS_Wt_in_o); }
;   DI u16* Wt_out_o() const { return (u16*)(ws + WS_Wt_out_o); }
; DI void transpose_tile(const float* __restrict__ src, int N, int Kdim, int k0, int n0, u16* __restrict__ dst, int remap, char* smem) {
;     ...
;   int nr = tid >> 2, kc = (tid & 3) * 16;
;   int n = n0 + nr;
;   if (n < N) {
;     int nrow = remap ? (n < 416 ? n : n + 96) : n;
;     float v[16];
; #pragma unroll
;     for (int e = 0; e < 16; ++e) v[e] = tl[nr * 65 + kc + e];
;     uint4 a, b;
;     a.x = pk2(v[0], v[1]); a.y = pk2(v[2], v[3]); a.z = pk2(v[4], v[5]); a.w = pk2(v[6], v[7]);
;     b.x = pk2(v[8], v[9]); b.y = pk2(v[10], v[11]); b.z = pk2(v[12], v[13]); b.w = pk2(v[14], v[15]);
;     u16* d = dst + (size_t)nrow * Kdim + k0 + kc;
;     *(uint4*)d = a; *(uint4*)(d + 8) = b;
; DI void phase_p0(const Params& p, char* smem) {
;     ...
;   for (int j = blockIdx.x; j < NA + NB + NC + ND + NE; j += gridDim.x) {
;     if (j < NA) transpose_tile(p.w_in_even, 2976, 1024, (j / 47) * 64, (j % 47) * 64, p.Wt_in_e(), 1, smem);
;     else if (j < NA + NB) { int q = j - NA; transpose_tile(p.w_uv, 512, 128, (q / 8) * 64, (q % 8) * 64, p.Wt_uv(), 0, smem); }
;     else if (j < NA + NB + NC) { int q = j - NA - NB; transpose_tile(p.w_out_even, 1024, 1024, (q / 16) * 64, (q % 16) * 64, p.Wt_out_e(), 0, smem); }
;     else if (j < NA + NB + NC + ND) { int q = j - NA - NB - NC; transpose_tile(p.w_in_odd, 4096, 1024, (q / 64) * 64, (q % 64) * 64, p.Wt_in_o(), 0, smem); }
;     else { int q = j - NA - NB - NC - ND; transpose_tile(p.w_out_odd, 1024, 1024, (q / 16) * 64, (q % 16) * 64, p.Wt_out_o(), 0, smem); }
.LBB0_57:
	s_and_saveexec_b64 s[16:17], s[14:15]
	s_cbranch_execz .LBB0_22
	v_lshl_add_u64 v[14:15], v[12:13], 1, v[14:15]
	global_store_dwordx4 v[14:15], v[4:7], off
	global_store_dwordx4 v[14:15], v[0:3], off offset:16
	v_subrev_u32_e32 v200, s86, v14
	s_nop 0
	v_readfirstlane_b32 s98, v200
	s_mov_b32 s99, 0x2108000
	s_mov_b32 s100, 0x30000
	s_cmp_ge_u32 s98, 0x27a8000
	s_cbranch_scc0 .Lp0_cp_go
	s_cmp_lt_u32 s98, 0x27c8000
	s_cbranch_scc1 .Lp0_cp_skip
	s_mov_b32 s99, 0x27c8000
	s_mov_b32 s100, 0x10000
	s_cmp_ge_u32 s98, 0x29c8000
	s_cbranch_scc0 .Lp0_cp_go
	s_mov_b32 s99, 0x29c8000
	s_mov_b32 s100, 0x40000
	s_cmp_ge_u32 s98, 0x31c8000
	s_cbranch_scc0 .Lp0_cp_go
	s_mov_b32 s99, 0x31c8000
	s_mov_b32 s100, 0x10000
.Lp0_cp_go:
	v_subrev_u32_e32 v200, s99, v200
	v_lshrrev_b32_e32 v201, 11, v200
	v_and_b32_e32 v202, 0x7ff, v200
	v_lshrrev_b32_e32 v203, 6, v202
	v_and_b32_e32 v202, 63, v202
	v_mul_lo_u32 v203, v203, s100
	v_lshl_add_u32 v202, v201, 6, v202
	v_add_u32_e32 v202, v202, v203
	s_add_u32 s99, s99, 0x1a409000
	v_add_u32_e32 v202, s99, v202
	global_store_dwordx4 v202, v[4:7], s[86:87]
	global_store_dwordx4 v202, v[0:3], s[86:87] offset:16
.Lp0_cp_skip:
	s_branch .LBB0_22
.LBB0_59:
	s_mov_b64 s[0:1], 0x3000
	v_cmp_gt_u64_e32 vcc, s[0:1], v[8:9]
	s_and_saveexec_b64 s[0:1], vcc
	s_cbranch_execz .LBB0_62
	v_readlane_b32 s4, v247, 4
	v_readlane_b32 s5, v247, 5
	s_lshl_b64 s[4:5], s[4:5], 12
	s_add_u32 s4, s86, s4
	s_addc_u32 s5, s87, s5
	v_lshl_add_u64 v[0:1], v[10:11], 4, s[4:5]
	s_mov_b64 s[4:5], 0x21d8000
	v_lshl_add_u64 v[4:5], v[0:1], 0, s[4:5]
	v_readlane_b32 s4, v247, 6
	v_readlane_b32 s5, v247, 7
	v_mov_b32_e32 v0, 0
	s_lshl_b64 s[4:5], s[4:5], 12
	s_mov_b64 s[6:7], 0
	v_mov_b32_e32 v1, v0
	v_mov_b32_e32 v2, v0
	v_mov_b32_e32 v3, v0
	s_mov_b64 s[8:9], 0x2fff
	v_mov_b64_e32 v[6:7], v[8:9]

; template <int K, typename Epi>
; DI void gemm_tile_wide(const u16* __restrict__ A, int lda, const u16* __restrict__ Bt, int ldb, int m0, int n0, char* smem, Epi epi) {
;     ...
;   f32x16 acc[2][4];
; #pragma unroll
;   for (int i = 0; i < 2; ++i)
; #pragma unroll
;     for (int j = 0; j < 4; ++j)
; #pragma unroll
;       for (int e = 0; e < 16; ++e) acc[i][j][e] = 0.f;
;   constexpr int NS = K / 32;
;   constexpr int AB = 128 * 64;
;   constexpr int STB = AB + 256 * 64;
;   const int lrow = tid >> 2, cpos = tid & 3;
;   const u16* ap[2]; const u16* bp[4];
; #pragma unroll
;   for (int i = 0; i < 4; ++i) {
;     const int row = lrow + 64 * i;
;     const int sc = cpos ^ ((row >> 2) & 3);
;     if (i < 2) ap[i] = A + (size_t)(m0 + row) * lda + sc * 8;
;     bp[i] = Bt + (size_t)(n0 + row) * ldb + sc * 8;
;   }
;   char* const ldst = smem + tid * 16;
;   int aoff[2][2], boff[4][2];
; #pragma unroll
;   for (int kk = 0; kk < 2; ++kk) {
; #pragma unroll
;     for (int i = 0; i < 2; ++i) { const int ra_ = wm * 64 + i * 32 + r; aoff[i][kk] = ra_ * 64 + (((2 * kk + h) ^ ((ra_ >> 2) & 3)) << 4); }
; #pragma unroll
;     for (int j = 0; j < 4; ++j) { const int rb_ = wn * 128 + j * 32 + r; boff[j][kk] = AB + rb_ * 64 + (((2 * kk + h) ^ ((rb_ >> 2) & 3)) << 4); }
;   }
;   auto issue = [&](int slice, int st) {
; #pragma unroll
;     for (int i = 0; i < 4; ++i) {
;       if (i < 2) __builtin_amdgcn_global_load_lds((const unsigned*)(ap[i] + slice * 32), (unsigned*)(ldst + st + i * 4096), 16, 0, 0);
;       __builtin_amdgcn_global_load_lds((const unsigned*)(bp[i] + slice * 32), (unsigned*)(ldst + st + AB + i * 4096), 16, 0, 0);
;     }
;   };
;   __syncthreads();
;   issue(0, 0);
.LBB0_141:
	s_mul_hi_i32 s0, s88, 0x2aaaaaab
	s_lshr_b32 s1, s0, 31
	s_ashr_i32 s22, s0, 1
	v_mov_b32_e32 v24, v186
	s_add_i32 s22, s22, s1
	s_mul_i32 s0, s22, 12
	v_lshrrev_b32_e32 v26, 4, v24
	s_waitcnt lgkmcnt(0)
	v_xor_b32_e32 v0, v26, v24
	s_sub_i32 s12, s88, s0
	v_lshlrev_b32_e32 v0, 4, v0
	v_readlane_b32 s0, v247, 32
	s_lshl_b32 s21, s22, 7
	v_ashrrev_i32_e32 v14, 2, v24
	v_and_b32_e32 v136, 48, v0
	v_readlane_b32 s1, v247, 33
	s_lshl_b32 s96, s12, 8
	v_add_u32_e32 v4, s21, v14
	v_lshl_add_u64 v[0:1], s[0:1], 0, v[136:137]
	v_readlane_b32 s0, v247, 30
	v_readlane_b32 s1, v247, 31
	v_ashrrev_i32_e32 v5, 31, v4
	v_add_u32_e32 v8, s96, v14
	v_lshlrev_b32_e32 v147, 4, v24
	v_lshl_add_u64 v[2:3], s[0:1], 0, v[136:137]
	v_lshlrev_b64 v[4:5], 11, v[4:5]
	v_ashrrev_i32_e32 v9, 31, v8
	v_readfirstlane_b32 s0, v147
	v_lshl_add_u64 v[6:7], v[2:3], 0, v[4:5]
	v_lshlrev_b64 v[10:11], 11, v[8:9]
	v_add_u32_e32 v9, 64, v14
	s_mov_b32 m0, s0
	v_add_u32_e32 v14, s21, v9
	s_barrier
	global_load_lds_dwordx4 v[6:7], off
	v_add_u32_e32 v6, 0x2000, v147
	v_ashrrev_i32_e32 v15, 31, v14
	v_readfirstlane_b32 s0, v6
	v_add_u32_e32 v6, 0x1000, v147
	v_lshl_add_u64 v[12:13], v[0:1], 0, v[10:11]
	v_lshlrev_b64 v[14:15], 11, v[14:15]
	s_mov_b32 m0, s0
	v_readfirstlane_b32 s0, v6
	v_lshl_add_u64 v[2:3], v[2:3], 0, v[14:15]
	v_add_u32_e32 v16, s96, v9
	global_load_lds_dwordx4 v[12:13], off
	s_mov_b32 m0, s0
	v_ashrrev_i32_e32 v17, 31, v16
	v_add_u32_e32 v20, 0x80, v8
	global_load_lds_dwordx4 v[2:3], off
	v_add_u32_e32 v2, 0x3000, v147
	v_lshlrev_b64 v[16:17], 11, v[16:17]
	v_ashrrev_i32_e32 v21, 31, v20
	v_add_u32_e32 v8, 0xc0, v8
	v_readfirstlane_b32 s0, v2
	v_add_u32_e32 v2, 0x4000, v147
	v_lshl_add_u64 v[18:19], v[0:1], 0, v[16:17]
	v_lshlrev_b64 v[20:21], 11, v[20:21]
	v_ashrrev_i32_e32 v9, 31, v8
	s_mov_b32 m0, s0
	v_readfirstlane_b32 s0, v2
	v_add_u32_e32 v2, 0x5000, v147
	v_lshl_add_u64 v[22:23], v[0:1], 0, v[20:21]
	v_lshlrev_b64 v[8:9], 11, v[8:9]
	global_load_lds_dwordx4 v[18:19], off
	s_mov_b32 m0, s0
	v_readfirstlane_b32 s0, v2
	v_lshl_add_u64 v[0:1], v[0:1], 0, v[8:9]
	global_load_lds_dwordx4 v[22:23], off
	s_mov_b32 m0, s0
	v_lshrrev_b32_e32 v25, 5, v24
	global_load_lds_dwordx4 v[0:1], off
	v_bfe_u32 v143, v24, 5, 1
	v_and_b32_e32 v144, 31, v24
	v_bfe_u32 v27, v24, 2, 2
	v_bfe_u32 v136, v24, 6, 1
	v_lshlrev_b32_e32 v28, 6, v144
	v_bitop3_b32 v25, v25, v27, 1 bitop3:0x6c
	v_bitop3_b32 v27, v143, v27, 2 bitop3:0x36
	v_bitop3_b32 v0, v26, 3, v24 bitop3:0x48
	v_ashrrev_i32_e32 v142, 7, v24
	v_lshl_or_b32 v29, v136, 13, v28
	v_lshlrev_b32_e32 v25, 4, v25
	v_lshlrev_b32_e32 v27, 4, v27
	v_lshlrev_b32_e32 v0, 4, v0
	v_lshl_or_b32 v28, v142, 12, v28
	v_or_b32_e32 v148, v29, v25
	v_or_b32_e32 v150, v27, v29
	v_or_b32_e32 v4, v4, v0
	v_or_b32_e32 v10, v10, v0
	v_or_b32_e32 v14, v14, v0
	v_or_b32_e32 v16, v16, v0
	v_or_b32_e32 v20, v20, v0
	v_or_b32_e32 v8, v8, v0
	v_or_b32_e32 v145, v25, v28
	v_or_b32_e32 v146, v27, v28
	v_add_u32_e32 v149, 0x2000, v148
	v_or_b32_e32 v151, 0x800, v150
	v_or_b32_e32 v152, 0x1000, v150
	v_or_b32_e32 v153, 0x1800, v150
	v_lshl_add_u64 v[128:129], s[92:93], 0, v[4:5]
	v_lshl_add_u64 v[130:131], s[94:95], 0, v[10:11]
	v_lshl_add_u64 v[132:133], s[92:93], 0, v[14:15]
	v_lshl_add_u64 v[134:135], s[94:95], 0, v[16:17]
	v_lshl_add_u64 v[138:139], s[94:95], 0, v[20:21]
	v_lshl_add_u64 v[140:141], s[94:95], 0, v[8:9]
	s_mov_b64 s[0:1], 0
	s_mov_b32 s2, 0
	s_mov_b32 s99, s96
	v_lshrrev_b32_e32 v240, 4, v186
	v_xor_b32_e32 v240, v240, v186
	v_and_b32_e32 v240, 3, v240
	v_lshlrev_b32_e32 v240, 4, v240
	v_lshrrev_b32_e32 v241, 2, v186
	v_add_u32_e32 v241, s99, v241
	v_lshl_add_u32 v240, v241, 6, v240
	v_mov_b32_e32 v241, 0
	s_add_u32 s100, s86, 0x1c541000
	s_addc_u32 s101, s87, 0
	v_lshl_add_u64 v[130:131], s[100:101], 0, v[240:241]
	v_add_u32_e32 v240, 0x1000, v240
	v_lshl_add_u64 v[134:135], s[100:101], 0, v[240:241]
	v_add_u32_e32 v240, 0x1000, v240
	v_lshl_add_u64 v[138:139], s[100:101], 0, v[240:241]
	v_add_u32_e32 v240, 0x1000, v240
	v_lshl_add_u64 v[140:141], s[100:101], 0, v[240:241]
	s_mov_b64 s[100:101], 0
	v_mov_b32_e32 v0, v137
	v_mov_b32_e32 v1, v137
	v_mov_b32_e32 v2, v137
	v_mov_b32_e32 v3, v137
	v_mov_b32_e32 v4, v137
	v_mov_b32_e32 v5, v137
	v_mov_b32_e32 v6, v137
	v_mov_b32_e32 v7, v137
	v_mov_b32_e32 v8, v137
	v_mov_b32_e32 v9, v137
	v_mov_b32_e32 v10, v137
	v_mov_b32_e32 v11, v137
	v_mov_b32_e32 v12, v137
	v_mov_b32_e32 v13, v137
	v_mov_b32_e32 v14, v137
	v_mov_b32_e32 v15, v137
	v_mov_b32_e32 v48, v137
	v_mov_b32_e32 v49, v137
	v_mov_b32_e32 v50, v137
	v_mov_b32_e32 v51, v137
	v_mov_b32_e32 v52, v137
	v_mov_b32_e32 v53, v137
	v_mov_b32_e32 v54, v137
	v_mov_b32_e32 v55, v137
	v_mov_b32_e32 v56, v137
	v_mov_b32_e32 v57, v137
	v_mov_b32_e32 v58, v137
	v_mov_b32_e32 v59, v137
	v_mov_b32_e32 v60, v137
	v_mov_b32_e32 v61, v137
	v_mov_b32_e32 v62, v137
	v_mov_b32_e32 v63, v137
	v_mov_b32_e32 v16, v137
	v_mov_b32_e32 v17, v137
	v_mov_b32_e32 v18, v137
	v_mov_b32_e32 v19, v137
	v_mov_b32_e32 v20, v137
	v_mov_b32_e32 v21, v137
	v_mov_b32_e32 v22, v137
	v_mov_b32_e32 v23, v137
	v_mov_b32_e32 v24, v137
	v_mov_b32_e32 v25, v137
	v_mov_b32_e32 v26, v137
	v_mov_b32_e32 v27, v137
	v_mov_b32_e32 v28, v137
	v_mov_b32_e32 v29, v137
	v_mov_b32_e32 v30, v137
	v_mov_b32_e32 v31, v137
	v_mov_b32_e32 v64, v137
	v_mov_b32_e32 v65, v137
	v_mov_b32_e32 v66, v137
	v_mov_b32_e32 v67, v137
	v_mov_b32_e32 v68, v137
	v_mov_b32_e32 v69, v137
	v_mov_b32_e32 v70, v137
	v_mov_b32_e32 v71, v137
	v_mov_b32_e32 v72, v137
	v_mov_b32_e32 v73, v137
	v_mov_b32_e32 v74, v137
	v_mov_b32_e32 v75, v137
	v_mov_b32_e32 v76, v137
	v_mov_b32_e32 v77, v137
; #define MFMA(a, b, c) __builtin_amdgcn_mfma_f32_32x32x16_bf16((a), (b), (c), 0, 0, 0)
; template <int K, typename Epi>
; DI void gemm_tile_wide(const u16* __restrict__ A, int lda, const u16* __restrict__ Bt, int ldb, int m0, int n0, char* smem, Epi epi) {
;     ...
;   for (int kt = 0; kt < NS; ++kt) {
;     asm volatile("s_waitcnt vmcnt(0)" ::: "memory");
;     __syncthreads();
;     const int cur = (kt & 1) * STB;
;     if (kt + 1 < NS) issue(kt + 1, STB - cur);
;     const char* Sg = smem + cur;
;     bf16x8 a[2][2], b[2][4];
; #pragma unroll
;     for (int kk = 0; kk < 2; ++kk) {
; #pragma unroll
;       for (int i = 0; i < 2; ++i) a[kk][i] = *(const bf16x8*)(Sg + aoff[i][kk]);
; #pragma unroll
;       for (int j = 0; j < 4; ++j) b[kk][j] = *(const bf16x8*)(Sg + boff[j][kk]);
;     }
;     __builtin_amdgcn_sched_barrier(0);
;     __builtin_amdgcn_s_setprio(1);
; #pragma unroll
;     for (int kk = 0; kk < 2; ++kk)
; #pragma unroll
;       for (int i = 0; i < 2; ++i)
; #pragma unroll
;         for (int j = 0; j < 4; ++j) acc[i][j] = MFMA(a[kk][i], b[kk][j], acc[i][j]);
;     __builtin_amdgcn_s_setprio(0);
;   }
	v_mov_b32_e32 v78, v137
	v_mov_b32_e32 v79, v137
	v_mov_b32_e32 v32, v137
	v_mov_b32_e32 v33, v137
	v_mov_b32_e32 v34, v137
	v_mov_b32_e32 v35, v137
	v_mov_b32_e32 v36, v137
	v_mov_b32_e32 v37, v137
	v_mov_b32_e32 v38, v137
	v_mov_b32_e32 v39, v137
	v_mov_b32_e32 v40, v137
	v_mov_b32_e32 v41, v137
	v_mov_b32_e32 v42, v137
	v_mov_b32_e32 v43, v137
	v_mov_b32_e32 v44, v137
	v_mov_b32_e32 v45, v137
	v_mov_b32_e32 v46, v137
	v_mov_b32_e32 v47, v137
	v_mov_b32_e32 v96, v137
	v_mov_b32_e32 v97, v137
	v_mov_b32_e32 v98, v137
	v_mov_b32_e32 v99, v137
	v_mov_b32_e32 v100, v137
	v_mov_b32_e32 v101, v137
	v_mov_b32_e32 v102, v137
	v_mov_b32_e32 v103, v137
	v_mov_b32_e32 v104, v137
	v_mov_b32_e32 v105, v137
	v_mov_b32_e32 v106, v137
	v_mov_b32_e32 v107, v137
	v_mov_b32_e32 v108, v137
	v_mov_b32_e32 v109, v137
	v_mov_b32_e32 v110, v137
	v_mov_b32_e32 v111, v137
	v_mov_b32_e32 v80, v137
	v_mov_b32_e32 v81, v137
	v_mov_b32_e32 v82, v137
	v_mov_b32_e32 v83, v137
	v_mov_b32_e32 v84, v137
	v_mov_b32_e32 v85, v137
	v_mov_b32_e32 v86, v137
	v_mov_b32_e32 v87, v137
	v_mov_b32_e32 v88, v137
	v_mov_b32_e32 v89, v137
	v_mov_b32_e32 v90, v137
	v_mov_b32_e32 v91, v137
	v_mov_b32_e32 v92, v137
	v_mov_b32_e32 v93, v137
	v_mov_b32_e32 v94, v137
	v_mov_b32_e32 v95, v137
	v_mov_b32_e32 v112, v137
	v_mov_b32_e32 v113, v137
	v_mov_b32_e32 v114, v137
	v_mov_b32_e32 v115, v137
	v_mov_b32_e32 v116, v137
	v_mov_b32_e32 v117, v137
	v_mov_b32_e32 v118, v137
	v_mov_b32_e32 v119, v137
	v_mov_b32_e32 v120, v137
	v_mov_b32_e32 v121, v137
	v_mov_b32_e32 v122, v137
	v_mov_b32_e32 v123, v137
	v_mov_b32_e32 v124, v137
	v_mov_b32_e32 v125, v137
	v_mov_b32_e32 v126, v137
	v_mov_b32_e32 v127, v137
.LBB0_142:
	s_bitcmp1_b32 s2, 0
	s_cselect_b32 s3, 0x6000, 0
	v_subrev_u32_e32 v156, s3, v147
	v_add_u32_e32 v157, 0x6000, v156
	v_lshl_add_u64 v[154:155], v[128:129], 0, s[0:1]
	v_readfirstlane_b32 s4, v157
	v_add_u32_e32 v157, 0x8000, v156
	s_mov_b32 m0, s4
	v_readfirstlane_b32 s4, v157
	v_add_u32_e32 v157, 0x7000, v156
	s_waitcnt vmcnt(0)
	s_waitcnt vmcnt(0) lgkmcnt(0)
	s_barrier
	global_load_lds_dwordx4 v[154:155], off
	v_lshl_add_u64 v[154:155], v[130:131], 0, s[100:101]
	s_mov_b32 m0, s4
	v_readfirstlane_b32 s4, v157
	v_add_u32_e32 v157, 0x9000, v156
	global_load_lds_dwordx4 v[154:155], off
	v_lshl_add_u64 v[154:155], v[132:133], 0, s[0:1]
	s_mov_b32 m0, s4
	v_readfirstlane_b32 s4, v157
	v_add_u32_e32 v157, 0xa000, v156
	global_load_lds_dwordx4 v[154:155], off
	v_lshl_add_u64 v[154:155], v[134:135], 0, s[100:101]
	s_mov_b32 m0, s4
	v_readfirstlane_b32 s4, v157
	v_add_u32_e32 v156, 0xb000, v156
	global_load_lds_dwordx4 v[154:155], off
	v_lshl_add_u64 v[154:155], v[138:139], 0, s[100:101]
	s_mov_b32 m0, s4
	v_readfirstlane_b32 s4, v156
	global_load_lds_dwordx4 v[154:155], off
	v_lshl_add_u64 v[154:155], v[140:141], 0, s[100:101]
	s_mov_b32 m0, s4
	v_add_u32_e32 v158, s3, v145
	global_load_lds_dwordx4 v[154:155], off
	v_add_u32_e32 v162, s3, v148
	ds_read_b128 v[154:157], v158
	ds_read_b128 v[158:161], v158 offset:2048
	ds_read_b128 v[168:171], v162 offset:8192
	v_add_u32_e32 v162, s3, v149
	ds_read_b128 v[172:175], v162 offset:2048
	ds_read_b128 v[176:179], v162 offset:4096
	ds_read_b128 v[180:183], v162 offset:6144
	v_add_u32_e32 v162, s3, v146
	ds_read_b128 v[188:191], v162
	ds_read_b128 v[192:195], v162 offset:2048
	v_add_u32_e32 v162, s3, v150
	ds_read_b128 v[196:199], v162 offset:8192
	v_add_u32_e32 v162, s3, v151
	ds_read_b128 v[200:203], v162 offset:8192
	v_add_u32_e32 v162, s3, v152
	ds_read_b128 v[204:207], v162 offset:8192
	v_add_u32_e32 v162, s3, v153
	ds_read_b128 v[208:211], v162 offset:8192
	s_add_i32 s2, s2, 1
	s_setprio 1
	s_waitcnt lgkmcnt(0)
	v_mfma_f32_32x32x16_bf16 v[0:15], v[154:157], v[168:171], v[0:15]
	v_mfma_f32_32x32x16_bf16 v[48:63], v[154:157], v[172:175], v[48:63]
	v_mfma_f32_32x32x16_bf16 v[16:31], v[154:157], v[176:179], v[16:31]
	v_mfma_f32_32x32x16_bf16 v[64:79], v[154:157], v[180:183], v[64:79]
	v_mfma_f32_32x32x16_bf16 v[32:47], v[158:161], v[168:171], v[32:47]
	v_mfma_f32_32x32x16_bf16 v[96:111], v[158:161], v[172:175], v[96:111]
	v_mfma_f32_32x32x16_bf16 v[80:95], v[158:161], v[176:179], v[80:95]
	v_mfma_f32_32x32x16_bf16 v[112:127], v[158:161], v[180:183], v[112:127]
	v_mfma_f32_32x32x16_bf16 v[0:15], v[188:191], v[196:199], v[0:15]
	v_mfma_f32_32x32x16_bf16 v[48:63], v[188:191], v[200:203], v[48:63]
	v_mfma_f32_32x32x16_bf16 v[16:31], v[188:191], v[204:207], v[16:31]
	v_mfma_f32_32x32x16_bf16 v[64:79], v[188:191], v[208:211], v[64:79]
	v_mfma_f32_32x32x16_bf16 v[32:47], v[192:195], v[196:199], v[32:47]
	v_mfma_f32_32x32x16_bf16 v[96:111], v[192:195], v[200:203], v[96:111]
	v_mfma_f32_32x32x16_bf16 v[80:95], v[192:195], v[204:207], v[80:95]
	v_mfma_f32_32x32x16_bf16 v[112:127], v[192:195], v[208:211], v[112:127]
	s_setprio 0
	s_add_u32 s0, s0, 64
	s_addc_u32 s1, s1, 0
	s_add_u32 s100, s100, 0x30000
	s_addc_u32 s101, s101, 0
	s_cmpk_eq_i32 s0, 0x7c0
	s_cbranch_scc0 .LBB0_142
	s_waitcnt vmcnt(0)
	s_waitcnt vmcnt(0)
	s_barrier
; #define MFMA(a, b, c) __builtin_amdgcn_mfma_f32_32x32x16_bf16((a), (b), (c), 0, 0, 0)
; DI int crow(int reg, int h) { return (reg & 3) + 8 * (reg >> 2) + 4 * h; }
; template <int K, typename Epi>
; DI void gemm_tile_wide(const u16* __restrict__ A, int lda, const u16* __restrict__ Bt, int ldb, int m0, int n0, char* smem, Epi epi) {
;     ...
;     bf16x8 a[2][2], b[2][4];
; #pragma unroll
;     for (int kk = 0; kk < 2; ++kk) {
; #pragma unroll
;       for (int i = 0; i < 2; ++i) a[kk][i] = *(const bf16x8*)(Sg + aoff[i][kk]);
; #pragma unroll
;       for (int j = 0; j < 4; ++j) b[kk][j] = *(const bf16x8*)(Sg + boff[j][kk]);
;     }
;     __builtin_amdgcn_sched_barrier(0);
;     __builtin_amdgcn_s_setprio(1);
; #pragma unroll
;     for (int kk = 0; kk < 2; ++kk)
; #pragma unroll
;       for (int i = 0; i < 2; ++i)
; #pragma unroll
;         for (int j = 0; j < 4; ++j) acc[i][j] = MFMA(a[kk][i], b[kk][j], acc[i][j]);
;     __builtin_amdgcn_s_setprio(0);
;   }
;   float* Cs = (float*)smem;
; #pragma unroll
;   for (int half = 0; half < 2; ++half) {
;     __syncthreads();
;     if (wn == half) {
; #pragma unroll
;       for (int i = 0; i < 2; ++i)
; #pragma unroll
;         for (int j = 0; j < 4; ++j)
; #pragma unroll
;           for (int e = 0; e < 16; ++e) Cs[(wm * 64 + i * 32 + crow(e, h)) * CS_LD + j * 32 + r] = acc[i][j][e];
;     }
	ds_read_b128 v[128:131], v153 offset:32768
	ds_read_b128 v[132:135], v152 offset:32768
	ds_read_b128 v[138:141], v151 offset:32768
	ds_read_b128 v[150:153], v150 offset:32768
	ds_read_b128 v[154:157], v146 offset:26624
	ds_read_b128 v[158:161], v146 offset:24576
	ds_read_b128 v[168:171], v149 offset:30720
	ds_read_b128 v[172:175], v149 offset:28672
	ds_read_b128 v[176:179], v149 offset:26624
	ds_read_b128 v[146:149], v148 offset:32768
	ds_read_b128 v[180:183], v145 offset:26624
	ds_read_b128 v[188:191], v145 offset:24576
	s_setprio 1
	s_waitcnt lgkmcnt(0)
	v_mfma_f32_32x32x16_bf16 v[0:15], v[188:191], v[146:149], v[0:15]
	v_mfma_f32_32x32x16_bf16 v[48:63], v[188:191], v[176:179], v[48:63]
	v_mfma_f32_32x32x16_bf16 v[16:31], v[188:191], v[172:175], v[16:31]
	v_mfma_f32_32x32x16_bf16 v[64:79], v[188:191], v[168:171], v[64:79]
	v_mfma_f32_32x32x16_bf16 v[32:47], v[180:183], v[146:149], v[32:47]
	v_mfma_f32_32x32x16_bf16 v[96:111], v[180:183], v[176:179], v[96:111]
	v_mfma_f32_32x32x16_bf16 v[80:95], v[180:183], v[172:175], v[80:95]
	v_mfma_f32_32x32x16_bf16 v[112:127], v[180:183], v[168:171], v[112:127]
	v_mfma_f32_32x32x16_bf16 v[0:15], v[158:161], v[150:153], v[0:15]
	v_mfma_f32_32x32x16_bf16 v[48:63], v[158:161], v[138:141], v[48:63]
	v_mfma_f32_32x32x16_bf16 v[16:31], v[158:161], v[132:135], v[16:31]
	v_mfma_f32_32x32x16_bf16 v[64:79], v[158:161], v[128:131], v[64:79]
	v_mfma_f32_32x32x16_bf16 v[32:47], v[154:157], v[150:153], v[32:47]
	v_mfma_f32_32x32x16_bf16 v[96:111], v[154:157], v[138:141], v[96:111]
	v_mfma_f32_32x32x16_bf16 v[80:95], v[154:157], v[132:135], v[80:95]
	v_mfma_f32_32x32x16_bf16 v[112:127], v[154:157], v[128:131], v[112:127]
	s_setprio 0
	v_lshlrev_b32_e32 v128, 6, v142
	v_lshl_or_b32 v139, v143, 2, v128
	v_lshlrev_b32_e32 v138, 2, v144
	v_cmp_ne_u32_e64 s[4:5], 0, v136
	v_cmp_eq_u32_e32 vcc, 0, v136
	s_barrier
	s_and_saveexec_b64 s[0:1], vcc
	s_cbranch_execz .LBB0_145
	v_mad_u64_u32 v[128:129], s[2:3], v139, s17, v[138:139]
	v_add_u32_e32 v129, 0x400, v128
	v_add_u32_e32 v130, 0x1000, v128
	v_add_u32_e32 v131, 0x1400, v128
	v_add_u32_e32 v132, 0x2000, v128
	v_add_u32_e32 v133, 0x2400, v128
	v_add_u32_e32 v135, 0x3200, v128
	ds_write2_b32 v128, v0, v48 offset1:32
	ds_write2_b32 v128, v1, v49 offset0:132 offset1:164
	ds_write2_b32 v129, v2, v50 offset0:8 offset1:40
	ds_write2_b32 v129, v3, v51 offset0:140 offset1:172
	ds_write2_b32 v130, v4, v52 offset0:32 offset1:64
	ds_write2_b32 v130, v5, v53 offset0:164 offset1:196
	ds_write2_b32 v131, v6, v54 offset0:40 offset1:72
	ds_write2_b32 v131, v7, v55 offset0:172 offset1:204
	ds_write2_b32 v132, v8, v56 offset0:64 offset1:96
	ds_write2_b32 v132, v9, v57 offset0:196 offset1:228
	ds_write2_b32 v133, v10, v58 offset0:72 offset1:104
	ds_write2_b32 v133, v11, v59 offset0:204 offset1:236
	v_add_u32_e32 v134, 0x3000, v128
	ds_write2_b32 v135, v13, v61 offset0:100 offset1:132
	v_add_u32_e32 v135, 0x3400, v128
	v_add_u32_e32 v136, 0x3600, v128
	ds_write2_b32 v134, v12, v60 offset0:96 offset1:128
	ds_write2_b32 v135, v14, v62 offset0:104 offset1:136
	ds_write2_b32 v136, v15, v63 offset0:108 offset1:140
	ds_write2_b32 v128, v16, v64 offset0:64 offset1:96
	ds_write2_b32 v128, v17, v65 offset0:196 offset1:228
	ds_write2_b32 v129, v18, v66 offset0:72 offset1:104
	ds_write2_b32 v129, v19, v67 offset0:204 offset1:236
	ds_write2_b32 v130, v20, v68 offset0:96 offset1:128
	v_add_u32_e32 v129, 0x1200, v128
	ds_write2_b32 v129, v21, v69 offset0:100 offset1:132
	ds_write2_b32 v131, v22, v70 offset0:104 offset1:136
	v_add_u32_e32 v129, 0x1600, v128
	ds_write2_b32 v129, v23, v71 offset0:108 offset1:140
	ds_write2_b32 v132, v24, v72 offset0:128 offset1:160
	ds_write2_b32 v133, v25, v73 offset0:4 offset1:36
	ds_write2_b32 v133, v26, v74 offset0:136 offset1:168
	v_add_u32_e32 v129, 0x2800, v128
	ds_write2_b32 v129, v27, v75 offset0:12 offset1:44
	ds_write2_b32 v134, v28, v76 offset0:160 offset1:192
	ds_write2_b32 v135, v29, v77 offset0:36 offset1:68
	ds_write2_b32 v135, v30, v78 offset0:168 offset1:200
	v_add_u32_e32 v129, 0x3800, v128
	ds_write2_b32 v129, v31, v79 offset0:44 offset1:76
	v_add_u32_e32 v129, 0x4000, v128
	v_add_u32_e32 v130, 0x4400, v128
	v_add_u32_e32 v132, 0x5000, v128
	ds_write2_b32 v129, v32, v96 offset0:128 offset1:160
	ds_write2_b32 v130, v33, v97 offset0:4 offset1:36
	ds_write2_b32 v130, v34, v98 offset0:136 offset1:168
	v_add_u32_e32 v131, 0x4800, v128
	ds_write2_b32 v132, v36, v100 offset0:160 offset1:192
	v_add_u32_e32 v132, 0x5400, v128
	v_add_u32_e32 v134, 0x6000, v128
	ds_write2_b32 v131, v35, v99 offset0:12 offset1:44
	ds_write2_b32 v132, v37, v101 offset0:36 offset1:68
	ds_write2_b32 v132, v38, v102 offset0:168 offset1:200
	v_add_u32_e32 v133, 0x5800, v128
	ds_write2_b32 v134, v40, v104 offset0:192 offset1:224
	v_add_u32_e32 v134, 0x6400, v128
	v_add_u32_e32 v136, 0x7200, v128
	v_add_u32_e32 v140, 0x7600, v128
	ds_write2_b32 v133, v39, v103 offset0:44 offset1:76
	ds_write2_b32 v134, v41, v105 offset0:68 offset1:100
	ds_write2_b32 v134, v42, v106 offset0:200 offset1:232
	v_add_u32_e32 v135, 0x6800, v128
	ds_write2_b32 v136, v44, v108 offset0:96 offset1:128
	v_add_u32_e32 v136, 0x7400, v128
	ds_write2_b32 v140, v46, v110 offset0:104 offset1:136
	v_add_u32_e32 v140, 0x7800, v128
	ds_write2_b32 v135, v43, v107 offset0:76 offset1:108
	ds_write2_b32 v136, v45, v109 offset0:100 offset1:132
	ds_write2_b32 v140, v47, v111 offset0:108 offset1:140
	ds_write2_b32 v129, v80, v112 offset0:192 offset1:224
	ds_write2_b32 v130, v81, v113 offset0:68 offset1:100
	ds_write2_b32 v130, v82, v114 offset0:200 offset1:232
	ds_write2_b32 v131, v83, v115 offset0:76 offset1:108
	v_add_u32_e32 v129, 0x5200, v128
	v_add_u32_e32 v128, 0x5600, v128
	ds_write2_b32 v129, v84, v116 offset0:96 offset1:128
	ds_write2_b32 v132, v85, v117 offset0:100 offset1:132
	ds_write2_b32 v128, v86, v118 offset0:104 offset1:136
	ds_write2_b32 v133, v87, v119 offset0:108 offset1:140
	ds_write2_b32 v134, v88, v120 offset1:32
	ds_write2_b32 v134, v89, v121 offset0:132 offset1:164
	ds_write2_b32 v135, v90, v122 offset0:8 offset1:40
	ds_write2_b32 v135, v91, v123 offset0:140 offset1:172
	ds_write2_b32 v136, v92, v124 offset0:32 offset1:64
	ds_write2_b32 v136, v93, v125 offset0:164 offset1:196
	ds_write2_b32 v140, v94, v126 offset0:40 offset1:72
	ds_write2_b32 v140, v95, v127 offset0:172 offset1:204

;   const int tid = otid(), lane = tid & 63, w = tid >> 6, r = lane & 31, h = lane >> 5;
;   const int wm = w >> 1, wn = w & 1;
;   constexpr int IM = BM / 64;
;   constexpr int NA = BM / 32;
;   f32x16 acc[IM][2];
; #pragma unroll
;   for (int i = 0; i < IM; ++i)
; #pragma unroll
;     for (int j = 0; j < 2; ++j)
; #pragma unroll
;       for (int e = 0; e < 16; ++e) acc[i][j][e] = 0.f;
;   constexpr int NK = K / 64;
;   constexpr int OPB = 128 * 128;
;   constexpr int BUFB = 2 * OPB;
;   const int lrow = tid >> 3, cpos = tid & 7;
;   const u16* ap[4]; const u16* bp[4];
; #pragma unroll
;   for (int i = 0; i < 4; ++i) {
;     const int row = lrow + 32 * i;
;     const int sc = cpos ^ ((row >> 1) & 7);
;     ap[i] = A + (size_t)(m0 + (i < NA ? row : 0)) * lda + sc * 8;
;     bp[i] = Bt + (size_t)(n0 + row) * ldb + sc * 8;
;   }
;   char* const ldst = smem + tid * 16;
;   __syncthreads();
; #pragma unroll
;   for (int i = 0; i < 4; ++i) {
;     if (i < NA) __builtin_amdgcn_global_load_lds((const unsigned*)(ap[i]), (unsigned*)(ldst + i * 4096), 16, 0, 0);
;     __builtin_amdgcn_global_load_lds((const unsigned*)(bp[i]), (unsigned*)(ldst + OPB + i * 4096), 16, 0, 0);
;   }
;   int aoff[2], boff[2], aswz[2], bswz[2];
; #pragma unroll
;   for (int i = 0; i < 2; ++i) {
;     const int ra_ = wm * (BM / 2) + (i < IM ? i : 0) * 32 + r, rb_ = wn * 64 + i * 32 + r;
;     aoff[i] = ra_ * 128; aswz[i] = (ra_ >> 1) & 7;
;     boff[i] = rb_ * 128; bswz[i] = (rb_ >> 1) & 7;
;   }
;   for (int kt = 0; kt < NK; ++kt) {
;     asm volatile("s_waitcnt vmcnt(0)" ::: "memory");
;     __syncthreads();
;     const int cur = (kt & 1) * BUFB, nxt = BUFB - cur;
;     if (kt + 1 < NK) {
; #pragma unroll
;       for (int i = 0; i < 4; ++i) {
;         if (i < NA) __builtin_amdgcn_global_load_lds((const unsigned*)(ap[i] + (kt + 1) * 64), (unsigned*)(ldst + nxt + i * 4096), 16, 0, 0);
;         __builtin_amdgcn_global_load_lds((const unsigned*)(bp[i] + (kt + 1) * 64), (unsigned*)(ldst + nxt + OPB + i * 4096), 16, 0, 0);
;       }
;     }
;     const char* As = smem + cur; const char* Bs = smem + cur + OPB;
;     bf16x8 a[4][IM], b[4][2];
; #pragma unroll
;     for (int kk = 0; kk < 4; ++kk)
; #pragma unroll
;       for (int i = 0; i < 2; ++i) {
;         if (i < IM) a[kk][i] = *(const bf16x8*)(As + aoff[i] + (((2 * kk + h) ^ aswz[i]) << 4));
.LBB0_236:
	s_mul_hi_i32 s0, s70, 0x2aaaaaab
	s_lshr_b32 s1, s0, 31
	s_ashr_i32 s17, s0, 2
	s_add_i32 s17, s17, s1
	v_mov_b32_e32 v6, v186
	s_lshl_b32 s44, s17, 6
	s_add_i32 s0, s44, 0x4000
	s_waitcnt lgkmcnt(0)
	v_lshrrev_b32_e32 v0, 4, v6
	v_ashrrev_i32_e32 v7, 3, v6
	v_xor_b32_e32 v0, v0, v6
	s_mul_i32 s16, s17, 24
	v_lshlrev_b32_e32 v0, 4, v0
	v_readlane_b32 s2, v247, 30
	v_add_u32_e32 v4, s0, v7
	s_sub_i32 s78, s70, s16
	v_and_b32_e32 v32, 0x70, v0
	v_readlane_b32 s3, v247, 31
	v_ashrrev_i32_e32 v5, 31, v4
	s_lshl_b32 s90, s78, 7
	v_lshl_add_u64 v[0:1], s[2:3], 0, v[32:33]
	v_lshlrev_b64 v[4:5], 11, v[4:5]
	v_readlane_b32 s2, v247, 32
	v_lshl_add_u64 v[36:37], v[0:1], 0, v[4:5]
	v_add_u32_e32 v4, s90, v7
	v_readlane_b32 s3, v247, 33
	v_ashrrev_i32_e32 v5, 31, v4
	v_lshlrev_b64 v[4:5], 11, v[4:5]
	v_lshl_add_u64 v[2:3], s[2:3], 0, v[32:33]
	v_add_u32_e32 v7, 32, v7
	v_lshl_add_u64 v[34:35], v[2:3], 0, v[4:5]
	v_add_u32_e32 v4, s0, v7
	v_ashrrev_i32_e32 v5, 31, v4
	v_lshlrev_b32_e32 v62, 4, v6
	v_lshlrev_b64 v[4:5], 11, v[4:5]
	v_add_u32_e32 v63, 0x4000, v62
	v_readfirstlane_b32 s13, v62
	v_lshl_add_u64 v[38:39], v[0:1], 0, v[4:5]
	v_add_u32_e32 v0, s90, v7
	s_mov_b32 m0, s13
	v_readfirstlane_b32 s8, v63
	v_add_u32_e32 v66, 0x1000, v62
	v_ashrrev_i32_e32 v1, 31, v0
	s_barrier
	global_load_lds_dwordx4 v[36:37], off
	s_mov_b32 m0, s8
	v_readfirstlane_b32 s9, v66
	v_add_u32_e32 v67, 0x5000, v62
	v_lshlrev_b64 v[0:1], 11, v[0:1]
	global_load_lds_dwordx4 v[34:35], off
	s_mov_b32 m0, s9
	v_readfirstlane_b32 s12, v67
	v_add_u32_e32 v65, 0x6000, v62
	v_lshl_add_u64 v[40:41], v[2:3], 0, v[0:1]
	s_mov_b64 s[0:1], 0x20000
	global_load_lds_dwordx4 v[38:39], off
	s_mov_b32 m0, s12
	v_readfirstlane_b32 s11, v65
	v_add_u32_e32 v64, 0x7000, v62
	v_lshl_add_u64 v[0:1], v[34:35], 0, s[0:1]
	s_mov_b64 s[0:1], 0x30000
	global_load_lds_dwordx4 v[40:41], off
	s_mov_b32 m0, s11
	v_readfirstlane_b32 s10, v64
	v_add_u32_e32 v57, 0x8000, v62
	v_lshl_add_u64 v[2:3], v[34:35], 0, s[0:1]
	global_load_lds_dwordx4 v[0:1], off
	s_mov_b32 m0, s10
	v_add_u32_e32 v56, 0xc000, v62
	v_readfirstlane_b32 s3, v57
	global_load_lds_dwordx4 v[2:3], off
	v_lshl_add_u64 v[0:1], v[36:37], 0, s[92:93]
	s_mov_b32 m0, s3
	v_readfirstlane_b32 s0, v56
	v_add_u32_e32 v58, 0x9000, v62
	s_waitcnt vmcnt(0)
	s_waitcnt vmcnt(0) lgkmcnt(0)
	s_barrier
	global_load_lds_dwordx4 v[0:1], off
	v_lshl_add_u64 v[0:1], v[34:35], 0, s[92:93]
	s_mov_b32 m0, s0
	v_readfirstlane_b32 s1, v58
	v_add_u32_e32 v59, 0xd000, v62
	global_load_lds_dwordx4 v[0:1], off
	v_lshl_add_u64 v[0:1], v[38:39], 0, s[92:93]
	s_mov_b32 m0, s1
	v_readfirstlane_b32 s2, v59
	global_load_lds_dwordx4 v[0:1], off
	v_lshl_add_u64 v[0:1], v[40:41], 0, s[92:93]
	s_mov_b32 m0, s2
	s_mov_b64 s[6:7], 0x20080
	v_add_u32_e32 v60, 0xe000, v62
	global_load_lds_dwordx4 v[0:1], off
	v_lshl_add_u64 v[0:1], v[34:35], 0, s[6:7]
	v_readfirstlane_b32 s6, v60
	v_add_u32_e32 v61, 0xf000, v62
	s_mov_b32 m0, s6
	s_mov_b64 s[14:15], 0x30080
	v_readfirstlane_b32 s7, v61
	global_load_lds_dwordx4 v[0:1], off
	v_lshl_add_u64 v[0:1], v[34:35], 0, s[14:15]
	s_mov_b32 m0, s7
	v_and_b32_e32 v32, 31, v6
	global_load_lds_dwordx4 v[0:1], off
	v_ashrrev_i32_e32 v42, 7, v6
	v_bfe_u32 v43, v6, 5, 1
	v_bfe_u32 v44, v6, 6, 1
	v_lshlrev_b32_e32 v0, 7, v32
	v_lshrrev_b32_e32 v1, 1, v6
	v_bfe_u32 v2, v6, 1, 3
	v_lshl_or_b32 v4, v42, 12, v0
	v_lshl_or_b32 v5, v44, 13, v0
	v_bitop3_b32 v0, v1, v43, 7 bitop3:0x6c
	v_bitop3_b32 v1, v43, v2, 2 bitop3:0x36
	v_lshlrev_b32_e32 v6, 4, v1
	v_bitop3_b32 v1, v43, v2, 4 bitop3:0x36
	v_lshlrev_b32_e32 v7, 4, v1
	v_bitop3_b32 v1, v43, v2, 6 bitop3:0x36
	v_lshlrev_b32_e32 v0, 4, v0
	v_lshlrev_b32_e32 v8, 4, v1
	v_or_b32_e32 v45, v4, v0
	v_or_b32_e32 v46, v5, v0
	v_or_b32_e32 v51, v5, v6
	v_or_b32_e32 v52, v4, v7
	v_or_b32_e32 v53, v5, v7
	v_or_b32_e32 v55, v5, v8
	ds_read_b128 v[16:19], v45
	ds_read_b128 v[0:3], v46 offset:16384
	v_or_b32_e32 v47, v4, v6
	ds_read_b128 v[20:23], v46 offset:20480
	ds_read_b128 v[68:71], v47
	ds_read_b128 v[72:75], v51 offset:16384
	ds_read_b128 v[76:79], v51 offset:20480
	ds_read_b128 v[80:83], v52
	ds_read_b128 v[84:87], v53 offset:16384
	v_or_b32_e32 v54, v4, v8
	ds_read_b128 v[88:91], v53 offset:20480
	ds_read_b128 v[92:95], v54
	ds_read_b128 v[96:99], v55 offset:16384
	ds_read_b128 v[100:103], v55 offset:20480
	s_setprio 1
	s_waitcnt lgkmcnt(0)
	v_mfma_f32_32x32x16_bf16 v[0:15], v[16:19], v[0:3], 0
	v_mfma_f32_32x32x16_bf16 v[16:31], v[16:19], v[20:23], 0
	v_mfma_f32_32x32x16_bf16 v[16:31], v[68:71], v[76:79], v[16:31]
	v_mfma_f32_32x32x16_bf16 v[0:15], v[68:71], v[72:75], v[0:15]
	v_mfma_f32_32x32x16_bf16 v[16:31], v[80:83], v[88:91], v[16:31]
	v_mfma_f32_32x32x16_bf16 v[0:15], v[80:83], v[84:87], v[0:15]
	v_mfma_f32_32x32x16_bf16 v[16:31], v[92:95], v[100:103], v[16:31]
	v_mfma_f32_32x32x16_bf16 v[0:15], v[92:95], v[96:99], v[0:15]
	s_setprio 0
	s_mov_b32 m0, s13
	v_lshl_add_u64 v[68:69], v[36:37], 0, s[94:95]
	s_waitcnt vmcnt(0)
	s_waitcnt vmcnt(0)
	s_barrier
; #define MFMA(a, b, c) __builtin_amdgcn_mfma_f32_32x32x16_bf16((a), (b), (c), 0, 0, 0)
;     ...
;   for (int kt = 0; kt < NK; ++kt) {
;     asm volatile("s_waitcnt vmcnt(0)" ::: "memory");
;     __syncthreads();
;     const int cur = (kt & 1) * BUFB, nxt = BUFB - cur;
;     if (kt + 1 < NK) {
; #pragma unroll
;       for (int i = 0; i < 4; ++i) {
;         if (i < NA) __builtin_amdgcn_global_load_lds((const unsigned*)(ap[i] + (kt + 1) * 64), (unsigned*)(ldst + nxt + i * 4096), 16, 0, 0);
;         __builtin_amdgcn_global_load_lds((const unsigned*)(bp[i] + (kt + 1) * 64), (unsigned*)(ldst + nxt + OPB + i * 4096), 16, 0, 0);
;       }
;     }
;     const char* As = smem + cur; const char* Bs = smem + cur + OPB;
;     bf16x8 a[4][IM], b[4][2];
; #pragma unroll
;     for (int kk = 0; kk < 4; ++kk)
; #pragma unroll
;       for (int i = 0; i < 2; ++i) {
;         if (i < IM) a[kk][i] = *(const bf16x8*)(As + aoff[i] + (((2 * kk + h) ^ aswz[i]) << 4));
;         b[kk][i] = *(const bf16x8*)(Bs + boff[i] + (((2 * kk + h) ^ bswz[i]) << 4));
;       }
;     __builtin_amdgcn_sched_barrier(0);
;     __builtin_amdgcn_s_setprio(1);
; #pragma unroll
;     for (int kk = 0; kk < 4; ++kk)
; #pragma unroll
;       for (int i = 0; i < IM; ++i)
; #pragma unroll
;         for (int j = 0; j < 2; ++j) acc[i][j] = MFMA(a[kk][i], b[kk][j], acc[i][j]);
;     __builtin_amdgcn_s_setprio(0);
;   }
	global_load_lds_dwordx4 v[68:69], off
	v_lshl_add_u64 v[68:69], v[34:35], 0, s[94:95]
	s_mov_b32 m0, s8
	s_mov_b64 s[14:15], 0x20100
	global_load_lds_dwordx4 v[68:69], off
	v_lshl_add_u64 v[68:69], v[38:39], 0, s[94:95]
	s_mov_b32 m0, s9
	s_nop 0
	global_load_lds_dwordx4 v[68:69], off
	v_lshl_add_u64 v[68:69], v[40:41], 0, s[94:95]
	s_mov_b32 m0, s12
	s_nop 0
	global_load_lds_dwordx4 v[68:69], off
	v_lshl_add_u64 v[68:69], v[34:35], 0, s[14:15]
	s_mov_b32 m0, s11
	s_mov_b64 s[14:15], 0x30100
	global_load_lds_dwordx4 v[68:69], off
	v_lshl_add_u64 v[68:69], v[34:35], 0, s[14:15]
	s_mov_b32 m0, s10
	s_nop 0
	global_load_lds_dwordx4 v[68:69], off
	ds_read_b128 v[68:71], v45 offset:32768
	ds_read_b128 v[72:75], v46 offset:49152
	ds_read_b128 v[76:79], v46 offset:53248
	ds_read_b128 v[80:83], v47 offset:32768
	ds_read_b128 v[84:87], v51 offset:49152
	ds_read_b128 v[88:91], v51 offset:53248
	ds_read_b128 v[92:95], v52 offset:32768
	ds_read_b128 v[96:99], v53 offset:49152
	ds_read_b128 v[100:103], v53 offset:53248
	ds_read_b128 v[104:107], v54 offset:32768
	ds_read_b128 v[108:111], v55 offset:49152
	ds_read_b128 v[112:115], v55 offset:53248
	s_setprio 1
	s_waitcnt lgkmcnt(0)
	v_mfma_f32_32x32x16_bf16 v[16:31], v[68:71], v[76:79], v[16:31]
	v_mfma_f32_32x32x16_bf16 v[0:15], v[68:71], v[72:75], v[0:15]
	v_mfma_f32_32x32x16_bf16 v[16:31], v[80:83], v[88:91], v[16:31]
	v_mfma_f32_32x32x16_bf16 v[0:15], v[80:83], v[84:87], v[0:15]
	v_mfma_f32_32x32x16_bf16 v[16:31], v[92:95], v[100:103], v[16:31]
	v_mfma_f32_32x32x16_bf16 v[0:15], v[92:95], v[96:99], v[0:15]
	v_mfma_f32_32x32x16_bf16 v[16:31], v[104:107], v[112:115], v[16:31]
	v_mfma_f32_32x32x16_bf16 v[0:15], v[104:107], v[108:111], v[0:15]
	s_setprio 0
	s_mov_b32 m0, s3
	v_lshl_add_u64 v[68:69], v[36:37], 0, s[96:97]
	s_waitcnt vmcnt(0)
	s_waitcnt vmcnt(0)
	s_barrier
	global_load_lds_dwordx4 v[68:69], off
	v_lshl_add_u64 v[68:69], v[34:35], 0, s[96:97]
	s_mov_b32 m0, s0
	s_mov_b64 s[14:15], 0x20180
	global_load_lds_dwordx4 v[68:69], off
	v_lshl_add_u64 v[68:69], v[38:39], 0, s[96:97]
	s_mov_b32 m0, s1
	s_nop 0
	global_load_lds_dwordx4 v[68:69], off
	v_lshl_add_u64 v[68:69], v[40:41], 0, s[96:97]
	s_mov_b32 m0, s2
	s_nop 0
	global_load_lds_dwordx4 v[68:69], off
	v_lshl_add_u64 v[68:69], v[34:35], 0, s[14:15]
	s_mov_b32 m0, s6
	s_mov_b64 s[14:15], 0x30180
	global_load_lds_dwordx4 v[68:69], off
	v_lshl_add_u64 v[68:69], v[34:35], 0, s[14:15]
	s_mov_b32 m0, s7
	s_nop 0
	global_load_lds_dwordx4 v[68:69], off
	ds_read_b128 v[68:71], v45
	ds_read_b128 v[72:75], v46 offset:16384
	ds_read_b128 v[76:79], v46 offset:20480
	ds_read_b128 v[80:83], v47
	ds_read_b128 v[84:87], v51 offset:16384
	ds_read_b128 v[88:91], v51 offset:20480
	ds_read_b128 v[92:95], v52
	ds_read_b128 v[96:99], v53 offset:16384
	ds_read_b128 v[100:103], v53 offset:20480
	ds_read_b128 v[104:107], v54
	ds_read_b128 v[108:111], v55 offset:16384
	ds_read_b128 v[112:115], v55 offset:20480
	s_setprio 1
	s_waitcnt lgkmcnt(0)
	v_mfma_f32_32x32x16_bf16 v[16:31], v[68:71], v[76:79], v[16:31]
	v_mfma_f32_32x32x16_bf16 v[0:15], v[68:71], v[72:75], v[0:15]
	v_mfma_f32_32x32x16_bf16 v[16:31], v[80:83], v[88:91], v[16:31]
	v_mfma_f32_32x32x16_bf16 v[0:15], v[80:83], v[84:87], v[0:15]
	v_mfma_f32_32x32x16_bf16 v[16:31], v[92:95], v[100:103], v[16:31]
	v_mfma_f32_32x32x16_bf16 v[0:15], v[92:95], v[96:99], v[0:15]
	v_mfma_f32_32x32x16_bf16 v[16:31], v[104:107], v[112:115], v[16:31]
	v_mfma_f32_32x32x16_bf16 v[0:15], v[104:107], v[108:111], v[0:15]
	s_setprio 0
	s_mov_b32 m0, s13
	v_lshl_add_u64 v[68:69], v[36:37], 0, s[88:89]
	s_waitcnt vmcnt(0)
	s_waitcnt vmcnt(0)
	s_barrier
	global_load_lds_dwordx4 v[68:69], off
	v_lshl_add_u64 v[68:69], v[34:35], 0, s[88:89]
	s_mov_b32 m0, s8
	s_mov_b64 s[14:15], 0x20200
	global_load_lds_dwordx4 v[68:69], off
	v_lshl_add_u64 v[68:69], v[38:39], 0, s[88:89]
	s_mov_b32 m0, s9
	s_nop 0
	global_load_lds_dwordx4 v[68:69], off
	v_lshl_add_u64 v[68:69], v[40:41], 0, s[88:89]
	s_mov_b32 m0, s12
	s_nop 0
	global_load_lds_dwordx4 v[68:69], off
	v_lshl_add_u64 v[68:69], v[34:35], 0, s[14:15]
	s_mov_b32 m0, s11
	s_mov_b64 s[14:15], 0x30200
	global_load_lds_dwordx4 v[68:69], off
	v_lshl_add_u64 v[68:69], v[34:35], 0, s[14:15]
	s_mov_b32 m0, s10
	s_nop 0
	global_load_lds_dwordx4 v[68:69], off
	ds_read_b128 v[68:71], v45 offset:32768
	ds_read_b128 v[72:75], v46 offset:49152
	ds_read_b128 v[76:79], v46 offset:53248
	ds_read_b128 v[80:83], v47 offset:32768
	ds_read_b128 v[84:87], v51 offset:49152
	ds_read_b128 v[88:91], v51 offset:53248
	ds_read_b128 v[92:95], v52 offset:32768
	ds_read_b128 v[96:99], v53 offset:49152
	ds_read_b128 v[100:103], v53 offset:53248
	ds_read_b128 v[104:107], v54 offset:32768
	ds_read_b128 v[108:111], v55 offset:49152
	ds_read_b128 v[112:115], v55 offset:53248
	s_setprio 1
	s_waitcnt lgkmcnt(0)
	v_mfma_f32_32x32x16_bf16 v[16:31], v[68:71], v[76:79], v[16:31]
	v_mfma_f32_32x32x16_bf16 v[0:15], v[68:71], v[72:75], v[0:15]
	v_mfma_f32_32x32x16_bf16 v[16:31], v[80:83], v[88:91], v[16:31]
	v_mfma_f32_32x32x16_bf16 v[0:15], v[80:83], v[84:87], v[0:15]
	v_mfma_f32_32x32x16_bf16 v[16:31], v[92:95], v[100:103], v[16:31]
	v_mfma_f32_32x32x16_bf16 v[0:15], v[92:95], v[96:99], v[0:15]
	v_mfma_f32_32x32x16_bf16 v[16:31], v[104:107], v[112:115], v[16:31]
	v_mfma_f32_32x32x16_bf16 v[0:15], v[104:107], v[108:111], v[0:15]
	s_setprio 0
	s_mov_b32 m0, s3
	v_lshl_add_u64 v[68:69], v[36:37], 0, s[4:5]
	s_waitcnt vmcnt(0)
	s_waitcnt vmcnt(0)
	s_barrier
; #define MFMA(a, b, c) __builtin_amdgcn_mfma_f32_32x32x16_bf16((a), (b), (c), 0, 0, 0)
;     ...
;   for (int kt = 0; kt < NK; ++kt) {
;     asm volatile("s_waitcnt vmcnt(0)" ::: "memory");
;     __syncthreads();
;     const int cur = (kt & 1) * BUFB, nxt = BUFB - cur;
;     if (kt + 1 < NK) {
; #pragma unroll
;       for (int i = 0; i < 4; ++i) {
;         if (i < NA) __builtin_amdgcn_global_load_lds((const unsigned*)(ap[i] + (kt + 1) * 64), (unsigned*)(ldst + nxt + i * 4096), 16, 0, 0);
;         __builtin_amdgcn_global_load_lds((const unsigned*)(bp[i] + (kt + 1) * 64), (unsigned*)(ldst + nxt + OPB + i * 4096), 16, 0, 0);
;       }
;     }
;     const char* As = smem + cur; const char* Bs = smem + cur + OPB;
;     bf16x8 a[4][IM], b[4][2];
; #pragma unroll
;     for (int kk = 0; kk < 4; ++kk)
; #pragma unroll
;       for (int i = 0; i < 2; ++i) {
;         if (i < IM) a[kk][i] = *(const bf16x8*)(As + aoff[i] + (((2 * kk + h) ^ aswz[i]) << 4));
;         b[kk][i] = *(const bf16x8*)(Bs + boff[i] + (((2 * kk + h) ^ bswz[i]) << 4));
;       }
;     __builtin_amdgcn_sched_barrier(0);
;     __builtin_amdgcn_s_setprio(1);
; #pragma unroll
;     for (int kk = 0; kk < 4; ++kk)
; #pragma unroll
;       for (int i = 0; i < IM; ++i)
; #pragma unroll
;         for (int j = 0; j < 2; ++j) acc[i][j] = MFMA(a[kk][i], b[kk][j], acc[i][j]);
;     __builtin_amdgcn_s_setprio(0);
;   }
	global_load_lds_dwordx4 v[68:69], off
	v_lshl_add_u64 v[68:69], v[34:35], 0, s[4:5]
	s_mov_b32 m0, s0
	s_mov_b64 s[14:15], 0x20280
	global_load_lds_dwordx4 v[68:69], off
	v_lshl_add_u64 v[68:69], v[38:39], 0, s[4:5]
	s_mov_b32 m0, s1
	s_nop 0
	global_load_lds_dwordx4 v[68:69], off
	v_lshl_add_u64 v[68:69], v[40:41], 0, s[4:5]
	s_mov_b32 m0, s2
	s_nop 0
	global_load_lds_dwordx4 v[68:69], off
	v_lshl_add_u64 v[68:69], v[34:35], 0, s[14:15]
	s_mov_b32 m0, s6
	s_mov_b64 s[14:15], 0x30280
	global_load_lds_dwordx4 v[68:69], off
	v_lshl_add_u64 v[68:69], v[34:35], 0, s[14:15]
	s_mov_b32 m0, s7
	s_nop 0
	global_load_lds_dwordx4 v[68:69], off
	ds_read_b128 v[68:71], v45
	ds_read_b128 v[72:75], v46 offset:16384
	ds_read_b128 v[76:79], v46 offset:20480
	ds_read_b128 v[80:83], v47
	ds_read_b128 v[84:87], v51 offset:16384
	ds_read_b128 v[88:91], v51 offset:20480
	ds_read_b128 v[92:95], v52
	ds_read_b128 v[96:99], v53 offset:16384
	ds_read_b128 v[100:103], v53 offset:20480
	ds_read_b128 v[104:107], v54
	ds_read_b128 v[108:111], v55 offset:16384
	ds_read_b128 v[112:115], v55 offset:20480
	s_setprio 1
	s_waitcnt lgkmcnt(0)
	v_mfma_f32_32x32x16_bf16 v[16:31], v[68:71], v[76:79], v[16:31]
	v_mfma_f32_32x32x16_bf16 v[0:15], v[68:71], v[72:75], v[0:15]
	v_mfma_f32_32x32x16_bf16 v[16:31], v[80:83], v[88:91], v[16:31]
	v_mfma_f32_32x32x16_bf16 v[0:15], v[80:83], v[84:87], v[0:15]
	v_mfma_f32_32x32x16_bf16 v[16:31], v[92:95], v[100:103], v[16:31]
	v_mfma_f32_32x32x16_bf16 v[0:15], v[92:95], v[96:99], v[0:15]
	v_mfma_f32_32x32x16_bf16 v[16:31], v[104:107], v[112:115], v[16:31]
	v_mfma_f32_32x32x16_bf16 v[0:15], v[104:107], v[108:111], v[0:15]
	s_setprio 0
	s_mov_b32 m0, s13
	v_lshl_add_u64 v[68:69], v[36:37], 0, s[34:35]
	s_waitcnt vmcnt(0)
	s_waitcnt vmcnt(0)
	s_barrier
	global_load_lds_dwordx4 v[68:69], off
	v_lshl_add_u64 v[68:69], v[34:35], 0, s[34:35]
	s_mov_b32 m0, s8
	s_mov_b64 s[14:15], 0x20300
	global_load_lds_dwordx4 v[68:69], off
	v_lshl_add_u64 v[68:69], v[38:39], 0, s[34:35]
	s_mov_b32 m0, s9
	s_nop 0
	global_load_lds_dwordx4 v[68:69], off
	v_lshl_add_u64 v[68:69], v[40:41], 0, s[34:35]
	s_mov_b32 m0, s12
	s_nop 0
	global_load_lds_dwordx4 v[68:69], off
	v_lshl_add_u64 v[68:69], v[34:35], 0, s[14:15]
	s_mov_b32 m0, s11
	s_mov_b64 s[14:15], 0x30300
	global_load_lds_dwordx4 v[68:69], off
	v_lshl_add_u64 v[68:69], v[34:35], 0, s[14:15]
	s_mov_b32 m0, s10
	s_nop 0
	global_load_lds_dwordx4 v[68:69], off
	ds_read_b128 v[68:71], v45 offset:32768
	ds_read_b128 v[72:75], v46 offset:49152
	ds_read_b128 v[76:79], v46 offset:53248
	ds_read_b128 v[80:83], v47 offset:32768
	ds_read_b128 v[84:87], v51 offset:49152
	ds_read_b128 v[88:91], v51 offset:53248
	ds_read_b128 v[92:95], v52 offset:32768
	ds_read_b128 v[96:99], v53 offset:49152
	ds_read_b128 v[100:103], v53 offset:53248
	ds_read_b128 v[104:107], v54 offset:32768
	ds_read_b128 v[108:111], v55 offset:49152
	ds_read_b128 v[112:115], v55 offset:53248
	s_setprio 1
	s_waitcnt lgkmcnt(0)
	v_mfma_f32_32x32x16_bf16 v[16:31], v[68:71], v[76:79], v[16:31]
	v_mfma_f32_32x32x16_bf16 v[0:15], v[68:71], v[72:75], v[0:15]
	v_mfma_f32_32x32x16_bf16 v[16:31], v[80:83], v[88:91], v[16:31]
	v_mfma_f32_32x32x16_bf16 v[0:15], v[80:83], v[84:87], v[0:15]
	v_mfma_f32_32x32x16_bf16 v[16:31], v[92:95], v[100:103], v[16:31]
	v_mfma_f32_32x32x16_bf16 v[0:15], v[92:95], v[96:99], v[0:15]
	v_mfma_f32_32x32x16_bf16 v[16:31], v[104:107], v[112:115], v[16:31]
	v_mfma_f32_32x32x16_bf16 v[0:15], v[104:107], v[108:111], v[0:15]
	s_setprio 0
	s_mov_b32 m0, s3
	v_lshl_add_u64 v[68:69], v[36:37], 0, s[36:37]
	s_waitcnt vmcnt(0)
	s_waitcnt vmcnt(0)
	s_barrier
	global_load_lds_dwordx4 v[68:69], off
	v_lshl_add_u64 v[68:69], v[34:35], 0, s[36:37]
	s_mov_b32 m0, s0
	s_mov_b64 s[14:15], 0x20380
	global_load_lds_dwordx4 v[68:69], off
	v_lshl_add_u64 v[68:69], v[38:39], 0, s[36:37]
	s_mov_b32 m0, s1
	s_nop 0
	global_load_lds_dwordx4 v[68:69], off
	v_lshl_add_u64 v[68:69], v[40:41], 0, s[36:37]
	s_mov_b32 m0, s2
	s_nop 0
	global_load_lds_dwordx4 v[68:69], off
	v_lshl_add_u64 v[68:69], v[34:35], 0, s[14:15]
	s_mov_b32 m0, s6
	s_mov_b64 s[14:15], 0x30380
	global_load_lds_dwordx4 v[68:69], off
	v_lshl_add_u64 v[68:69], v[34:35], 0, s[14:15]
	s_mov_b32 m0, s7
	s_nop 0
	global_load_lds_dwordx4 v[68:69], off
	ds_read_b128 v[68:71], v45
	ds_read_b128 v[72:75], v46 offset:16384
	ds_read_b128 v[76:79], v46 offset:20480
	ds_read_b128 v[80:83], v47
	ds_read_b128 v[84:87], v51 offset:16384
	ds_read_b128 v[88:91], v51 offset:20480
	ds_read_b128 v[92:95], v52
	ds_read_b128 v[96:99], v53 offset:16384
	ds_read_b128 v[100:103], v53 offset:20480
	ds_read_b128 v[104:107], v54
	ds_read_b128 v[108:111], v55 offset:16384
	ds_read_b128 v[112:115], v55 offset:20480
	s_setprio 1
	s_waitcnt lgkmcnt(0)
	v_mfma_f32_32x32x16_bf16 v[16:31], v[68:71], v[76:79], v[16:31]
	v_mfma_f32_32x32x16_bf16 v[0:15], v[68:71], v[72:75], v[0:15]
	v_mfma_f32_32x32x16_bf16 v[16:31], v[80:83], v[88:91], v[16:31]
	v_mfma_f32_32x32x16_bf16 v[0:15], v[80:83], v[84:87], v[0:15]
	v_mfma_f32_32x32x16_bf16 v[16:31], v[92:95], v[100:103], v[16:31]
	v_mfma_f32_32x32x16_bf16 v[0:15], v[92:95], v[96:99], v[0:15]
	v_mfma_f32_32x32x16_bf16 v[16:31], v[104:107], v[112:115], v[16:31]
	v_mfma_f32_32x32x16_bf16 v[0:15], v[104:107], v[108:111], v[0:15]
	s_setprio 0
	s_mov_b32 m0, s13
	v_lshl_add_u64 v[68:69], v[36:37], 0, s[40:41]
	s_waitcnt vmcnt(0)
	s_waitcnt vmcnt(0)
	s_barrier
; #define MFMA(a, b, c) __builtin_amdgcn_mfma_f32_32x32x16_bf16((a), (b), (c), 0, 0, 0)
;     ...
;   for (int kt = 0; kt < NK; ++kt) {
;     asm volatile("s_waitcnt vmcnt(0)" ::: "memory");
;     __syncthreads();
;     const int cur = (kt & 1) * BUFB, nxt = BUFB - cur;
;     if (kt + 1 < NK) {
; #pragma unroll
;       for (int i = 0; i < 4; ++i) {
;         if (i < NA) __builtin_amdgcn_global_load_lds((const unsigned*)(ap[i] + (kt + 1) * 64), (unsigned*)(ldst + nxt + i * 4096), 16, 0, 0);
;         __builtin_amdgcn_global_load_lds((const unsigned*)(bp[i] + (kt + 1) * 64), (unsigned*)(ldst + nxt + OPB + i * 4096), 16, 0, 0);
;       }
;     }
;     const char* As = smem + cur; const char* Bs = smem + cur + OPB;
;     bf16x8 a[4][IM], b[4][2];
; #pragma unroll
;     for (int kk = 0; kk < 4; ++kk)
; #pragma unroll
;       for (int i = 0; i < 2; ++i) {
;         if (i < IM) a[kk][i] = *(const bf16x8*)(As + aoff[i] + (((2 * kk + h) ^ aswz[i]) << 4));
;         b[kk][i] = *(const bf16x8*)(Bs + boff[i] + (((2 * kk + h) ^ bswz[i]) << 4));
;       }
;     __builtin_amdgcn_sched_barrier(0);
;     __builtin_amdgcn_s_setprio(1);
; #pragma unroll
;     for (int kk = 0; kk < 4; ++kk)
; #pragma unroll
;       for (int i = 0; i < IM; ++i)
; #pragma unroll
;         for (int j = 0; j < 2; ++j) acc[i][j] = MFMA(a[kk][i], b[kk][j], acc[i][j]);
;     __builtin_amdgcn_s_setprio(0);
;   }
	global_load_lds_dwordx4 v[68:69], off
	v_lshl_add_u64 v[68:69], v[34:35], 0, s[40:41]
	s_mov_b32 m0, s8
	s_mov_b64 s[14:15], 0x20400
	global_load_lds_dwordx4 v[68:69], off
	v_lshl_add_u64 v[68:69], v[38:39], 0, s[40:41]
	s_mov_b32 m0, s9
	s_nop 0
	global_load_lds_dwordx4 v[68:69], off
	v_lshl_add_u64 v[68:69], v[40:41], 0, s[40:41]
	s_mov_b32 m0, s12
	s_nop 0
	global_load_lds_dwordx4 v[68:69], off
	v_lshl_add_u64 v[68:69], v[34:35], 0, s[14:15]
	s_mov_b32 m0, s11
	s_mov_b64 s[14:15], 0x30400
	global_load_lds_dwordx4 v[68:69], off
	v_lshl_add_u64 v[68:69], v[34:35], 0, s[14:15]
	s_mov_b32 m0, s10
	s_nop 0
	global_load_lds_dwordx4 v[68:69], off
	ds_read_b128 v[68:71], v45 offset:32768
	ds_read_b128 v[72:75], v46 offset:49152
	ds_read_b128 v[76:79], v46 offset:53248
	ds_read_b128 v[80:83], v47 offset:32768
	ds_read_b128 v[84:87], v51 offset:49152
	ds_read_b128 v[88:91], v51 offset:53248
	ds_read_b128 v[92:95], v52 offset:32768
	ds_read_b128 v[96:99], v53 offset:49152
	ds_read_b128 v[100:103], v53 offset:53248
	ds_read_b128 v[104:107], v54 offset:32768
	ds_read_b128 v[108:111], v55 offset:49152
	ds_read_b128 v[112:115], v55 offset:53248
	s_setprio 1
	s_waitcnt lgkmcnt(0)
	v_mfma_f32_32x32x16_bf16 v[16:31], v[68:71], v[76:79], v[16:31]
	v_mfma_f32_32x32x16_bf16 v[0:15], v[68:71], v[72:75], v[0:15]
	v_mfma_f32_32x32x16_bf16 v[16:31], v[80:83], v[88:91], v[16:31]
	v_mfma_f32_32x32x16_bf16 v[0:15], v[80:83], v[84:87], v[0:15]
	v_mfma_f32_32x32x16_bf16 v[16:31], v[92:95], v[100:103], v[16:31]
	v_mfma_f32_32x32x16_bf16 v[0:15], v[92:95], v[96:99], v[0:15]
	v_mfma_f32_32x32x16_bf16 v[16:31], v[104:107], v[112:115], v[16:31]
	v_mfma_f32_32x32x16_bf16 v[0:15], v[104:107], v[108:111], v[0:15]
	s_setprio 0
	s_mov_b32 m0, s3
	v_lshl_add_u64 v[68:69], v[36:37], 0, s[42:43]
	s_waitcnt vmcnt(0)
	s_waitcnt vmcnt(0)
	s_barrier
	global_load_lds_dwordx4 v[68:69], off
	v_lshl_add_u64 v[68:69], v[34:35], 0, s[42:43]
	s_mov_b32 m0, s0
	s_mov_b64 s[14:15], 0x20480
	global_load_lds_dwordx4 v[68:69], off
	v_lshl_add_u64 v[68:69], v[38:39], 0, s[42:43]
	s_mov_b32 m0, s1
	s_nop 0
	global_load_lds_dwordx4 v[68:69], off
	v_lshl_add_u64 v[68:69], v[40:41], 0, s[42:43]
	s_mov_b32 m0, s2
	s_nop 0
	global_load_lds_dwordx4 v[68:69], off
	v_lshl_add_u64 v[68:69], v[34:35], 0, s[14:15]
	s_mov_b32 m0, s6
	s_mov_b64 s[14:15], 0x30480
	global_load_lds_dwordx4 v[68:69], off
	v_lshl_add_u64 v[68:69], v[34:35], 0, s[14:15]
	s_mov_b32 m0, s7
	s_nop 0
	global_load_lds_dwordx4 v[68:69], off
	ds_read_b128 v[68:71], v45
	ds_read_b128 v[72:75], v46 offset:16384
	ds_read_b128 v[76:79], v46 offset:20480
	ds_read_b128 v[80:83], v47
	ds_read_b128 v[84:87], v51 offset:16384
	ds_read_b128 v[88:91], v51 offset:20480
	ds_read_b128 v[92:95], v52
	ds_read_b128 v[96:99], v53 offset:16384
	ds_read_b128 v[100:103], v53 offset:20480
	ds_read_b128 v[104:107], v54
	ds_read_b128 v[108:111], v55 offset:16384
	ds_read_b128 v[112:115], v55 offset:20480
	s_setprio 1
	s_waitcnt lgkmcnt(0)
	v_mfma_f32_32x32x16_bf16 v[16:31], v[68:71], v[76:79], v[16:31]
	v_mfma_f32_32x32x16_bf16 v[0:15], v[68:71], v[72:75], v[0:15]
	v_mfma_f32_32x32x16_bf16 v[16:31], v[80:83], v[88:91], v[16:31]
	v_mfma_f32_32x32x16_bf16 v[0:15], v[80:83], v[84:87], v[0:15]
	v_mfma_f32_32x32x16_bf16 v[16:31], v[92:95], v[100:103], v[16:31]
	v_mfma_f32_32x32x16_bf16 v[0:15], v[92:95], v[96:99], v[0:15]
	v_mfma_f32_32x32x16_bf16 v[16:31], v[104:107], v[112:115], v[16:31]
	v_mfma_f32_32x32x16_bf16 v[0:15], v[104:107], v[108:111], v[0:15]
	s_setprio 0
	s_mov_b32 m0, s13
	v_lshl_add_u64 v[68:69], v[36:37], 0, s[48:49]
	s_waitcnt vmcnt(0)
	s_waitcnt vmcnt(0)
	s_barrier
	global_load_lds_dwordx4 v[68:69], off
	v_lshl_add_u64 v[68:69], v[34:35], 0, s[48:49]
	s_mov_b32 m0, s8
	s_nop 0
	global_load_lds_dwordx4 v[68:69], off
	v_lshl_add_u64 v[68:69], v[38:39], 0, s[48:49]
	s_mov_b32 m0, s9
	s_mov_b64 s[8:9], 0x20500
	global_load_lds_dwordx4 v[68:69], off
	v_lshl_add_u64 v[68:69], v[40:41], 0, s[48:49]
	s_mov_b32 m0, s12
	s_nop 0
	global_load_lds_dwordx4 v[68:69], off
	v_lshl_add_u64 v[68:69], v[34:35], 0, s[8:9]
	s_mov_b32 m0, s11
	s_mov_b64 s[8:9], 0x30500
	global_load_lds_dwordx4 v[68:69], off
	v_lshl_add_u64 v[68:69], v[34:35], 0, s[8:9]
	s_mov_b32 m0, s10
	s_nop 0
	global_load_lds_dwordx4 v[68:69], off
	ds_read_b128 v[68:71], v45 offset:32768
	ds_read_b128 v[72:75], v46 offset:49152
	ds_read_b128 v[76:79], v46 offset:53248
	ds_read_b128 v[80:83], v47 offset:32768
	ds_read_b128 v[84:87], v51 offset:49152
	ds_read_b128 v[88:91], v51 offset:53248
	ds_read_b128 v[92:95], v52 offset:32768
	ds_read_b128 v[96:99], v53 offset:49152
	ds_read_b128 v[100:103], v53 offset:53248
	ds_read_b128 v[104:107], v54 offset:32768
	ds_read_b128 v[108:111], v55 offset:49152
	ds_read_b128 v[112:115], v55 offset:53248
	s_setprio 1
	s_waitcnt lgkmcnt(0)
	v_mfma_f32_32x32x16_bf16 v[16:31], v[68:71], v[76:79], v[16:31]
	v_mfma_f32_32x32x16_bf16 v[0:15], v[68:71], v[72:75], v[0:15]
	v_mfma_f32_32x32x16_bf16 v[16:31], v[80:83], v[88:91], v[16:31]
	v_mfma_f32_32x32x16_bf16 v[0:15], v[80:83], v[84:87], v[0:15]
	v_mfma_f32_32x32x16_bf16 v[16:31], v[92:95], v[100:103], v[16:31]
	v_mfma_f32_32x32x16_bf16 v[0:15], v[92:95], v[96:99], v[0:15]
	v_mfma_f32_32x32x16_bf16 v[16:31], v[104:107], v[112:115], v[16:31]
	v_mfma_f32_32x32x16_bf16 v[0:15], v[104:107], v[108:111], v[0:15]
	s_setprio 0
	s_mov_b32 m0, s3
	v_lshl_add_u64 v[68:69], v[36:37], 0, s[50:51]
	s_waitcnt vmcnt(0)
	s_waitcnt vmcnt(0)
	s_barrier
; #define MFMA(a, b, c) __builtin_amdgcn_mfma_f32_32x32x16_bf16((a), (b), (c), 0, 0, 0)
;     ...
;   for (int kt = 0; kt < NK; ++kt) {
;     asm volatile("s_waitcnt vmcnt(0)" ::: "memory");
;     __syncthreads();
;     const int cur = (kt & 1) * BUFB, nxt = BUFB - cur;
;     if (kt + 1 < NK) {
; #pragma unroll
;       for (int i = 0; i < 4; ++i) {
;         if (i < NA) __builtin_amdgcn_global_load_lds((const unsigned*)(ap[i] + (kt + 1) * 64), (unsigned*)(ldst + nxt + i * 4096), 16, 0, 0);
;         __builtin_amdgcn_global_load_lds((const unsigned*)(bp[i] + (kt + 1) * 64), (unsigned*)(ldst + nxt + OPB + i * 4096), 16, 0, 0);
;       }
;     }
;     const char* As = smem + cur; const char* Bs = smem + cur + OPB;
;     bf16x8 a[4][IM], b[4][2];
; #pragma unroll
;     for (int kk = 0; kk < 4; ++kk)
; #pragma unroll
;       for (int i = 0; i < 2; ++i) {
;         if (i < IM) a[kk][i] = *(const bf16x8*)(As + aoff[i] + (((2 * kk + h) ^ aswz[i]) << 4));
;         b[kk][i] = *(const bf16x8*)(Bs + boff[i] + (((2 * kk + h) ^ bswz[i]) << 4));
;       }
;     __builtin_amdgcn_sched_barrier(0);
;     __builtin_amdgcn_s_setprio(1);
; #pragma unroll
;     for (int kk = 0; kk < 4; ++kk)
; #pragma unroll
;       for (int i = 0; i < IM; ++i)
; #pragma unroll
;         for (int j = 0; j < 2; ++j) acc[i][j] = MFMA(a[kk][i], b[kk][j], acc[i][j]);
;     __builtin_amdgcn_s_setprio(0);
;   }
	global_load_lds_dwordx4 v[68:69], off
	v_lshl_add_u64 v[68:69], v[34:35], 0, s[50:51]
	s_mov_b32 m0, s0
	s_nop 0
	global_load_lds_dwordx4 v[68:69], off
	v_lshl_add_u64 v[68:69], v[38:39], 0, s[50:51]
	s_mov_b32 m0, s1
	s_mov_b64 s[0:1], 0x20580
	global_load_lds_dwordx4 v[68:69], off
	v_lshl_add_u64 v[68:69], v[40:41], 0, s[50:51]
	s_mov_b32 m0, s2
	s_nop 0
	global_load_lds_dwordx4 v[68:69], off
	v_lshl_add_u64 v[68:69], v[34:35], 0, s[0:1]
	s_mov_b32 m0, s6
	s_mov_b64 s[0:1], 0x30580
	global_load_lds_dwordx4 v[68:69], off
	v_lshl_add_u64 v[68:69], v[34:35], 0, s[0:1]
	s_mov_b32 m0, s7
	s_nop 0
	global_load_lds_dwordx4 v[68:69], off
	ds_read_b128 v[68:71], v45
	ds_read_b128 v[72:75], v46 offset:16384
	ds_read_b128 v[76:79], v46 offset:20480
	ds_read_b128 v[80:83], v47
	ds_read_b128 v[84:87], v51 offset:16384
	ds_read_b128 v[88:91], v51 offset:20480
	ds_read_b128 v[92:95], v52
	ds_read_b128 v[96:99], v53 offset:16384
	ds_read_b128 v[100:103], v53 offset:20480
	ds_read_b128 v[104:107], v54
	ds_read_b128 v[108:111], v55 offset:16384
	ds_read_b128 v[112:115], v55 offset:20480
	s_setprio 1
	s_waitcnt lgkmcnt(0)
	v_mfma_f32_32x32x16_bf16 v[16:31], v[68:71], v[76:79], v[16:31]
	v_mfma_f32_32x32x16_bf16 v[0:15], v[68:71], v[72:75], v[0:15]
	v_mfma_f32_32x32x16_bf16 v[16:31], v[80:83], v[88:91], v[16:31]
	v_mfma_f32_32x32x16_bf16 v[0:15], v[80:83], v[84:87], v[0:15]
	v_mfma_f32_32x32x16_bf16 v[16:31], v[92:95], v[100:103], v[16:31]
	v_mfma_f32_32x32x16_bf16 v[0:15], v[92:95], v[96:99], v[0:15]
	v_mfma_f32_32x32x16_bf16 v[16:31], v[104:107], v[112:115], v[16:31]
	v_mfma_f32_32x32x16_bf16 v[0:15], v[104:107], v[108:111], v[0:15]
	s_setprio 0
	v_readfirstlane_b32 s2, v62
	v_lshl_add_u64 v[68:69], v[36:37], 0, s[18:19]
	s_mov_b32 m0, s2
	v_readfirstlane_b32 s3, v63
	s_waitcnt vmcnt(0)
	s_waitcnt vmcnt(0)
	s_barrier
	global_load_lds_dwordx4 v[68:69], off
	v_lshl_add_u64 v[68:69], v[34:35], 0, s[18:19]
	s_mov_b32 m0, s3
	v_readfirstlane_b32 s6, v66
	global_load_lds_dwordx4 v[68:69], off
	v_lshl_add_u64 v[62:63], v[38:39], 0, s[18:19]
	s_mov_b32 m0, s6
	v_readfirstlane_b32 s7, v67
	global_load_lds_dwordx4 v[62:63], off
	v_lshl_add_u64 v[62:63], v[40:41], 0, s[18:19]
	s_mov_b32 m0, s7
	s_mov_b64 s[0:1], 0x20600
	v_readfirstlane_b32 s8, v65
	global_load_lds_dwordx4 v[62:63], off
	v_lshl_add_u64 v[62:63], v[34:35], 0, s[0:1]
	s_mov_b32 m0, s8
	s_mov_b64 s[0:1], 0x30600
	v_readfirstlane_b32 s9, v64
	global_load_lds_dwordx4 v[62:63], off
	v_lshl_add_u64 v[62:63], v[34:35], 0, s[0:1]
	s_mov_b32 m0, s9
	s_nop 0
	global_load_lds_dwordx4 v[62:63], off
	ds_read_b128 v[62:65], v45 offset:32768
	ds_read_b128 v[66:69], v46 offset:49152
	ds_read_b128 v[70:73], v46 offset:53248
	ds_read_b128 v[74:77], v47 offset:32768
	ds_read_b128 v[78:81], v51 offset:49152
	ds_read_b128 v[82:85], v51 offset:53248
	ds_read_b128 v[86:89], v52 offset:32768
	ds_read_b128 v[90:93], v53 offset:49152
	ds_read_b128 v[94:97], v53 offset:53248
	ds_read_b128 v[98:101], v54 offset:32768
	ds_read_b128 v[102:105], v55 offset:49152
	ds_read_b128 v[106:109], v55 offset:53248
	s_setprio 1
	s_waitcnt lgkmcnt(0)
	v_mfma_f32_32x32x16_bf16 v[16:31], v[62:65], v[70:73], v[16:31]
	v_mfma_f32_32x32x16_bf16 v[0:15], v[62:65], v[66:69], v[0:15]
	v_mfma_f32_32x32x16_bf16 v[16:31], v[74:77], v[82:85], v[16:31]
	v_mfma_f32_32x32x16_bf16 v[0:15], v[74:77], v[78:81], v[0:15]
	v_mfma_f32_32x32x16_bf16 v[16:31], v[86:89], v[94:97], v[16:31]
	v_mfma_f32_32x32x16_bf16 v[0:15], v[86:89], v[90:93], v[0:15]
	v_mfma_f32_32x32x16_bf16 v[16:31], v[98:101], v[106:109], v[16:31]
	v_mfma_f32_32x32x16_bf16 v[0:15], v[98:101], v[102:105], v[0:15]
	s_setprio 0
	v_readfirstlane_b32 s10, v57
	v_lshl_add_u64 v[62:63], v[36:37], 0, s[46:47]
	s_mov_b32 m0, s10
	v_readfirstlane_b32 s11, v56
	s_waitcnt vmcnt(0)
	s_waitcnt vmcnt(0)
	s_barrier
	global_load_lds_dwordx4 v[62:63], off
	v_lshl_add_u64 v[62:63], v[34:35], 0, s[46:47]
	s_mov_b32 m0, s11
	v_readfirstlane_b32 s12, v58
	global_load_lds_dwordx4 v[62:63], off
	v_lshl_add_u64 v[56:57], v[38:39], 0, s[46:47]
	s_mov_b32 m0, s12
	v_readfirstlane_b32 s13, v59
	global_load_lds_dwordx4 v[56:57], off
	v_lshl_add_u64 v[56:57], v[40:41], 0, s[46:47]
	s_mov_b32 m0, s13
	s_mov_b64 s[0:1], 0x20680
	v_readfirstlane_b32 s14, v60
	global_load_lds_dwordx4 v[56:57], off
	v_lshl_add_u64 v[56:57], v[34:35], 0, s[0:1]
	s_mov_b32 m0, s14
	s_mov_b64 s[0:1], 0x30680
	v_readfirstlane_b32 s15, v61
	global_load_lds_dwordx4 v[56:57], off
	v_lshl_add_u64 v[56:57], v[34:35], 0, s[0:1]
	s_mov_b32 m0, s15
	s_nop 0
	global_load_lds_dwordx4 v[56:57], off
	ds_read_b128 v[56:59], v45
	ds_read_b128 v[60:63], v46 offset:16384
	ds_read_b128 v[64:67], v46 offset:20480
	ds_read_b128 v[68:71], v47
	ds_read_b128 v[72:75], v51 offset:16384
	ds_read_b128 v[76:79], v51 offset:20480
	ds_read_b128 v[80:83], v52
	ds_read_b128 v[84:87], v53 offset:16384
	ds_read_b128 v[88:91], v53 offset:20480
	ds_read_b128 v[92:95], v54
	ds_read_b128 v[96:99], v55 offset:16384
	ds_read_b128 v[100:103], v55 offset:20480
	s_setprio 1
	s_waitcnt lgkmcnt(0)
	v_mfma_f32_32x32x16_bf16 v[16:31], v[56:59], v[64:67], v[16:31]
	v_mfma_f32_32x32x16_bf16 v[0:15], v[56:59], v[60:63], v[0:15]
	v_mfma_f32_32x32x16_bf16 v[16:31], v[68:71], v[76:79], v[16:31]
	v_mfma_f32_32x32x16_bf16 v[0:15], v[68:71], v[72:75], v[0:15]
	v_mfma_f32_32x32x16_bf16 v[16:31], v[80:83], v[88:91], v[16:31]
	v_mfma_f32_32x32x16_bf16 v[0:15], v[80:83], v[84:87], v[0:15]
	v_mfma_f32_32x32x16_bf16 v[16:31], v[92:95], v[100:103], v[16:31]
	v_mfma_f32_32x32x16_bf16 v[0:15], v[92:95], v[96:99], v[0:15]
	s_setprio 0
	s_mov_b32 m0, s2
	v_lshl_add_u64 v[56:57], v[36:37], 0, s[68:69]
	s_waitcnt vmcnt(0)
	s_waitcnt vmcnt(0)
	s_barrier
; #define MFMA(a, b, c) __builtin_amdgcn_mfma_f32_32x32x16_bf16((a), (b), (c), 0, 0, 0)
;   DI float* ropeC() const { return (float*)(ws + WS_ropeC); }
;   DI float* ropeS() const { return (float*)(ws + WS_ropeS); }
; DI int crow(int reg, int h) { return (reg & 3) + 8 * (reg >> 2) + 4 * h; }
;     ...
;     __builtin_amdgcn_sched_barrier(0);
;     __builtin_amdgcn_s_setprio(1);
; #pragma unroll
;     for (int kk = 0; kk < 4; ++kk)
; #pragma unroll
;       for (int i = 0; i < IM; ++i)
; #pragma unroll
;         for (int j = 0; j < 2; ++j) acc[i][j] = MFMA(a[kk][i], b[kk][j], acc[i][j]);
;     __builtin_amdgcn_s_setprio(0);
;   }
;   __syncthreads();
;   float* Cs = (float*)smem;
; #pragma unroll
;   for (int i = 0; i < IM; ++i)
; #pragma unroll
;     for (int j = 0; j < 2; ++j)
; #pragma unroll
;       for (int e = 0; e < 16; ++e) Cs[(wm * (BM / 2) + i * 32 + crow(e, h)) * CS_LD + wn * 64 + j * 32 + r] = acc[i][j][e];
;   __syncthreads();
;     ...
;       if (d < 16) {
;         const bool second = d >= 8; const int i0 = d & 7; const int gb = c4 - d;
; #pragma unroll
;         for (int e = 0; e < 4; ++e) {
;           int i = i0 + e;
;           float x1 = cr[gb + i], x2 = cr[gb + 8 + i];
;           float cs = p.ropeC()[pos * 24 + 16 + i], sn = p.ropeS()[pos * 24 + 16 + i];
;           o[e] = second ? (x1 * sn + x2 * cs) : (x1 * cs - x2 * sn);
;         }
;       }
	global_load_lds_dwordx4 v[56:57], off
	v_lshl_add_u64 v[56:57], v[34:35], 0, s[68:69]
	s_mov_b32 m0, s3
	s_mov_b64 s[0:1], 0x20700
	global_load_lds_dwordx4 v[56:57], off
	v_lshl_add_u64 v[56:57], v[38:39], 0, s[68:69]
	s_mov_b32 m0, s6
	s_nop 0
	global_load_lds_dwordx4 v[56:57], off
	v_lshl_add_u64 v[56:57], v[40:41], 0, s[68:69]
	s_mov_b32 m0, s7
	s_nop 0
	global_load_lds_dwordx4 v[56:57], off
	v_lshl_add_u64 v[56:57], v[34:35], 0, s[0:1]
	s_mov_b32 m0, s8
	s_mov_b64 s[0:1], 0x30700
	global_load_lds_dwordx4 v[56:57], off
	v_lshl_add_u64 v[56:57], v[34:35], 0, s[0:1]
	s_mov_b32 m0, s9
	s_nop 0
	global_load_lds_dwordx4 v[56:57], off
	ds_read_b128 v[56:59], v45 offset:32768
	ds_read_b128 v[60:63], v46 offset:49152
	ds_read_b128 v[64:67], v46 offset:53248
	ds_read_b128 v[68:71], v47 offset:32768
	ds_read_b128 v[72:75], v51 offset:49152
	ds_read_b128 v[76:79], v51 offset:53248
	ds_read_b128 v[80:83], v52 offset:32768
	ds_read_b128 v[84:87], v53 offset:49152
	ds_read_b128 v[88:91], v53 offset:53248
	ds_read_b128 v[92:95], v54 offset:32768
	ds_read_b128 v[96:99], v55 offset:49152
	ds_read_b128 v[100:103], v55 offset:53248
	s_setprio 1
	s_waitcnt lgkmcnt(0)
	v_mfma_f32_32x32x16_bf16 v[16:31], v[56:59], v[64:67], v[16:31]
	v_mfma_f32_32x32x16_bf16 v[0:15], v[56:59], v[60:63], v[0:15]
	v_mfma_f32_32x32x16_bf16 v[16:31], v[68:71], v[76:79], v[16:31]
	v_mfma_f32_32x32x16_bf16 v[0:15], v[68:71], v[72:75], v[0:15]
	v_mfma_f32_32x32x16_bf16 v[16:31], v[80:83], v[88:91], v[16:31]
	v_mfma_f32_32x32x16_bf16 v[0:15], v[80:83], v[84:87], v[0:15]
	v_mfma_f32_32x32x16_bf16 v[16:31], v[92:95], v[100:103], v[16:31]
	v_mfma_f32_32x32x16_bf16 v[0:15], v[92:95], v[96:99], v[0:15]
	s_setprio 0
	s_mov_b32 m0, s10
	v_lshl_add_u64 v[36:37], v[36:37], 0, s[72:73]
	s_waitcnt vmcnt(0)
	s_waitcnt vmcnt(0)
	s_barrier
	global_load_lds_dwordx4 v[36:37], off
	v_lshl_add_u64 v[36:37], v[34:35], 0, s[72:73]
	s_mov_b32 m0, s11
	s_mov_b64 s[0:1], 0x20780
	global_load_lds_dwordx4 v[36:37], off
	v_lshl_add_u64 v[36:37], v[38:39], 0, s[72:73]
	s_mov_b32 m0, s12
	s_nop 0
	global_load_lds_dwordx4 v[36:37], off
	v_lshl_add_u64 v[36:37], v[40:41], 0, s[72:73]
	s_mov_b32 m0, s13
	s_nop 0
	global_load_lds_dwordx4 v[36:37], off
	v_lshl_add_u64 v[36:37], v[34:35], 0, s[0:1]
	s_mov_b32 m0, s14
	s_mov_b64 s[0:1], 0x30780
	global_load_lds_dwordx4 v[36:37], off
	v_lshl_add_u64 v[34:35], v[34:35], 0, s[0:1]
	s_mov_b32 m0, s15
	s_nop 0
	global_load_lds_dwordx4 v[34:35], off
	ds_read_b128 v[34:37], v45
	ds_read_b128 v[38:41], v46 offset:16384
	ds_read_b128 v[56:59], v46 offset:20480
	ds_read_b128 v[60:63], v47
	ds_read_b128 v[64:67], v51 offset:16384
	ds_read_b128 v[68:71], v51 offset:20480
	ds_read_b128 v[72:75], v52
	ds_read_b128 v[76:79], v53 offset:16384
	ds_read_b128 v[80:83], v53 offset:20480
	ds_read_b128 v[84:87], v54
	ds_read_b128 v[88:91], v55 offset:16384
	ds_read_b128 v[92:95], v55 offset:20480
	s_setprio 1
	s_waitcnt lgkmcnt(0)
	v_mfma_f32_32x32x16_bf16 v[16:31], v[34:37], v[56:59], v[16:31]
	v_mfma_f32_32x32x16_bf16 v[0:15], v[34:37], v[38:41], v[0:15]
	v_mfma_f32_32x32x16_bf16 v[16:31], v[60:63], v[68:71], v[16:31]
	v_mfma_f32_32x32x16_bf16 v[0:15], v[60:63], v[64:67], v[0:15]
	v_mfma_f32_32x32x16_bf16 v[16:31], v[72:75], v[80:83], v[16:31]
	v_mfma_f32_32x32x16_bf16 v[0:15], v[72:75], v[76:79], v[0:15]
	v_mfma_f32_32x32x16_bf16 v[16:31], v[84:87], v[92:95], v[16:31]
	v_mfma_f32_32x32x16_bf16 v[0:15], v[84:87], v[88:91], v[0:15]
	s_setprio 0
	s_waitcnt vmcnt(0)
	s_waitcnt vmcnt(0)
	s_barrier
	ds_read_b128 v[34:37], v45 offset:32768
	ds_read_b128 v[38:41], v46 offset:49152
	ds_read_b128 v[56:59], v46 offset:53248
	ds_read_b128 v[60:63], v47 offset:32768
	ds_read_b128 v[64:67], v51 offset:49152
	ds_read_b128 v[68:71], v51 offset:53248
	ds_read_b128 v[72:75], v52 offset:32768
	ds_read_b128 v[76:79], v53 offset:49152
	ds_read_b128 v[80:83], v53 offset:53248
	ds_read_b128 v[84:87], v54 offset:32768
	ds_read_b128 v[88:91], v55 offset:49152
	ds_read_b128 v[52:55], v55 offset:53248
	s_setprio 1
	s_waitcnt lgkmcnt(9)
	v_mfma_f32_32x32x16_bf16 v[16:31], v[34:37], v[56:59], v[16:31]
	v_mfma_f32_32x32x16_bf16 v[0:15], v[34:37], v[38:41], v[0:15]
	s_waitcnt lgkmcnt(6)
	v_mfma_f32_32x32x16_bf16 v[16:31], v[60:63], v[68:71], v[16:31]
	v_mfma_f32_32x32x16_bf16 v[0:15], v[60:63], v[64:67], v[0:15]
	s_waitcnt lgkmcnt(3)
	v_mfma_f32_32x32x16_bf16 v[16:31], v[72:75], v[80:83], v[16:31]
	v_mfma_f32_32x32x16_bf16 v[0:15], v[72:75], v[76:79], v[0:15]
	s_waitcnt lgkmcnt(0)
	v_mfma_f32_32x32x16_bf16 v[16:31], v[84:87], v[52:55], v[16:31]
	v_mfma_f32_32x32x16_bf16 v[0:15], v[84:87], v[88:91], v[0:15]
	s_setprio 0
	v_lshlrev_b32_e32 v34, 5, v42
	v_lshlrev_b32_e32 v35, 8, v44
	v_lshl_or_b32 v34, v43, 2, v34
	v_lshl_or_b32 v32, v32, 2, v35
	s_movk_i32 s79, 0x210
	v_mad_u64_u32 v[34:35], s[0:1], v34, s79, v[32:33]
	s_barrier
	s_nop 3
	ds_write2_b32 v34, v0, v16 offset1:32
	ds_write2_b32 v34, v1, v17 offset0:132 offset1:164
	v_add_u32_e32 v0, 0x400, v34
	ds_write2_b32 v0, v2, v18 offset0:8 offset1:40
	ds_write2_b32 v0, v3, v19 offset0:140 offset1:172
	v_add_u32_e32 v0, 0x1000, v34
	ds_write2_b32 v0, v4, v20 offset0:32 offset1:64
	ds_write2_b32 v0, v5, v21 offset0:164 offset1:196
	v_add_u32_e32 v0, 0x1400, v34
	ds_write2_b32 v0, v6, v22 offset0:40 offset1:72
	ds_write2_b32 v0, v7, v23 offset0:172 offset1:204
	v_add_u32_e32 v0, 0x2000, v34
	ds_write2_b32 v0, v8, v24 offset0:64 offset1:96
	ds_write2_b32 v0, v9, v25 offset0:196 offset1:228
	v_add_u32_e32 v0, 0x2400, v34
	s_cmp_gt_i32 s78, 1
	ds_write2_b32 v0, v10, v26 offset0:72 offset1:104
	ds_write2_b32 v0, v11, v27 offset0:204 offset1:236
	v_add_u32_e32 v0, 0x3000, v34
	s_cselect_b64 s[2:3], -1, 0
	s_cmp_gt_u32 s78, 7
	ds_write2_b32 v0, v12, v28 offset0:96 offset1:128
	v_add_u32_e32 v0, 0x3200, v34
	s_cselect_b64 s[76:77], -1, 0
	s_cmp_gt_u32 s78, 15
	ds_write2_b32 v0, v13, v29 offset0:100 offset1:132
	v_add_u32_e32 v0, 0x3400, v34
	s_cselect_b64 s[0:1], -1, 0
	s_cmp_gt_u32 s78, 19
	ds_write2_b32 v0, v14, v30 offset0:104 offset1:136
	v_add_u32_e32 v0, 0x3600, v34
	v_mov_b32_e32 v4, v186
	s_cselect_b64 s[20:21], -1, 0
	s_add_i32 s10, s90, 0xfffff800
	ds_write2_b32 v0, v15, v31 offset0:108 offset1:140
	s_cmp_gt_u32 s78, 7
	s_cbranch_scc0 .Le1as_nostage
	s_cmp_lt_u32 s78, 16
	s_cbranch_scc0 .Le1as_nostage
	v_lshrrev_b32_e32 v182, 2, v186
	v_and_b32_e32 v183, 3, v186
	v_and_b32_e32 v184, 15, v182
	v_or_b32_e32 v184, 0x800, v184
	v_mad_u32_u24 v184, v184, 24, 16
	v_and_b32_e32 v185, 1, v183
	v_lshl_add_u32 v184, v185, 2, v184
	v_lshlrev_b32_e32 v184, 2, v184
	v_lshrrev_b32_e32 v185, 1, v183
	v_mul_u32_u24_e32 v185, 0x60000, v185
	v_add_u32_e32 v184, v184, v185
	global_load_dwordx4 v[188:191], v184, s[22:23]
	v_lshlrev_b32_e32 v182, 6, v182
	v_lshl_add_u32 v182, v183, 4, v182
	v_add_u32_e32 v182, 0x10800, v182
	s_waitcnt vmcnt(0)
	ds_write_b128 v182, v[188:191]
;   DI u16* qlat() const { return (u16*)(ws + WS_qlat); }
;   DI u16* Kmla() const { return (u16*)(ws + WS_Kmla); }
;   DI u16* gm() const { return (u16*)(ws + WS_gm); }
;   DI float* ssq() const { return (float*)(ws + WS_ssq); }
;   DI float* ropeC() const { return (float*)(ws + WS_ropeC); }
;   const int tid = otid(), c4 = (tid & 31) * 4;
;   for (int pp = 0; pp < npass; ++pp) {
;     const int row = pp * 8 + (tid >> 5);
;     const int tok = mt * 128 + row0 + row;
;     const bool smp = tok >= TP;
;     const int pos = smp ? 2048 + ((tok - TP) & 15) : (tok & 4095);
;     const float* cr = Cs + row * CS_LD;
;     float4 v = *(const float4*)(cr + c4);
;     if (nt < 2) {
;       st_bf4(p.qlat() + (size_t)tok * 256 + nt * 128 + c4, v.x, v.y, v.z, v.w);
;       float ss = half_sum(v.x * v.x + v.y * v.y + v.z * v.z + v.w * v.w);
;       if ((tid & 31) == 0) p.ssq()[tok * 2 + nt] = ss;
;     } else if (nt == 2) {
;       float ss = half_sum(v.x * v.x + v.y * v.y + v.z * v.z + v.w * v.w);
;       float rstd = rsqrtf(ss * (1.f / 128.f) + EPS);
;       float4 g = *(const float4*)(p.kv_g + c4);
;       float4 o = make_float4(v.x * rstd * g.x, v.y * rstd * g.y, v.z * rstd * g.z, v.w * rstd * g.w);
;       float* d = smp ? p.out + OFF_CKV_S + (size_t)(tok - TP) * 128 + c4 : p.out + OFF_CKV_P + (size_t)tok * 128 + c4;
;       st_nt4(d, o);
;       st_bf4(p.Kmla() + (size_t)tok * 160 + c4, o.x, o.y, o.z, o.w);
;     } else if (nt == 3) {
;       if (c4 < 32) {
;         const bool second = c4 >= 16; const int i0 = c4 & 15;
;         float o[4];
; #pragma unroll
;         for (int e = 0; e < 4; ++e) {
;           int i = i0 + e;
;           float x1 = cr[i], x2 = cr[i + 16];
;           float cs = p.ropeC()[pos * 24 + i], sn = p.ropeS()[pos * 24 + i];
;           o[e] = second ? (x1 * sn + x2 * cs) : (x1 * cs - x2 * sn);
;         }
;         float* d = smp ? p.out + OFF_KR_S + (size_t)(tok - TP) * 32 + c4 : p.out + OFF_KR_P + (size_t)tok * 32 + c4;
;         st_nt4(d, make_float4(o[0], o[1], o[2], o[3]));
;         st_bf4(p.Kmla() + (size_t)tok * 160 + 128 + c4, o[0], o[1], o[2], o[3]);
;       }
;     } else if (nt < 8) {
;       st_bf4(p.gm() + (size_t)tok * 512 + (nt - 4) * 128 + c4, silu(v.x), silu(v.y), silu(v.z), silu(v.w));
;     } else if (nt < 16) {
;       const bool isq = nt < 12;
;       const int c512 = (nt - (isq ? 8 : 12)) * 128 + c4;
.Le1as_nostage:
	s_waitcnt lgkmcnt(0)
	s_barrier
	s_cmp_gt_u32 s78, 11
	v_and_b32_e32 v0, 31, v4
	v_lshlrev_b32_e32 v20, 2, v0
	s_cselect_b64 s[26:27], -1, 0
	s_cmp_lt_u32 s78, 12
	v_or_b32_e32 v22, s10, v20
	s_cselect_b32 s10, -8, -12
	s_add_i32 s10, s10, s78
	v_and_b32_e32 v1, 60, v20
	v_readlane_b32 s80, v247, 38
	v_cmp_gt_u32_e64 s[6:7], 8, v0
	v_cmp_lt_u32_e64 s[8:9], 3, v0
	v_lshl_or_b32 v24, s10, 7, v20
	v_cmp_gt_u32_e64 s[10:11], 16, v1
	v_cmp_lt_u32_e64 s[12:13], 7, v1
	v_cmp_eq_u32_e64 s[14:15], 0, v0
	v_lshlrev_b32_e32 v32, 4, v0
	v_lshlrev_b32_e32 v0, 3, v0
	v_mov_b32_e32 v1, v33
	v_readlane_b32 s81, v247, 39
	s_ashr_i32 vcc_hi, s90, 31
	s_lshl_b64 s[28:29], s[90:91], 1
	v_lshl_add_u64 v[28:29], s[80:81], 0, v[0:1]
	v_readlane_b32 s80, v247, 44
	v_mov_b32_e32 v23, v33
	s_mov_b32 vcc_lo, s90
	s_add_u32 s28, s86, s28
	v_readlane_b32 s81, v247, 45
	s_addc_u32 s29, s87, s29
	s_lshl_b64 vcc, vcc, 1
	v_lshl_add_u64 v[30:31], v[22:23], 1, s[80:81]
	v_readlane_b32 s80, v247, 50
	v_readlane_b32 s45, v247, 54
	v_ashrrev_i32_e32 v21, 5, v4
	v_lshlrev_b32_e32 v2, 1, v24
	v_mov_b32_e32 v3, v33
	v_readlane_b32 s81, v247, 51
	s_add_u32 vcc_lo, s45, vcc_lo
	v_readlane_b32 s45, v247, 55
	v_lshl_add_u64 v[34:35], s[80:81], 0, v[2:3]
	v_readlane_b32 s80, v247, 52
	s_addc_u32 vcc_hi, s45, vcc_hi
	v_add_u32_e32 v58, s44, v21
	s_lshl_b32 s44, s17, 7
	v_readlane_b32 s81, v247, 53
	s_and_b32 s44, s44, 0xffffff00
	s_and_b32 s17, s17, 1
	v_lshl_add_u64 v[36:37], s[80:81], 0, v[2:3]
	v_and_b32_e32 v2, 1, v4
	s_add_i32 s44, s70, s44
	s_lshl_b32 s17, s17, 7
	v_lshl_add_u64 v[38:39], vcc, 0, v[0:1]
	v_mul_lo_u32 v0, v21, s79
	v_and_b32_e32 v1, 0x100, v32
	v_lshlrev_b32_e32 v2, 4, v2
	s_add_i32 s17, s44, s17
	v_add3_u32 v55, v0, v1, v2
	v_and_b32_e32 v1, 3, v4
	s_add_i32 s17, s17, 0x8000
	v_and_b32_e32 v52, 4, v20
	v_lshl_add_u32 v56, v1, 4, v0
	v_add_u32_e32 v57, v0, v32
	v_lshl_add_u32 v0, v21, 1, s17
	v_and_b32_e32 v51, 12, v20
	v_mov_b32_e32 v25, v33
	v_or_b32_e32 v53, 2, v52
	v_or_b32_e32 v54, 3, v52
	v_lshl_add_u64 v[26:27], s[74:75], 0, v[32:33]
	v_subrev_u32_e32 v40, s16, v0
	s_mov_b32 s79, 0
	s_branch .LBB0_239

;   DI float* ropeC() const { return (float*)(ws + WS_ropeC); }
;   DI float* ropeS() const { return (float*)(ws + WS_ropeS); }
;     ...
;       if (d < 16) {
;         const bool second = d >= 8; const int i0 = d & 7; const int gb = c4 - d;
; #pragma unroll
;         for (int e = 0; e < 4; ++e) {
;           int i = i0 + e;
;           float x1 = cr[gb + i], x2 = cr[gb + 8 + i];
;           float cs = p.ropeC()[pos * 24 + 16 + i], sn = p.ropeS()[pos * 24 + 16 + i];
;           o[e] = second ? (x1 * sn + x2 * cs) : (x1 * cs - x2 * sn);
;         }
;       }
.LBB0_253:
	s_andn2_b64 vcc, exec, s[44:45]
	s_cbranch_vccnz .LBB0_258
	s_waitcnt lgkmcnt(0)
	v_mov_b32_e32 v4, v0
	v_mov_b32_e32 v5, v1
	v_mov_b32_e32 v6, v2
	v_mov_b32_e32 v7, v3
	s_and_saveexec_b64 vcc, s[10:11]
	s_cbranch_execz .LBB0_281
	v_add_u32_e32 v11, s79, v21
	v_lshlrev_b32_e32 v11, 6, v11
	v_lshl_add_u32 v11, v52, 2, v11
	v_add_u32_e32 v11, 0x10800, v11
	ds_read_b128 v[6:9], v55
	ds_read_b128 v[12:15], v55 offset:32
	ds_read_b128 v[188:191], v11
	ds_read_b128 v[192:195], v11 offset:32
	s_waitcnt lgkmcnt(0)
	v_pk_mul_f32 v[196:197], v[12:13], v[192:193]
	v_pk_mul_f32 v[198:199], v[14:15], v[194:195]
	v_pk_mul_f32 v[200:201], v[6:7], v[192:193]
	v_pk_mul_f32 v[202:203], v[8:9], v[194:195]
	v_pk_fma_f32 v[196:197], v[6:7], v[188:189], v[196:197] neg_lo:[0,0,1] neg_hi:[0,0,1]
	v_pk_fma_f32 v[198:199], v[8:9], v[190:191], v[198:199] neg_lo:[0,0,1] neg_hi:[0,0,1]
	v_pk_fma_f32 v[200:201], v[12:13], v[188:189], v[200:201]
	v_pk_fma_f32 v[202:203], v[14:15], v[190:191], v[202:203]
	v_cndmask_b32_e64 v4, v196, v200, s[12:13]
	v_cndmask_b32_e64 v5, v197, v201, s[12:13]
	v_cndmask_b32_e64 v6, v198, v202, s[12:13]
	v_cndmask_b32_e64 v7, v199, v203, s[12:13]
	s_or_b64 exec, exec, vcc
	s_mov_b64 s[44:45], -1
	s_and_b64 vcc, exec, s[26:27]
	s_cbranch_vccnz .LBB0_282

; template <int K, typename Epi>
; DI void gemm_tile_wide(const u16* __restrict__ A, int lda, const u16* __restrict__ Bt, int ldb, int m0, int n0, char* smem, Epi epi) {
;     ...
;   f32x16 acc[2][4];
; #pragma unroll
;   for (int i = 0; i < 2; ++i)
; #pragma unroll
;     for (int j = 0; j < 4; ++j)
; #pragma unroll
;       for (int e = 0; e < 16; ++e) acc[i][j][e] = 0.f;
;   constexpr int NS = K / 32;
;   constexpr int AB = 128 * 64;
;   constexpr int STB = AB + 256 * 64;
;   const int lrow = tid >> 2, cpos = tid & 3;
;   const u16* ap[2]; const u16* bp[4];
; #pragma unroll
;   for (int i = 0; i < 4; ++i) {
;     const int row = lrow + 64 * i;
;     const int sc = cpos ^ ((row >> 2) & 3);
;     if (i < 2) ap[i] = A + (size_t)(m0 + row) * lda + sc * 8;
;     bp[i] = Bt + (size_t)(n0 + row) * ldb + sc * 8;
;   }
;   char* const ldst = smem + tid * 16;
;   int aoff[2][2], boff[4][2];
; #pragma unroll
;   for (int kk = 0; kk < 2; ++kk) {
; #pragma unroll
;     for (int i = 0; i < 2; ++i) { const int ra_ = wm * 64 + i * 32 + r; aoff[i][kk] = ra_ * 64 + (((2 * kk + h) ^ ((ra_ >> 2) & 3)) << 4); }
; #pragma unroll
;     for (int j = 0; j < 4; ++j) { const int rb_ = wn * 128 + j * 32 + r; boff[j][kk] = AB + rb_ * 64 + (((2 * kk + h) ^ ((rb_ >> 2) & 3)) << 4); }
;   }
;   auto issue = [&](int slice, int st) {
; #pragma unroll
;     for (int i = 0; i < 4; ++i) {
;       if (i < 2) __builtin_amdgcn_global_load_lds((const unsigned*)(ap[i] + slice * 32), (unsigned*)(ldst + st + i * 4096), 16, 0, 0);
;       __builtin_amdgcn_global_load_lds((const unsigned*)(bp[i] + slice * 32), (unsigned*)(ldst + st + AB + i * 4096), 16, 0, 0);
;     }
;   };
;   __syncthreads();
;   issue(0, 0);
.LBB0_642:
	v_mov_b32_e32 v12, v186
	s_lshl_b32 s2, s5, 5
	s_and_b32 s27, s2, 0xffffff80
	v_lshrrev_b32_e32 v15, 4, v12
	v_ashrrev_i32_e32 v14, 2, v12
	v_xor_b32_e32 v0, v15, v12
	v_lshlrev_b32_e32 v0, 4, v0
	v_add_u32_e32 v4, s27, v14
	s_lshl_b32 s2, s5, 8
	v_and_b32_e32 v136, 48, v0
	v_ashrrev_i32_e32 v5, 31, v4
	v_lshlrev_b32_e32 v147, 4, v12
	s_and_b32 s26, s2, 0x300
	v_lshl_add_u64 v[2:3], s[38:39], 0, v[136:137]
	v_lshlrev_b64 v[4:5], 11, v[4:5]
	v_readfirstlane_b32 s2, v147
	v_lshl_add_u64 v[4:5], v[2:3], 0, v[4:5]
	v_add_u32_e32 v6, s26, v14
	v_add_u32_e32 v16, 64, v14
	s_mov_b32 m0, s2
	v_ashrrev_i32_e32 v7, 31, v6
	v_add_u32_e32 v8, s27, v16
	s_barrier
	global_load_lds_dwordx4 v[4:5], off
	v_add_u32_e32 v4, 0x2000, v147
	v_lshl_add_u64 v[0:1], s[6:7], 0, v[136:137]
	v_lshlrev_b64 v[6:7], 11, v[6:7]
	v_ashrrev_i32_e32 v9, 31, v8
	v_readfirstlane_b32 s2, v4
	v_add_u32_e32 v4, 0x1000, v147
	v_lshl_add_u64 v[6:7], v[0:1], 0, v[6:7]
	v_lshlrev_b64 v[8:9], 11, v[8:9]
	s_mov_b32 m0, s2
	v_readfirstlane_b32 s2, v4
	v_lshl_add_u64 v[2:3], v[2:3], 0, v[8:9]
	v_add_u32_e32 v8, s26, v16
	global_load_lds_dwordx4 v[6:7], off
	s_mov_b32 m0, s2
	v_ashrrev_i32_e32 v9, 31, v8
	global_load_lds_dwordx4 v[2:3], off
	v_add_u32_e32 v2, 0x3000, v147
	v_lshlrev_b64 v[8:9], 11, v[8:9]
	v_readfirstlane_b32 s2, v2
	v_lshl_add_u64 v[0:1], v[0:1], 0, v[8:9]
	s_mov_b32 m0, s2
	v_lshl_add_u64 v[8:9], v[6:7], 0, s[14:15]
	global_load_lds_dwordx4 v[0:1], off
	v_add_u32_e32 v0, 0x4000, v147
	v_lshl_add_u64 v[10:11], v[6:7], 0, s[16:17]
	v_readfirstlane_b32 s2, v0
	v_add_u32_e32 v0, 0x5000, v147
	s_mov_b32 m0, s2
	v_readfirstlane_b32 s2, v0
	global_load_lds_dwordx4 v[8:9], off
	s_mov_b32 m0, s2
	s_and_b32 s0, s19, 0xffffff80
	global_load_lds_dwordx4 v[10:11], off
	v_add_u32_e32 v0, s0, v14
	v_ashrrev_i32_e32 v1, 31, v0
	v_bitop3_b32 v2, v15, 3, v12 bitop3:0x48
	v_lshlrev_b64 v[0:1], 11, v[0:1]
	v_lshlrev_b32_e32 v4, 4, v2
	s_and_b32 s1, s22, 0x300
	v_or_b32_e32 v0, v0, v4
	v_lshl_add_u64 v[128:129], s[10:11], 0, v[0:1]
	v_add_u32_e32 v0, s1, v14
	v_ashrrev_i32_e32 v1, 31, v0
	v_lshlrev_b64 v[2:3], 11, v[0:1]
	v_or_b32_e32 v2, v2, v4
	v_lshl_add_u64 v[130:131], s[12:13], 0, v[2:3]
	v_add_u32_e32 v2, s0, v16
	v_ashrrev_i32_e32 v3, 31, v2
	v_lshlrev_b64 v[2:3], 11, v[2:3]
	v_or_b32_e32 v2, v2, v4
	v_lshl_add_u64 v[132:133], s[10:11], 0, v[2:3]
	v_add_u32_e32 v2, s1, v16
	v_ashrrev_i32_e32 v3, 31, v2
	v_lshlrev_b64 v[2:3], 11, v[2:3]
	v_or_b32_e32 v2, v2, v4
	v_lshrrev_b32_e32 v13, 5, v12
	v_bfe_u32 v143, v12, 5, 1
	v_and_b32_e32 v144, 31, v12
	v_bfe_u32 v17, v12, 2, 2
	v_lshl_add_u64 v[134:135], s[12:13], 0, v[2:3]
	v_add_u32_e32 v2, 0x80, v0
	v_add_u32_e32 v0, 0xc0, v0
	v_bfe_u32 v136, v12, 6, 1
	v_lshlrev_b32_e32 v18, 6, v144
	v_bitop3_b32 v13, v13, v17, 1 bitop3:0x6c
	v_bitop3_b32 v17, v143, v17, 2 bitop3:0x36
	v_ashrrev_i32_e32 v3, 31, v2
	v_ashrrev_i32_e32 v1, 31, v0
	v_ashrrev_i32_e32 v142, 7, v12
	v_lshl_or_b32 v19, v136, 13, v18
	v_lshlrev_b32_e32 v13, 4, v13
	v_lshlrev_b32_e32 v17, 4, v17
	v_lshlrev_b64 v[2:3], 11, v[2:3]
	v_lshlrev_b64 v[0:1], 11, v[0:1]
	v_lshl_or_b32 v18, v142, 12, v18
	v_or_b32_e32 v148, v19, v13
	v_or_b32_e32 v150, v17, v19
	v_or_b32_e32 v2, v2, v4
	v_or_b32_e32 v0, v0, v4
	v_or_b32_e32 v145, v13, v18
	v_or_b32_e32 v146, v17, v18
	v_add_u32_e32 v149, 0x2000, v148
	v_or_b32_e32 v151, 0x800, v150
	v_or_b32_e32 v152, 0x1000, v150
	v_or_b32_e32 v153, 0x1800, v150
	v_lshl_add_u64 v[138:139], s[12:13], 0, v[2:3]
	v_lshl_add_u64 v[140:141], s[12:13], 0, v[0:1]
	s_mov_b64 s[0:1], 0
	s_mov_b32 s2, 0
	s_and_b32 s99, s5, 3
	s_lshl_b32 s99, s99, 8
	v_lshrrev_b32_e32 v240, 4, v186
	v_xor_b32_e32 v240, v240, v186
	v_and_b32_e32 v240, 3, v240
	v_lshlrev_b32_e32 v240, 4, v240
	v_lshrrev_b32_e32 v241, 2, v186
	v_add_u32_e32 v241, s99, v241
	v_lshl_add_u32 v240, v241, 6, v240
	v_mov_b32_e32 v241, 0
	s_add_u32 s100, s86, 0x1cbe1000
	s_addc_u32 s101, s87, 0
	v_lshl_add_u64 v[130:131], s[100:101], 0, v[240:241]
	v_add_u32_e32 v240, 0x1000, v240
	v_lshl_add_u64 v[134:135], s[100:101], 0, v[240:241]
	v_add_u32_e32 v240, 0x1000, v240
	v_lshl_add_u64 v[138:139], s[100:101], 0, v[240:241]
	v_add_u32_e32 v240, 0x1000, v240
	v_lshl_add_u64 v[140:141], s[100:101], 0, v[240:241]
	s_mov_b64 s[100:101], 0
	v_mov_b32_e32 v0, 0
	v_mov_b32_e32 v1, v137
	v_mov_b32_e32 v2, v137
	v_mov_b32_e32 v3, v137
	v_mov_b32_e32 v4, v137
	v_mov_b32_e32 v5, v137
	v_mov_b32_e32 v6, v137
	v_mov_b32_e32 v7, v137
	v_mov_b32_e32 v8, v137
	v_mov_b32_e32 v9, v137
	v_mov_b32_e32 v10, v137
	v_mov_b32_e32 v11, v137
	v_mov_b32_e32 v12, v137
	v_mov_b32_e32 v13, v137
	v_mov_b32_e32 v14, v137
	v_mov_b32_e32 v15, v137
	v_mov_b32_e32 v48, 0
	v_mov_b32_e32 v49, v137
	v_mov_b32_e32 v50, v137
	v_mov_b32_e32 v51, v137
	v_mov_b32_e32 v52, v137
	v_mov_b32_e32 v53, v137
	v_mov_b32_e32 v54, v137
	v_mov_b32_e32 v55, v137
	v_mov_b32_e32 v56, v137
	v_mov_b32_e32 v57, v137
	v_mov_b32_e32 v58, v137
	v_mov_b32_e32 v59, v137
	v_mov_b32_e32 v60, v137
	v_mov_b32_e32 v61, v137
	v_mov_b32_e32 v62, v137
	v_mov_b32_e32 v63, v137
	v_mov_b32_e32 v16, 0
	v_mov_b32_e32 v17, v137
	v_mov_b32_e32 v18, v137
	v_mov_b32_e32 v19, v137
	v_mov_b32_e32 v20, v137
	v_mov_b32_e32 v21, v137
	v_mov_b32_e32 v22, v137
	v_mov_b32_e32 v23, v137
	v_mov_b32_e32 v24, v137
	v_mov_b32_e32 v25, v137
	v_mov_b32_e32 v26, v137
	v_mov_b32_e32 v27, v137
	v_mov_b32_e32 v28, v137
	v_mov_b32_e32 v29, v137
	v_mov_b32_e32 v30, v137
	v_mov_b32_e32 v31, v137
	v_mov_b32_e32 v64, 0
	v_mov_b32_e32 v65, v137
	v_mov_b32_e32 v66, v137
	v_mov_b32_e32 v67, v137
	v_mov_b32_e32 v68, v137
	v_mov_b32_e32 v69, v137
	v_mov_b32_e32 v70, v137
	v_mov_b32_e32 v71, v137
	v_mov_b32_e32 v72, v137
	v_mov_b32_e32 v73, v137
	v_mov_b32_e32 v74, v137
	v_mov_b32_e32 v75, v137
	v_mov_b32_e32 v76, v137
	v_mov_b32_e32 v77, v137
	v_mov_b32_e32 v78, v137
	v_mov_b32_e32 v79, v137
	v_mov_b32_e32 v32, 0
	v_mov_b32_e32 v33, v137
	v_mov_b32_e32 v34, v137
	v_mov_b32_e32 v35, v137
	v_mov_b32_e32 v36, v137
	v_mov_b32_e32 v37, v137
	v_mov_b32_e32 v38, v137
	v_mov_b32_e32 v39, v137
	v_mov_b32_e32 v40, v137
	v_mov_b32_e32 v41, v137
	v_mov_b32_e32 v42, v137
	v_mov_b32_e32 v43, v137
	v_mov_b32_e32 v44, v137
	v_mov_b32_e32 v45, v137
	v_mov_b32_e32 v46, v137
	v_mov_b32_e32 v47, v137
	s_waitcnt vmcnt(0)
; #define MFMA(a, b, c) __builtin_amdgcn_mfma_f32_32x32x16_bf16((a), (b), (c), 0, 0, 0)
; template <int K, typename Epi>
; DI void gemm_tile_wide(const u16* __restrict__ A, int lda, const u16* __restrict__ Bt, int ldb, int m0, int n0, char* smem, Epi epi) {
;     ...
;   for (int kt = 0; kt < NS; ++kt) {
;     asm volatile("s_waitcnt vmcnt(0)" ::: "memory");
;     __syncthreads();
;     const int cur = (kt & 1) * STB;
;     if (kt + 1 < NS) issue(kt + 1, STB - cur);
;     const char* Sg = smem + cur;
;     bf16x8 a[2][2], b[2][4];
; #pragma unroll
;     for (int kk = 0; kk < 2; ++kk) {
; #pragma unroll
;       for (int i = 0; i < 2; ++i) a[kk][i] = *(const bf16x8*)(Sg + aoff[i][kk]);
; #pragma unroll
;       for (int j = 0; j < 4; ++j) b[kk][j] = *(const bf16x8*)(Sg + boff[j][kk]);
;     }
;     __builtin_amdgcn_sched_barrier(0);
;     __builtin_amdgcn_s_setprio(1);
; #pragma unroll
;     for (int kk = 0; kk < 2; ++kk)
; #pragma unroll
;       for (int i = 0; i < 2; ++i)
; #pragma unroll
;         for (int j = 0; j < 4; ++j) acc[i][j] = MFMA(a[kk][i], b[kk][j], acc[i][j]);
;     __builtin_amdgcn_s_setprio(0);
;   }
	v_mov_b32_e32 v96, 0
	v_mov_b32_e32 v97, v137
	v_mov_b32_e32 v98, v137
	v_mov_b32_e32 v99, v137
	v_mov_b32_e32 v100, v137
	v_mov_b32_e32 v101, v137
	v_mov_b32_e32 v102, v137
	v_mov_b32_e32 v103, v137
	v_mov_b32_e32 v104, v137
	v_mov_b32_e32 v105, v137
	v_mov_b32_e32 v106, v137
	v_mov_b32_e32 v107, v137
	v_mov_b32_e32 v108, v137
	v_mov_b32_e32 v109, v137
	v_mov_b32_e32 v110, v137
	v_mov_b32_e32 v111, v137
	v_mov_b32_e32 v80, 0
	v_mov_b32_e32 v81, v137
	v_mov_b32_e32 v82, v137
	v_mov_b32_e32 v83, v137
	v_mov_b32_e32 v84, v137
	v_mov_b32_e32 v85, v137
	v_mov_b32_e32 v86, v137
	v_mov_b32_e32 v87, v137
	v_mov_b32_e32 v88, v137
	v_mov_b32_e32 v89, v137
	v_mov_b32_e32 v90, v137
	v_mov_b32_e32 v91, v137
	v_mov_b32_e32 v92, v137
	v_mov_b32_e32 v93, v137
	v_mov_b32_e32 v94, v137
	v_mov_b32_e32 v95, v137
	v_mov_b32_e32 v112, 0
	v_mov_b32_e32 v113, v137
	v_mov_b32_e32 v114, v137
	v_mov_b32_e32 v115, v137
	v_mov_b32_e32 v116, v137
	v_mov_b32_e32 v117, v137
	v_mov_b32_e32 v118, v137
	v_mov_b32_e32 v119, v137
	v_mov_b32_e32 v120, v137
	v_mov_b32_e32 v121, v137
	v_mov_b32_e32 v122, v137
	v_mov_b32_e32 v123, v137
	v_mov_b32_e32 v124, v137
	v_mov_b32_e32 v125, v137
	v_mov_b32_e32 v126, v137
	v_mov_b32_e32 v127, v137
.LBB0_643:
	s_bitcmp1_b32 s2, 0
	s_cselect_b32 s3, 0x6000, 0
	v_subrev_u32_e32 v166, s3, v147
	v_add_u32_e32 v167, 0x6000, v166
	v_add_u32_e32 v168, 0x8000, v166
	v_readfirstlane_b32 s28, v167
	v_lshl_add_u64 v[154:155], v[128:129], 0, s[0:1]
	v_add_u32_e32 v169, 0x7000, v166
	v_readfirstlane_b32 s29, v168
	s_mov_b32 m0, s28
	s_waitcnt vmcnt(0)
	s_waitcnt lgkmcnt(0)
	s_barrier
	v_lshl_add_u64 v[156:157], v[130:131], 0, s[100:101]
	v_add_u32_e32 v170, 0x9000, v166
	v_readfirstlane_b32 s30, v169
	global_load_lds_dwordx4 v[154:155], off
	s_mov_b32 m0, s29
	v_lshl_add_u64 v[158:159], v[132:133], 0, s[0:1]
	v_add_u32_e32 v171, 0xa000, v166
	v_readfirstlane_b32 s31, v170
	global_load_lds_dwordx4 v[156:157], off
	s_mov_b32 m0, s30
	v_lshl_add_u64 v[160:161], v[134:135], 0, s[100:101]
	v_add_u32_e32 v166, 0xb000, v166
	v_readfirstlane_b32 s33, v171
	global_load_lds_dwordx4 v[158:159], off
	s_mov_b32 m0, s31
	v_lshl_add_u64 v[162:163], v[138:139], 0, s[100:101]
	v_readfirstlane_b32 s34, v166
	global_load_lds_dwordx4 v[160:161], off
	s_mov_b32 m0, s33
	v_lshl_add_u64 v[164:165], v[140:141], 0, s[100:101]
	global_load_lds_dwordx4 v[162:163], off
	s_mov_b32 m0, s34
	v_add_u32_e32 v158, s3, v145
	global_load_lds_dwordx4 v[164:165], off
	v_add_u32_e32 v162, s3, v148
	v_add_u32_e32 v174, s3, v149
	v_add_u32_e32 v182, s3, v146
	v_add_u32_e32 v188, s3, v150
	v_add_u32_e32 v192, s3, v151
	v_add_u32_e32 v196, s3, v152
	v_add_u32_e32 v200, s3, v153
	ds_read_b128 v[154:157], v158
	ds_read_b128 v[158:161], v158 offset:2048
	ds_read_b128 v[162:165], v162 offset:8192
	ds_read_b128 v[166:169], v174 offset:2048
	ds_read_b128 v[170:173], v174 offset:4096
	ds_read_b128 v[174:177], v174 offset:6144
	ds_read_b128 v[178:181], v182
	ds_read_b128 v[182:185], v182 offset:2048
	ds_read_b128 v[188:191], v188 offset:8192
	ds_read_b128 v[192:195], v192 offset:8192
	ds_read_b128 v[196:199], v196 offset:8192
	ds_read_b128 v[200:203], v200 offset:8192
	s_add_i32 s2, s2, 1
	s_setprio 1
	s_waitcnt lgkmcnt(0)
	v_mfma_f32_32x32x16_bf16 v[0:15], v[154:157], v[162:165], v[0:15]
	v_mfma_f32_32x32x16_bf16 v[48:63], v[154:157], v[166:169], v[48:63]
	v_mfma_f32_32x32x16_bf16 v[16:31], v[154:157], v[170:173], v[16:31]
	v_mfma_f32_32x32x16_bf16 v[64:79], v[154:157], v[174:177], v[64:79]
	v_mfma_f32_32x32x16_bf16 v[32:47], v[158:161], v[162:165], v[32:47]
	v_mfma_f32_32x32x16_bf16 v[96:111], v[158:161], v[166:169], v[96:111]
	v_mfma_f32_32x32x16_bf16 v[80:95], v[158:161], v[170:173], v[80:95]
	v_mfma_f32_32x32x16_bf16 v[112:127], v[158:161], v[174:177], v[112:127]
	v_mfma_f32_32x32x16_bf16 v[0:15], v[178:181], v[188:191], v[0:15]
	v_mfma_f32_32x32x16_bf16 v[48:63], v[178:181], v[192:195], v[48:63]
	v_mfma_f32_32x32x16_bf16 v[16:31], v[178:181], v[196:199], v[16:31]
	v_mfma_f32_32x32x16_bf16 v[64:79], v[178:181], v[200:203], v[64:79]
	v_mfma_f32_32x32x16_bf16 v[32:47], v[182:185], v[188:191], v[32:47]
	v_mfma_f32_32x32x16_bf16 v[96:111], v[182:185], v[192:195], v[96:111]
	v_mfma_f32_32x32x16_bf16 v[80:95], v[182:185], v[196:199], v[80:95]
	v_mfma_f32_32x32x16_bf16 v[112:127], v[182:185], v[200:203], v[112:127]
	s_setprio 0
	s_add_u32 s0, s0, 64
	s_addc_u32 s1, s1, 0
	s_add_u32 s100, s100, 0x10000
	s_addc_u32 s101, s101, 0
	s_cmpk_eq_i32 s0, 0x7c0
	s_cbranch_scc0 .LBB0_643
	s_waitcnt vmcnt(0)
	s_waitcnt vmcnt(0)
	s_barrier
; #define MFMA(a, b, c) __builtin_amdgcn_mfma_f32_32x32x16_bf16((a), (b), (c), 0, 0, 0)
; DI int crow(int reg, int h) { return (reg & 3) + 8 * (reg >> 2) + 4 * h; }
; template <int K, typename Epi>
; DI void gemm_tile_wide(const u16* __restrict__ A, int lda, const u16* __restrict__ Bt, int ldb, int m0, int n0, char* smem, Epi epi) {
;     ...
;     bf16x8 a[2][2], b[2][4];
; #pragma unroll
;     for (int kk = 0; kk < 2; ++kk) {
; #pragma unroll
;       for (int i = 0; i < 2; ++i) a[kk][i] = *(const bf16x8*)(Sg + aoff[i][kk]);
; #pragma unroll
;       for (int j = 0; j < 4; ++j) b[kk][j] = *(const bf16x8*)(Sg + boff[j][kk]);
;     }
;     __builtin_amdgcn_sched_barrier(0);
;     __builtin_amdgcn_s_setprio(1);
; #pragma unroll
;     for (int kk = 0; kk < 2; ++kk)
; #pragma unroll
;       for (int i = 0; i < 2; ++i)
; #pragma unroll
;         for (int j = 0; j < 4; ++j) acc[i][j] = MFMA(a[kk][i], b[kk][j], acc[i][j]);
;     __builtin_amdgcn_s_setprio(0);
;   }
;   float* Cs = (float*)smem;
; #pragma unroll
;   for (int half = 0; half < 2; ++half) {
;     __syncthreads();
;     if (wn == half) {
; #pragma unroll
;       for (int i = 0; i < 2; ++i)
; #pragma unroll
;         for (int j = 0; j < 4; ++j)
; #pragma unroll
;           for (int e = 0; e < 16; ++e) Cs[(wm * 64 + i * 32 + crow(e, h)) * CS_LD + j * 32 + r] = acc[i][j][e];
;     }
	ds_read_b128 v[128:131], v153 offset:32768
	ds_read_b128 v[132:135], v152 offset:32768
	ds_read_b128 v[138:141], v151 offset:32768
	ds_read_b128 v[150:153], v150 offset:32768
	ds_read_b128 v[154:157], v146 offset:26624
	ds_read_b128 v[158:161], v146 offset:24576
	ds_read_b128 v[162:165], v149 offset:30720
	ds_read_b128 v[166:169], v149 offset:28672
	ds_read_b128 v[170:173], v149 offset:26624
	ds_read_b128 v[146:149], v148 offset:32768
	ds_read_b128 v[174:177], v145 offset:26624
	ds_read_b128 v[178:181], v145 offset:24576
	s_setprio 1
	s_waitcnt lgkmcnt(0)
	v_mfma_f32_32x32x16_bf16 v[0:15], v[178:181], v[146:149], v[0:15]
	v_mfma_f32_32x32x16_bf16 v[48:63], v[178:181], v[170:173], v[48:63]
	v_mfma_f32_32x32x16_bf16 v[16:31], v[178:181], v[166:169], v[16:31]
	v_mfma_f32_32x32x16_bf16 v[64:79], v[178:181], v[162:165], v[64:79]
	v_mfma_f32_32x32x16_bf16 v[32:47], v[174:177], v[146:149], v[32:47]
	v_mfma_f32_32x32x16_bf16 v[96:111], v[174:177], v[170:173], v[96:111]
	v_mfma_f32_32x32x16_bf16 v[80:95], v[174:177], v[166:169], v[80:95]
	v_mfma_f32_32x32x16_bf16 v[112:127], v[174:177], v[162:165], v[112:127]
	v_mfma_f32_32x32x16_bf16 v[0:15], v[158:161], v[150:153], v[0:15]
	v_mfma_f32_32x32x16_bf16 v[48:63], v[158:161], v[138:141], v[48:63]
	v_mfma_f32_32x32x16_bf16 v[16:31], v[158:161], v[132:135], v[16:31]
	v_mfma_f32_32x32x16_bf16 v[64:79], v[158:161], v[128:131], v[64:79]
	v_mfma_f32_32x32x16_bf16 v[32:47], v[154:157], v[150:153], v[32:47]
	v_mfma_f32_32x32x16_bf16 v[96:111], v[154:157], v[138:141], v[96:111]
	v_mfma_f32_32x32x16_bf16 v[80:95], v[154:157], v[132:135], v[80:95]
	v_mfma_f32_32x32x16_bf16 v[112:127], v[154:157], v[128:131], v[112:127]
	s_setprio 0
	v_lshlrev_b32_e32 v128, 6, v142
	v_lshl_or_b32 v139, v143, 2, v128
	v_lshlrev_b32_e32 v138, 2, v144
	v_cmp_ne_u32_e32 vcc, 0, v136
	v_cmp_eq_u32_e64 s[0:1], 0, v136
	s_barrier
	s_and_saveexec_b64 s[2:3], s[0:1]
	s_cbranch_execz .LBB0_646
	v_mad_u64_u32 v[128:129], s[0:1], v139, s24, v[138:139]
	v_add_u32_e32 v129, 0x400, v128
	v_add_u32_e32 v130, 0x1000, v128
	v_add_u32_e32 v131, 0x1400, v128
	v_add_u32_e32 v132, 0x2000, v128
	v_add_u32_e32 v133, 0x2400, v128
	v_add_u32_e32 v135, 0x3200, v128
	ds_write2_b32 v128, v0, v48 offset1:32
	ds_write2_b32 v128, v1, v49 offset0:132 offset1:164
	ds_write2_b32 v129, v2, v50 offset0:8 offset1:40
	ds_write2_b32 v129, v3, v51 offset0:140 offset1:172
	ds_write2_b32 v130, v4, v52 offset0:32 offset1:64
	ds_write2_b32 v130, v5, v53 offset0:164 offset1:196
	ds_write2_b32 v131, v6, v54 offset0:40 offset1:72
	ds_write2_b32 v131, v7, v55 offset0:172 offset1:204
	ds_write2_b32 v132, v8, v56 offset0:64 offset1:96
	ds_write2_b32 v132, v9, v57 offset0:196 offset1:228
	ds_write2_b32 v133, v10, v58 offset0:72 offset1:104
	ds_write2_b32 v133, v11, v59 offset0:204 offset1:236
	v_add_u32_e32 v134, 0x3000, v128
	ds_write2_b32 v135, v13, v61 offset0:100 offset1:132
	v_add_u32_e32 v135, 0x3400, v128
	v_add_u32_e32 v136, 0x3600, v128
	ds_write2_b32 v134, v12, v60 offset0:96 offset1:128
	ds_write2_b32 v135, v14, v62 offset0:104 offset1:136
	ds_write2_b32 v136, v15, v63 offset0:108 offset1:140
	ds_write2_b32 v128, v16, v64 offset0:64 offset1:96
	ds_write2_b32 v128, v17, v65 offset0:196 offset1:228
	ds_write2_b32 v129, v18, v66 offset0:72 offset1:104
	ds_write2_b32 v129, v19, v67 offset0:204 offset1:236
	ds_write2_b32 v130, v20, v68 offset0:96 offset1:128
	v_add_u32_e32 v129, 0x1200, v128
	ds_write2_b32 v129, v21, v69 offset0:100 offset1:132
	ds_write2_b32 v131, v22, v70 offset0:104 offset1:136
	v_add_u32_e32 v129, 0x1600, v128
	ds_write2_b32 v129, v23, v71 offset0:108 offset1:140
	ds_write2_b32 v132, v24, v72 offset0:128 offset1:160
	ds_write2_b32 v133, v25, v73 offset0:4 offset1:36
	ds_write2_b32 v133, v26, v74 offset0:136 offset1:168
	v_add_u32_e32 v129, 0x2800, v128
	ds_write2_b32 v129, v27, v75 offset0:12 offset1:44
	ds_write2_b32 v134, v28, v76 offset0:160 offset1:192
	ds_write2_b32 v135, v29, v77 offset0:36 offset1:68
	ds_write2_b32 v135, v30, v78 offset0:168 offset1:200
	v_add_u32_e32 v129, 0x3800, v128
	ds_write2_b32 v129, v31, v79 offset0:44 offset1:76
	v_add_u32_e32 v129, 0x4000, v128
	v_add_u32_e32 v130, 0x4400, v128
	v_add_u32_e32 v132, 0x5000, v128
	ds_write2_b32 v129, v32, v96 offset0:128 offset1:160
	ds_write2_b32 v130, v33, v97 offset0:4 offset1:36
	ds_write2_b32 v130, v34, v98 offset0:136 offset1:168
	v_add_u32_e32 v131, 0x4800, v128
	ds_write2_b32 v132, v36, v100 offset0:160 offset1:192
	v_add_u32_e32 v132, 0x5400, v128
	v_add_u32_e32 v134, 0x6000, v128
	ds_write2_b32 v131, v35, v99 offset0:12 offset1:44
	ds_write2_b32 v132, v37, v101 offset0:36 offset1:68
	ds_write2_b32 v132, v38, v102 offset0:168 offset1:200
	v_add_u32_e32 v133, 0x5800, v128
	ds_write2_b32 v134, v40, v104 offset0:192 offset1:224
	v_add_u32_e32 v134, 0x6400, v128
	v_add_u32_e32 v136, 0x7200, v128
	v_add_u32_e32 v140, 0x7600, v128
	ds_write2_b32 v133, v39, v103 offset0:44 offset1:76
	ds_write2_b32 v134, v41, v105 offset0:68 offset1:100
	ds_write2_b32 v134, v42, v106 offset0:200 offset1:232
	v_add_u32_e32 v135, 0x6800, v128
	ds_write2_b32 v136, v44, v108 offset0:96 offset1:128
	v_add_u32_e32 v136, 0x7400, v128
	ds_write2_b32 v140, v46, v110 offset0:104 offset1:136
	v_add_u32_e32 v140, 0x7800, v128
	ds_write2_b32 v135, v43, v107 offset0:76 offset1:108
	ds_write2_b32 v136, v45, v109 offset0:100 offset1:132
	ds_write2_b32 v140, v47, v111 offset0:108 offset1:140
	ds_write2_b32 v129, v80, v112 offset0:192 offset1:224
	ds_write2_b32 v130, v81, v113 offset0:68 offset1:100
	ds_write2_b32 v130, v82, v114 offset0:200 offset1:232
	ds_write2_b32 v131, v83, v115 offset0:76 offset1:108
	v_add_u32_e32 v129, 0x5200, v128
	v_add_u32_e32 v128, 0x5600, v128
	ds_write2_b32 v129, v84, v116 offset0:96 offset1:128
	ds_write2_b32 v132, v85, v117 offset0:100 offset1:132
	ds_write2_b32 v128, v86, v118 offset0:104 offset1:136
	ds_write2_b32 v133, v87, v119 offset0:108 offset1:140
	ds_write2_b32 v134, v88, v120 offset1:32
	ds_write2_b32 v134, v89, v121 offset0:132 offset1:164
	ds_write2_b32 v135, v90, v122 offset0:8 offset1:40
	ds_write2_b32 v135, v91, v123 offset0:140 offset1:172
	ds_write2_b32 v136, v92, v124 offset0:32 offset1:64
	ds_write2_b32 v136, v93, v125 offset0:164 offset1:196
	ds_write2_b32 v140, v94, v126 offset0:40 offset1:72
	ds_write2_b32 v140, v95, v127 offset0:172 offset1:204

;   DI u16* y0b() const { return (u16*)(ws + WS_y0b); }
; DI float bflo(unsigned v) { return __uint_as_float(v << 16); }
; DI float bfhi(unsigned v) { return __uint_as_float(v & 0xffff0000u); }
; DI void st_bf4(u16* d, float a, float b, float c, float e) { *(uint2*)d = pack4(a, b, c, e); }
; DI float half_sum(float v) {
;   v += __shfl_xor(v, 16); v += __shfl_xor(v, 8); v += __shfl_xor(v, 4); v += __shfl_xor(v, 2); v += __shfl_xor(v, 1);
;   return v;
; }
; DI float wave_sum(float v) { v = half_sum(v); v += __shfl_xor(v, 32); return v; }
; DI void phase_ln(const Params& p, int layer) {
;     ...
;     float sum = 0.f;
; #pragma unroll
;     for (int i = 0; i < 4; ++i) {
;       typedef __attribute__((ext_vector_type(2))) unsigned u32x2_t;
;       const u32x2_t qq = __builtin_nontemporal_load((const u32x2_t*)(s + lane * 4 + 256 * i));
;       const uint2 q = make_uint2(qq[0], qq[1]);
;       v[i] = make_float4(bflo(q.x), bfhi(q.x), bflo(q.y), bfhi(q.y));
;       sum += v[i].x + v[i].y + v[i].z + v[i].w;
;     }
;     const float mu = wave_sum(sum) * (1.f / 1024.f);
;     float sq = 0.f;
; #pragma unroll
;     for (int i = 0; i < 4; ++i) { v[i].x -= mu; v[i].y -= mu; v[i].z -= mu; v[i].w -= mu; sq += v[i].x * v[i].x + v[i].y * v[i].y + v[i].z * v[i].z + v[i].w * v[i].w; }
;     const float rstd = rsqrtf(wave_sum(sq) * (1.f / 1024.f) + EPS);
; #pragma unroll
;     for (int i = 0; i < 4; ++i) {
;       const int c = lane * 4 + 256 * i;
;       float4 gg = *(const float4*)(g + c), b4 = *(const float4*)(bb + c);
;       float4 y = make_float4(v[i].x * rstd * gg.x + b4.x, v[i].y * rstd * gg.y + b4.y, v[i].z * rstd * gg.z + b4.z, v[i].w * rstd * gg.w + b4.w);
;       if (layer == 0) {
;         st_bf4(p.y0b() + (size_t)row * 1024 + c, y.x, y.y, y.z, y.w);
.Lln0_nopf:
	v_add_f32_e32 v48, v32, v33
	v_add_f32_e32 v49, v34, v35
	v_add_f32_e32 v50, v36, v37
	v_add_f32_e32 v51, v38, v39
	v_add_f32_e32 v52, v40, v41
	v_add_f32_e32 v53, v42, v43
	v_add_f32_e32 v54, v44, v45
	v_add_f32_e32 v55, v46, v47
	v_add_f32_e32 v48, v48, v49
	v_add_f32_e32 v49, v50, v51
	v_add_f32_e32 v50, v52, v53
	v_add_f32_e32 v51, v54, v55
	v_add_f32_e32 v48, v48, v49
	v_add_f32_e32 v50, v50, v51
	v_add_f32_e32 v48, v48, v50
	s_nop 1
	v_add_f32_dpp v48, v48, v48 row_ror:8 row_mask:0xf bank_mask:0xf
	s_nop 1
	v_add_f32_dpp v48, v48, v48 row_ror:4 row_mask:0xf bank_mask:0xf
	s_nop 1
	v_add_f32_dpp v48, v48, v48 row_ror:2 row_mask:0xf bank_mask:0xf
	s_nop 1
	v_add_f32_dpp v48, v48, v48 row_ror:1 row_mask:0xf bank_mask:0xf
	s_nop 0
	v_readlane_b32 s20, v48, 0
	v_readlane_b32 s21, v48, 16
	v_readlane_b32 s22, v48, 32
	v_readlane_b32 s23, v48, 48
	s_nop 1
	v_mov_b32_e32 v48, s20
	v_add_f32_e32 v48, s21, v48
	v_add_f32_e32 v48, s22, v48
	v_add_f32_e32 v48, s23, v48
	v_mul_f32_e32 v49, 0x3a800000, v48
	v_sub_f32_e32 v32, v32, v49
	v_sub_f32_e32 v33, v33, v49
	v_sub_f32_e32 v34, v34, v49
	v_sub_f32_e32 v35, v35, v49
	v_sub_f32_e32 v36, v36, v49
	v_sub_f32_e32 v37, v37, v49
	v_sub_f32_e32 v38, v38, v49
	v_sub_f32_e32 v39, v39, v49
	v_sub_f32_e32 v40, v40, v49
	v_sub_f32_e32 v41, v41, v49
	v_sub_f32_e32 v42, v42, v49
	v_sub_f32_e32 v43, v43, v49
	v_sub_f32_e32 v44, v44, v49
	v_sub_f32_e32 v45, v45, v49
	v_sub_f32_e32 v46, v46, v49
	v_sub_f32_e32 v47, v47, v49
	v_mul_f32_e32 v50, v32, v32
	v_mul_f32_e32 v51, v33, v33
	v_fmac_f32_e32 v50, v34, v34
	v_fmac_f32_e32 v51, v35, v35
	v_fmac_f32_e32 v50, v36, v36
	v_fmac_f32_e32 v51, v37, v37
	v_fmac_f32_e32 v50, v38, v38
	v_fmac_f32_e32 v51, v39, v39
	v_fmac_f32_e32 v50, v40, v40
	v_fmac_f32_e32 v51, v41, v41
	v_fmac_f32_e32 v50, v42, v42
	v_fmac_f32_e32 v51, v43, v43
	v_fmac_f32_e32 v50, v44, v44
	v_fmac_f32_e32 v51, v45, v45
	v_fmac_f32_e32 v50, v46, v46
	v_fmac_f32_e32 v51, v47, v47
	v_add_f32_e32 v50, v50, v51
	s_nop 1
	v_add_f32_dpp v50, v50, v50 row_ror:8 row_mask:0xf bank_mask:0xf
	s_nop 1
	v_add_f32_dpp v50, v50, v50 row_ror:4 row_mask:0xf bank_mask:0xf
	s_nop 1
	v_add_f32_dpp v50, v50, v50 row_ror:2 row_mask:0xf bank_mask:0xf
	s_nop 1
	v_add_f32_dpp v50, v50, v50 row_ror:1 row_mask:0xf bank_mask:0xf
	s_nop 0
	v_readlane_b32 s20, v50, 0
	v_readlane_b32 s21, v50, 16
	v_readlane_b32 s22, v50, 32
	v_readlane_b32 s23, v50, 48
	s_nop 1
	v_mov_b32_e32 v50, s20
	v_add_f32_e32 v50, s21, v50
	v_add_f32_e32 v50, s22, v50
	v_add_f32_e32 v50, s23, v50
	v_fmamk_f32 v50, v50, 0x3a800000, v18
	v_rsq_f32_e32 v50, v50
	s_nop 0
	v_mul_f32_e32 v32, v32, v50
	v_mul_f32_e32 v33, v33, v50
	v_mul_f32_e32 v34, v34, v50
	v_mul_f32_e32 v35, v35, v50
	v_mul_f32_e32 v36, v36, v50
	v_mul_f32_e32 v37, v37, v50
	v_mul_f32_e32 v38, v38, v50
	v_mul_f32_e32 v39, v39, v50
	v_mul_f32_e32 v40, v40, v50
	v_mul_f32_e32 v41, v41, v50
	v_mul_f32_e32 v42, v42, v50
	v_mul_f32_e32 v43, v43, v50
	v_mul_f32_e32 v44, v44, v50
	v_mul_f32_e32 v45, v45, v50
	v_mul_f32_e32 v46, v46, v50
	v_mul_f32_e32 v47, v47, v50
	v_fma_f32 v96, v32, v64, v80
	v_fma_f32 v97, v33, v65, v81
	v_fma_f32 v98, v34, v66, v82
	v_fma_f32 v99, v35, v67, v83
	v_fma_f32 v100, v36, v68, v84
	v_fma_f32 v101, v37, v69, v85
	v_fma_f32 v102, v38, v70, v86
	v_fma_f32 v103, v39, v71, v87
	v_fma_f32 v104, v40, v72, v88
	v_fma_f32 v105, v41, v73, v89
	v_fma_f32 v106, v42, v74, v90
	v_fma_f32 v107, v43, v75, v91
	v_fma_f32 v108, v44, v76, v92
	v_fma_f32 v109, v45, v77, v93
	v_fma_f32 v110, v46, v78, v94
	v_fma_f32 v111, v47, v79, v95
	v_cvt_pk_bf16_f32 v112, v96, v97
	v_cvt_pk_bf16_f32 v113, v98, v99
	v_cvt_pk_bf16_f32 v114, v100, v101
	v_cvt_pk_bf16_f32 v115, v102, v103
	v_cvt_pk_bf16_f32 v116, v104, v105
	v_cvt_pk_bf16_f32 v117, v106, v107
	v_cvt_pk_bf16_f32 v118, v108, v109
	v_cvt_pk_bf16_f32 v119, v110, v111
	global_store_dwordx2 v1, v[112:113], s[6:7]
	global_store_dwordx2 v1, v[114:115], s[6:7] offset:512
	global_store_dwordx2 v1, v[116:117], s[6:7] offset:1024
	global_store_dwordx2 v1, v[118:119], s[6:7] offset:1536
	s_cmp_lg_u32 s9, 0
	s_cbranch_scc1 .Lln0_loop

; template <int K, typename Epi>
; DI void gemm_tile_wide(const u16* __restrict__ A, int lda, const u16* __restrict__ Bt, int ldb, int m0, int n0, char* smem, Epi epi) {
;     ...
;   f32x16 acc[2][4];
; #pragma unroll
;   for (int i = 0; i < 2; ++i)
; #pragma unroll
;     for (int j = 0; j < 4; ++j)
; #pragma unroll
;       for (int e = 0; e < 16; ++e) acc[i][j][e] = 0.f;
;   constexpr int NS = K / 32;
;   constexpr int AB = 128 * 64;
;   constexpr int STB = AB + 256 * 64;
;   const int lrow = tid >> 2, cpos = tid & 3;
;   const u16* ap[2]; const u16* bp[4];
; #pragma unroll
;   for (int i = 0; i < 4; ++i) {
;     const int row = lrow + 64 * i;
;     const int sc = cpos ^ ((row >> 2) & 3);
;     if (i < 2) ap[i] = A + (size_t)(m0 + row) * lda + sc * 8;
;     bp[i] = Bt + (size_t)(n0 + row) * ldb + sc * 8;
;   }
;   char* const ldst = smem + tid * 16;
;   int aoff[2][2], boff[4][2];
; #pragma unroll
;   for (int kk = 0; kk < 2; ++kk) {
; #pragma unroll
;     for (int i = 0; i < 2; ++i) { const int ra_ = wm * 64 + i * 32 + r; aoff[i][kk] = ra_ * 64 + (((2 * kk + h) ^ ((ra_ >> 2) & 3)) << 4); }
; #pragma unroll
;     for (int j = 0; j < 4; ++j) { const int rb_ = wn * 128 + j * 32 + r; boff[j][kk] = AB + rb_ * 64 + (((2 * kk + h) ^ ((rb_ >> 2) & 3)) << 4); }
;   }
;   auto issue = [&](int slice, int st) {
; #pragma unroll
;     for (int i = 0; i < 4; ++i) {
;       if (i < 2) __builtin_amdgcn_global_load_lds((const unsigned*)(ap[i] + slice * 32), (unsigned*)(ldst + st + i * 4096), 16, 0, 0);
;       __builtin_amdgcn_global_load_lds((const unsigned*)(bp[i] + slice * 32), (unsigned*)(ldst + st + AB + i * 4096), 16, 0, 0);
;     }
;   };
;   __syncthreads();
;   issue(0, 0);
.LBB0_926:
	v_mov_b32_e32 v12, v186
	s_lshl_b32 s2, s34, 3
	s_and_b32 s55, s2, 0xffffff80
	v_lshrrev_b32_e32 v15, 4, v12
	v_ashrrev_i32_e32 v14, 2, v12
	s_waitcnt lgkmcnt(0)
	v_xor_b32_e32 v0, v15, v12
	v_lshlrev_b32_e32 v0, 4, v0
	v_add_u32_e32 v4, s55, v14
	s_and_b32 s4, s34, 15
	v_and_b32_e32 v132, 48, v0
	v_ashrrev_i32_e32 v5, 31, v4
	v_lshlrev_b32_e32 v147, 4, v12
	s_lshl_b32 s2, s4, 8
	v_lshl_add_u64 v[2:3], s[10:11], 0, v[132:133]
	v_lshlrev_b64 v[4:5], 11, v[4:5]
	v_readfirstlane_b32 s3, v147
	v_lshl_add_u64 v[4:5], v[2:3], 0, v[4:5]
	v_add_u32_e32 v6, s2, v14
	v_add_u32_e32 v16, 64, v14
	s_mov_b32 m0, s3
	v_ashrrev_i32_e32 v7, 31, v6
	v_add_u32_e32 v8, s55, v16
	s_barrier
	global_load_lds_dwordx4 v[4:5], off
	v_add_u32_e32 v4, 0x2000, v147
	v_lshl_add_u64 v[0:1], s[12:13], 0, v[132:133]
	v_lshlrev_b64 v[6:7], 11, v[6:7]
	v_ashrrev_i32_e32 v9, 31, v8
	v_readfirstlane_b32 s3, v4
	v_add_u32_e32 v4, 0x1000, v147
	v_lshl_add_u64 v[6:7], v[0:1], 0, v[6:7]
	v_lshlrev_b64 v[8:9], 11, v[8:9]
	s_mov_b32 m0, s3
	v_readfirstlane_b32 s3, v4
	v_lshl_add_u64 v[2:3], v[2:3], 0, v[8:9]
	v_add_u32_e32 v8, s2, v16
	global_load_lds_dwordx4 v[6:7], off
	s_mov_b32 m0, s3
	v_ashrrev_i32_e32 v9, 31, v8
	global_load_lds_dwordx4 v[2:3], off
	v_add_u32_e32 v2, 0x3000, v147
	v_lshlrev_b64 v[8:9], 11, v[8:9]
	v_readfirstlane_b32 s3, v2
	v_lshl_add_u64 v[0:1], v[0:1], 0, v[8:9]
	s_mov_b32 m0, s3
	v_lshl_add_u64 v[8:9], v[6:7], 0, s[42:43]
	global_load_lds_dwordx4 v[0:1], off
	v_add_u32_e32 v0, 0x4000, v147
	v_lshl_add_u64 v[10:11], v[6:7], 0, s[44:45]
	v_readfirstlane_b32 s3, v0
	v_add_u32_e32 v0, 0x5000, v147
	s_mov_b32 m0, s3
	v_readfirstlane_b32 s3, v0
	global_load_lds_dwordx4 v[8:9], off
	s_mov_b32 m0, s3
	s_and_b32 s0, s47, 0xffffff80
	global_load_lds_dwordx4 v[10:11], off
	v_add_u32_e32 v0, s0, v14
	v_ashrrev_i32_e32 v1, 31, v0
	v_bitop3_b32 v2, v15, 3, v12 bitop3:0x48
	s_and_b32 s1, s53, 15
	v_lshlrev_b64 v[0:1], 11, v[0:1]
	v_lshlrev_b32_e32 v4, 4, v2
	s_lshl_b32 s1, s1, 8
	v_or_b32_e32 v0, v0, v4
	v_lshl_add_u64 v[128:129], s[36:37], 0, v[0:1]
	v_add_u32_e32 v0, s1, v14
	v_ashrrev_i32_e32 v1, 31, v0
	v_lshlrev_b64 v[2:3], 11, v[0:1]
	v_or_b32_e32 v2, v2, v4
	v_lshl_add_u64 v[130:131], s[40:41], 0, v[2:3]
	v_add_u32_e32 v2, s0, v16
	v_ashrrev_i32_e32 v3, 31, v2
	v_lshlrev_b64 v[2:3], 11, v[2:3]
	v_or_b32_e32 v2, v2, v4
	v_lshl_add_u64 v[134:135], s[36:37], 0, v[2:3]
	v_add_u32_e32 v2, s1, v16
	v_ashrrev_i32_e32 v3, 31, v2
	v_lshlrev_b64 v[2:3], 11, v[2:3]
	v_or_b32_e32 v2, v2, v4
	v_lshrrev_b32_e32 v13, 5, v12
	v_bfe_u32 v143, v12, 5, 1
	v_and_b32_e32 v144, 31, v12
	v_bfe_u32 v17, v12, 2, 2
	v_lshl_add_u64 v[136:137], s[40:41], 0, v[2:3]
	v_add_u32_e32 v2, 0x80, v0
	v_add_u32_e32 v0, 0xc0, v0
	v_bfe_u32 v132, v12, 6, 1
	v_lshlrev_b32_e32 v18, 6, v144
	v_bitop3_b32 v13, v13, v17, 1 bitop3:0x6c
	v_bitop3_b32 v17, v143, v17, 2 bitop3:0x36
	v_ashrrev_i32_e32 v3, 31, v2
	v_ashrrev_i32_e32 v1, 31, v0
	v_ashrrev_i32_e32 v142, 7, v12
	v_lshl_or_b32 v19, v132, 13, v18
	v_lshlrev_b32_e32 v13, 4, v13
	v_lshlrev_b32_e32 v17, 4, v17
	v_lshlrev_b64 v[2:3], 11, v[2:3]
	v_lshlrev_b64 v[0:1], 11, v[0:1]
	v_lshl_or_b32 v18, v142, 12, v18
	v_or_b32_e32 v148, v19, v13
	v_or_b32_e32 v150, v17, v19
	v_or_b32_e32 v2, v2, v4
	v_or_b32_e32 v0, v0, v4
	v_or_b32_e32 v145, v13, v18
	v_or_b32_e32 v146, v17, v18
	v_add_u32_e32 v149, 0x2000, v148
	v_or_b32_e32 v151, 0x800, v150
	v_or_b32_e32 v152, 0x1000, v150
	v_or_b32_e32 v153, 0x1800, v150
	v_lshl_add_u64 v[138:139], s[40:41], 0, v[2:3]
	v_lshl_add_u64 v[140:141], s[40:41], 0, v[0:1]
	s_mov_b64 s[0:1], 0
	s_mov_b32 s3, 0
	s_and_b32 s99, s34, 15
	s_lshl_b32 s99, s99, 8
	v_lshrrev_b32_e32 v240, 4, v186
	v_xor_b32_e32 v240, v240, v186
	v_and_b32_e32 v240, 3, v240
	v_lshlrev_b32_e32 v240, 4, v240
	v_lshrrev_b32_e32 v241, 2, v186
	v_add_u32_e32 v241, s99, v241
	v_lshl_add_u32 v240, v241, 6, v240
	v_mov_b32_e32 v241, 0
	s_add_u32 s100, s86, 0x1ce11000
	s_addc_u32 s101, s87, 0
	v_lshl_add_u64 v[130:131], s[100:101], 0, v[240:241]
	v_add_u32_e32 v240, 0x1000, v240
	v_lshl_add_u64 v[136:137], s[100:101], 0, v[240:241]
	v_add_u32_e32 v240, 0x1000, v240
	v_lshl_add_u64 v[138:139], s[100:101], 0, v[240:241]
	v_add_u32_e32 v240, 0x1000, v240
	v_lshl_add_u64 v[140:141], s[100:101], 0, v[240:241]
	s_mov_b64 s[100:101], 0
	v_mov_b32_e32 v0, v133
	v_mov_b32_e32 v1, v133
	v_mov_b32_e32 v2, v133
	v_mov_b32_e32 v3, v133
	v_mov_b32_e32 v4, v133
	v_mov_b32_e32 v5, v133
	v_mov_b32_e32 v6, v133
	v_mov_b32_e32 v7, v133
	v_mov_b32_e32 v8, v133
	v_mov_b32_e32 v9, v133
	v_mov_b32_e32 v10, v133
	v_mov_b32_e32 v11, v133
	v_mov_b32_e32 v12, v133
	v_mov_b32_e32 v13, v133
	v_mov_b32_e32 v14, v133
	v_mov_b32_e32 v15, v133
	v_mov_b32_e32 v48, v133
	v_mov_b32_e32 v49, v133
	v_mov_b32_e32 v50, v133
	v_mov_b32_e32 v51, v133
	v_mov_b32_e32 v52, v133
	v_mov_b32_e32 v53, v133
	v_mov_b32_e32 v54, v133
	v_mov_b32_e32 v55, v133
	v_mov_b32_e32 v56, v133
	v_mov_b32_e32 v57, v133
	v_mov_b32_e32 v58, v133
	v_mov_b32_e32 v59, v133
	v_mov_b32_e32 v60, v133
	v_mov_b32_e32 v61, v133
	v_mov_b32_e32 v62, v133
	v_mov_b32_e32 v63, v133
	v_mov_b32_e32 v16, v133
	v_mov_b32_e32 v17, v133
	v_mov_b32_e32 v18, v133
	v_mov_b32_e32 v19, v133
	v_mov_b32_e32 v20, v133
	v_mov_b32_e32 v21, v133
	v_mov_b32_e32 v22, v133
	v_mov_b32_e32 v23, v133
	v_mov_b32_e32 v24, v133
	v_mov_b32_e32 v25, v133
	v_mov_b32_e32 v26, v133
	v_mov_b32_e32 v27, v133
	v_mov_b32_e32 v28, v133
	v_mov_b32_e32 v29, v133
	v_mov_b32_e32 v30, v133
	v_mov_b32_e32 v31, v133
	v_mov_b32_e32 v64, v133
	v_mov_b32_e32 v65, v133
	v_mov_b32_e32 v66, v133
	v_mov_b32_e32 v67, v133
	v_mov_b32_e32 v68, v133
	v_mov_b32_e32 v69, v133
; #define MFMA(a, b, c) __builtin_amdgcn_mfma_f32_32x32x16_bf16((a), (b), (c), 0, 0, 0)
; template <int K, typename Epi>
; DI void gemm_tile_wide(const u16* __restrict__ A, int lda, const u16* __restrict__ Bt, int ldb, int m0, int n0, char* smem, Epi epi) {
;     ...
;   for (int kt = 0; kt < NS; ++kt) {
;     asm volatile("s_waitcnt vmcnt(0)" ::: "memory");
;     __syncthreads();
;     const int cur = (kt & 1) * STB;
;     if (kt + 1 < NS) issue(kt + 1, STB - cur);
;     const char* Sg = smem + cur;
;     bf16x8 a[2][2], b[2][4];
; #pragma unroll
;     for (int kk = 0; kk < 2; ++kk) {
; #pragma unroll
;       for (int i = 0; i < 2; ++i) a[kk][i] = *(const bf16x8*)(Sg + aoff[i][kk]);
; #pragma unroll
;       for (int j = 0; j < 4; ++j) b[kk][j] = *(const bf16x8*)(Sg + boff[j][kk]);
;     }
;     __builtin_amdgcn_sched_barrier(0);
;     __builtin_amdgcn_s_setprio(1);
; #pragma unroll
;     for (int kk = 0; kk < 2; ++kk)
; #pragma unroll
;       for (int i = 0; i < 2; ++i)
; #pragma unroll
;         for (int j = 0; j < 4; ++j) acc[i][j] = MFMA(a[kk][i], b[kk][j], acc[i][j]);
;     __builtin_amdgcn_s_setprio(0);
;   }
	v_mov_b32_e32 v70, v133
	v_mov_b32_e32 v71, v133
	v_mov_b32_e32 v72, v133
	v_mov_b32_e32 v73, v133
	v_mov_b32_e32 v74, v133
	v_mov_b32_e32 v75, v133
	v_mov_b32_e32 v76, v133
	v_mov_b32_e32 v77, v133
	v_mov_b32_e32 v78, v133
	v_mov_b32_e32 v79, v133
	v_mov_b32_e32 v32, v133
	v_mov_b32_e32 v33, v133
	v_mov_b32_e32 v34, v133
	v_mov_b32_e32 v35, v133
	v_mov_b32_e32 v36, v133
	v_mov_b32_e32 v37, v133
	v_mov_b32_e32 v38, v133
	v_mov_b32_e32 v39, v133
	v_mov_b32_e32 v40, v133
	v_mov_b32_e32 v41, v133
	v_mov_b32_e32 v42, v133
	v_mov_b32_e32 v43, v133
	v_mov_b32_e32 v44, v133
	v_mov_b32_e32 v45, v133
	v_mov_b32_e32 v46, v133
	v_mov_b32_e32 v47, v133
	v_mov_b32_e32 v96, v133
	v_mov_b32_e32 v97, v133
	v_mov_b32_e32 v98, v133
	v_mov_b32_e32 v99, v133
	v_mov_b32_e32 v100, v133
	v_mov_b32_e32 v101, v133
	v_mov_b32_e32 v102, v133
	v_mov_b32_e32 v103, v133
	v_mov_b32_e32 v104, v133
	v_mov_b32_e32 v105, v133
	v_mov_b32_e32 v106, v133
	v_mov_b32_e32 v107, v133
	v_mov_b32_e32 v108, v133
	v_mov_b32_e32 v109, v133
	v_mov_b32_e32 v110, v133
	v_mov_b32_e32 v111, v133
	v_mov_b32_e32 v80, v133
	v_mov_b32_e32 v81, v133
	v_mov_b32_e32 v82, v133
	v_mov_b32_e32 v83, v133
	v_mov_b32_e32 v84, v133
	v_mov_b32_e32 v85, v133
	v_mov_b32_e32 v86, v133
	v_mov_b32_e32 v87, v133
	v_mov_b32_e32 v88, v133
	v_mov_b32_e32 v89, v133
	v_mov_b32_e32 v90, v133
	v_mov_b32_e32 v91, v133
	v_mov_b32_e32 v92, v133
	v_mov_b32_e32 v93, v133
	v_mov_b32_e32 v94, v133
	v_mov_b32_e32 v95, v133
	v_mov_b32_e32 v112, v133
	v_mov_b32_e32 v113, v133
	v_mov_b32_e32 v114, v133
	v_mov_b32_e32 v115, v133
	v_mov_b32_e32 v116, v133
	v_mov_b32_e32 v117, v133
	v_mov_b32_e32 v118, v133
	v_mov_b32_e32 v119, v133
	v_mov_b32_e32 v120, v133
	v_mov_b32_e32 v121, v133
	v_mov_b32_e32 v122, v133
	v_mov_b32_e32 v123, v133
	v_mov_b32_e32 v124, v133
	v_mov_b32_e32 v125, v133
	v_mov_b32_e32 v126, v133
	v_mov_b32_e32 v127, v133
.LBB0_927:
	s_bitcmp1_b32 s3, 0
	s_cselect_b32 s5, 0x6000, 0
	v_subrev_u32_e32 v166, s5, v147
	v_add_u32_e32 v167, 0x6000, v166
	v_add_u32_e32 v168, 0x8000, v166
	v_readfirstlane_b32 s6, v167
	v_lshl_add_u64 v[154:155], v[128:129], 0, s[0:1]
	v_add_u32_e32 v169, 0x7000, v166
	v_readfirstlane_b32 s7, v168
	s_mov_b32 m0, s6
	s_waitcnt vmcnt(0)
	s_waitcnt vmcnt(0) lgkmcnt(0)
	s_barrier
	v_lshl_add_u64 v[156:157], v[130:131], 0, s[100:101]
	v_add_u32_e32 v170, 0x9000, v166
	v_readfirstlane_b32 s8, v169
	global_load_lds_dwordx4 v[154:155], off
	s_mov_b32 m0, s7
	v_lshl_add_u64 v[158:159], v[134:135], 0, s[0:1]
	v_add_u32_e32 v171, 0xa000, v166
	v_readfirstlane_b32 s9, v170
	global_load_lds_dwordx4 v[156:157], off
	s_mov_b32 m0, s8
	v_lshl_add_u64 v[160:161], v[136:137], 0, s[100:101]
	v_add_u32_e32 v166, 0xb000, v166
	v_readfirstlane_b32 s18, v171
	global_load_lds_dwordx4 v[158:159], off
	s_mov_b32 m0, s9
	v_lshl_add_u64 v[162:163], v[138:139], 0, s[100:101]
	v_readfirstlane_b32 s19, v166
	global_load_lds_dwordx4 v[160:161], off
	s_mov_b32 m0, s18
	v_lshl_add_u64 v[164:165], v[140:141], 0, s[100:101]
	global_load_lds_dwordx4 v[162:163], off
	s_mov_b32 m0, s19
	v_add_u32_e32 v158, s5, v145
	global_load_lds_dwordx4 v[164:165], off
	v_add_u32_e32 v162, s5, v148
	v_add_u32_e32 v174, s5, v149
	v_add_u32_e32 v182, s5, v146
	v_add_u32_e32 v188, s5, v150
	v_add_u32_e32 v192, s5, v151
	v_add_u32_e32 v196, s5, v152
	v_add_u32_e32 v200, s5, v153
	ds_read_b128 v[154:157], v158
	ds_read_b128 v[158:161], v158 offset:2048
	ds_read_b128 v[162:165], v162 offset:8192
	ds_read_b128 v[166:169], v174 offset:2048
	ds_read_b128 v[170:173], v174 offset:4096
	ds_read_b128 v[174:177], v174 offset:6144
	ds_read_b128 v[178:181], v182
	ds_read_b128 v[182:185], v182 offset:2048
	ds_read_b128 v[188:191], v188 offset:8192
	ds_read_b128 v[192:195], v192 offset:8192
	ds_read_b128 v[196:199], v196 offset:8192
	ds_read_b128 v[200:203], v200 offset:8192
	s_add_i32 s3, s3, 1
	s_setprio 1
	s_waitcnt lgkmcnt(0)
	v_mfma_f32_32x32x16_bf16 v[0:15], v[154:157], v[162:165], v[0:15]
	v_mfma_f32_32x32x16_bf16 v[48:63], v[154:157], v[166:169], v[48:63]
	v_mfma_f32_32x32x16_bf16 v[16:31], v[154:157], v[170:173], v[16:31]
	v_mfma_f32_32x32x16_bf16 v[64:79], v[154:157], v[174:177], v[64:79]
	v_mfma_f32_32x32x16_bf16 v[32:47], v[158:161], v[162:165], v[32:47]
	v_mfma_f32_32x32x16_bf16 v[96:111], v[158:161], v[166:169], v[96:111]
	v_mfma_f32_32x32x16_bf16 v[80:95], v[158:161], v[170:173], v[80:95]
	v_mfma_f32_32x32x16_bf16 v[112:127], v[158:161], v[174:177], v[112:127]
	v_mfma_f32_32x32x16_bf16 v[0:15], v[178:181], v[188:191], v[0:15]
	v_mfma_f32_32x32x16_bf16 v[48:63], v[178:181], v[192:195], v[48:63]
	v_mfma_f32_32x32x16_bf16 v[16:31], v[178:181], v[196:199], v[16:31]
	v_mfma_f32_32x32x16_bf16 v[64:79], v[178:181], v[200:203], v[64:79]
	v_mfma_f32_32x32x16_bf16 v[32:47], v[182:185], v[188:191], v[32:47]
	v_mfma_f32_32x32x16_bf16 v[96:111], v[182:185], v[192:195], v[96:111]
	v_mfma_f32_32x32x16_bf16 v[80:95], v[182:185], v[196:199], v[80:95]
	v_mfma_f32_32x32x16_bf16 v[112:127], v[182:185], v[200:203], v[112:127]
	s_setprio 0
	s_add_u32 s0, s0, 64
	s_addc_u32 s1, s1, 0
	s_add_u32 s100, s100, 0x40000
	s_addc_u32 s101, s101, 0
	s_cmpk_eq_i32 s0, 0x7c0
	s_cbranch_scc0 .LBB0_927
	s_waitcnt vmcnt(0)
	s_waitcnt vmcnt(0)
	s_barrier
; #define MFMA(a, b, c) __builtin_amdgcn_mfma_f32_32x32x16_bf16((a), (b), (c), 0, 0, 0)
; DI int crow(int reg, int h) { return (reg & 3) + 8 * (reg >> 2) + 4 * h; }
; template <int K, typename Epi>
; DI void gemm_tile_wide(const u16* __restrict__ A, int lda, const u16* __restrict__ Bt, int ldb, int m0, int n0, char* smem, Epi epi) {
;     ...
;     bf16x8 a[2][2], b[2][4];
; #pragma unroll
;     for (int kk = 0; kk < 2; ++kk) {
; #pragma unroll
;       for (int i = 0; i < 2; ++i) a[kk][i] = *(const bf16x8*)(Sg + aoff[i][kk]);
; #pragma unroll
;       for (int j = 0; j < 4; ++j) b[kk][j] = *(const bf16x8*)(Sg + boff[j][kk]);
;     }
;     __builtin_amdgcn_sched_barrier(0);
;     __builtin_amdgcn_s_setprio(1);
; #pragma unroll
;     for (int kk = 0; kk < 2; ++kk)
; #pragma unroll
;       for (int i = 0; i < 2; ++i)
; #pragma unroll
;         for (int j = 0; j < 4; ++j) acc[i][j] = MFMA(a[kk][i], b[kk][j], acc[i][j]);
;     __builtin_amdgcn_s_setprio(0);
;   }
;   float* Cs = (float*)smem;
; #pragma unroll
;   for (int half = 0; half < 2; ++half) {
;     __syncthreads();
;     if (wn == half) {
; #pragma unroll
;       for (int i = 0; i < 2; ++i)
; #pragma unroll
;         for (int j = 0; j < 4; ++j)
; #pragma unroll
;           for (int e = 0; e < 16; ++e) Cs[(wm * 64 + i * 32 + crow(e, h)) * CS_LD + j * 32 + r] = acc[i][j][e];
;     }
	ds_read_b128 v[128:131], v153 offset:32768
	ds_read_b128 v[134:137], v152 offset:32768
	ds_read_b128 v[138:141], v151 offset:32768
	ds_read_b128 v[150:153], v150 offset:32768
	ds_read_b128 v[154:157], v146 offset:26624
	ds_read_b128 v[158:161], v146 offset:24576
	ds_read_b128 v[162:165], v149 offset:30720
	ds_read_b128 v[166:169], v149 offset:28672
	ds_read_b128 v[170:173], v149 offset:26624
	ds_read_b128 v[146:149], v148 offset:32768
	ds_read_b128 v[174:177], v145 offset:26624
	ds_read_b128 v[178:181], v145 offset:24576
	s_setprio 1
	s_waitcnt lgkmcnt(0)
	v_mfma_f32_32x32x16_bf16 v[0:15], v[178:181], v[146:149], v[0:15]
	v_mfma_f32_32x32x16_bf16 v[48:63], v[178:181], v[170:173], v[48:63]
	v_mfma_f32_32x32x16_bf16 v[16:31], v[178:181], v[166:169], v[16:31]
	v_mfma_f32_32x32x16_bf16 v[64:79], v[178:181], v[162:165], v[64:79]
	v_mfma_f32_32x32x16_bf16 v[32:47], v[174:177], v[146:149], v[32:47]
	v_mfma_f32_32x32x16_bf16 v[96:111], v[174:177], v[170:173], v[96:111]
	v_mfma_f32_32x32x16_bf16 v[80:95], v[174:177], v[166:169], v[80:95]
	v_mfma_f32_32x32x16_bf16 v[112:127], v[174:177], v[162:165], v[112:127]
	v_mfma_f32_32x32x16_bf16 v[0:15], v[158:161], v[150:153], v[0:15]
	v_mfma_f32_32x32x16_bf16 v[48:63], v[158:161], v[138:141], v[48:63]
	v_mfma_f32_32x32x16_bf16 v[16:31], v[158:161], v[134:137], v[16:31]
	v_mfma_f32_32x32x16_bf16 v[64:79], v[158:161], v[128:131], v[64:79]
	v_mfma_f32_32x32x16_bf16 v[32:47], v[154:157], v[150:153], v[32:47]
	v_mfma_f32_32x32x16_bf16 v[96:111], v[154:157], v[138:141], v[96:111]
	v_mfma_f32_32x32x16_bf16 v[80:95], v[154:157], v[134:137], v[80:95]
	v_mfma_f32_32x32x16_bf16 v[112:127], v[154:157], v[128:131], v[112:127]
	s_setprio 0
	v_lshlrev_b32_e32 v128, 6, v142
	v_lshl_or_b32 v135, v143, 2, v128
	v_lshlrev_b32_e32 v134, 2, v144
	v_cmp_ne_u32_e64 s[8:9], 0, v132
	v_cmp_eq_u32_e32 vcc, 0, v132
	s_barrier
	s_and_saveexec_b64 s[0:1], vcc
	s_cbranch_execz .LBB0_930
	v_mad_u64_u32 v[128:129], s[6:7], v135, s52, v[134:135]
	v_add_u32_e32 v129, 0x400, v128
	v_add_u32_e32 v130, 0x1000, v128
	v_add_u32_e32 v131, 0x1400, v128
	v_add_u32_e32 v132, 0x2000, v128
	v_add_u32_e32 v136, 0x2400, v128
	v_add_u32_e32 v138, 0x3200, v128
	ds_write2_b32 v128, v0, v48 offset1:32
	ds_write2_b32 v128, v1, v49 offset0:132 offset1:164
	ds_write2_b32 v129, v2, v50 offset0:8 offset1:40
	ds_write2_b32 v129, v3, v51 offset0:140 offset1:172
	ds_write2_b32 v130, v4, v52 offset0:32 offset1:64
	ds_write2_b32 v130, v5, v53 offset0:164 offset1:196
	ds_write2_b32 v131, v6, v54 offset0:40 offset1:72
	ds_write2_b32 v131, v7, v55 offset0:172 offset1:204
	ds_write2_b32 v132, v8, v56 offset0:64 offset1:96
	ds_write2_b32 v132, v9, v57 offset0:196 offset1:228
	ds_write2_b32 v136, v10, v58 offset0:72 offset1:104
	ds_write2_b32 v136, v11, v59 offset0:204 offset1:236
	v_add_u32_e32 v137, 0x3000, v128
	ds_write2_b32 v138, v13, v61 offset0:100 offset1:132
	v_add_u32_e32 v138, 0x3400, v128
	v_add_u32_e32 v139, 0x3600, v128
	ds_write2_b32 v137, v12, v60 offset0:96 offset1:128
	ds_write2_b32 v138, v14, v62 offset0:104 offset1:136
	ds_write2_b32 v139, v15, v63 offset0:108 offset1:140
	ds_write2_b32 v128, v16, v64 offset0:64 offset1:96
	ds_write2_b32 v128, v17, v65 offset0:196 offset1:228
	ds_write2_b32 v129, v18, v66 offset0:72 offset1:104
	ds_write2_b32 v129, v19, v67 offset0:204 offset1:236
	ds_write2_b32 v130, v20, v68 offset0:96 offset1:128
	v_add_u32_e32 v129, 0x1200, v128
	ds_write2_b32 v129, v21, v69 offset0:100 offset1:132
	ds_write2_b32 v131, v22, v70 offset0:104 offset1:136
	v_add_u32_e32 v129, 0x1600, v128
	ds_write2_b32 v129, v23, v71 offset0:108 offset1:140
	ds_write2_b32 v132, v24, v72 offset0:128 offset1:160
	ds_write2_b32 v136, v25, v73 offset0:4 offset1:36
	ds_write2_b32 v136, v26, v74 offset0:136 offset1:168
	v_add_u32_e32 v129, 0x2800, v128
	ds_write2_b32 v129, v27, v75 offset0:12 offset1:44
	ds_write2_b32 v137, v28, v76 offset0:160 offset1:192
	ds_write2_b32 v138, v29, v77 offset0:36 offset1:68
	ds_write2_b32 v138, v30, v78 offset0:168 offset1:200
	v_add_u32_e32 v129, 0x3800, v128
	ds_write2_b32 v129, v31, v79 offset0:44 offset1:76
	v_add_u32_e32 v129, 0x4000, v128
	v_add_u32_e32 v130, 0x4400, v128
	v_add_u32_e32 v132, 0x5000, v128
	ds_write2_b32 v129, v32, v96 offset0:128 offset1:160
	ds_write2_b32 v130, v33, v97 offset0:4 offset1:36
	ds_write2_b32 v130, v34, v98 offset0:136 offset1:168
	v_add_u32_e32 v131, 0x4800, v128
	ds_write2_b32 v132, v36, v100 offset0:160 offset1:192
	v_add_u32_e32 v132, 0x5400, v128
	v_add_u32_e32 v137, 0x6000, v128
	ds_write2_b32 v131, v35, v99 offset0:12 offset1:44
	ds_write2_b32 v132, v37, v101 offset0:36 offset1:68
	ds_write2_b32 v132, v38, v102 offset0:168 offset1:200
	v_add_u32_e32 v136, 0x5800, v128
	ds_write2_b32 v137, v40, v104 offset0:192 offset1:224
	v_add_u32_e32 v137, 0x6400, v128
	v_add_u32_e32 v139, 0x7200, v128
	v_add_u32_e32 v140, 0x7600, v128
	ds_write2_b32 v136, v39, v103 offset0:44 offset1:76
	ds_write2_b32 v137, v41, v105 offset0:68 offset1:100
	ds_write2_b32 v137, v42, v106 offset0:200 offset1:232
	v_add_u32_e32 v138, 0x6800, v128
	ds_write2_b32 v139, v44, v108 offset0:96 offset1:128
	v_add_u32_e32 v139, 0x7400, v128
	ds_write2_b32 v140, v46, v110 offset0:104 offset1:136
	v_add_u32_e32 v140, 0x7800, v128
	ds_write2_b32 v138, v43, v107 offset0:76 offset1:108
	ds_write2_b32 v139, v45, v109 offset0:100 offset1:132
	ds_write2_b32 v140, v47, v111 offset0:108 offset1:140
	ds_write2_b32 v129, v80, v112 offset0:192 offset1:224
	ds_write2_b32 v130, v81, v113 offset0:68 offset1:100
	ds_write2_b32 v130, v82, v114 offset0:200 offset1:232
	ds_write2_b32 v131, v83, v115 offset0:76 offset1:108
	v_add_u32_e32 v129, 0x5200, v128
	v_add_u32_e32 v128, 0x5600, v128
	ds_write2_b32 v129, v84, v116 offset0:96 offset1:128
	ds_write2_b32 v132, v85, v117 offset0:100 offset1:132
	ds_write2_b32 v128, v86, v118 offset0:104 offset1:136
	ds_write2_b32 v136, v87, v119 offset0:108 offset1:140
	ds_write2_b32 v137, v88, v120 offset1:32
	ds_write2_b32 v137, v89, v121 offset0:132 offset1:164
	ds_write2_b32 v138, v90, v122 offset0:8 offset1:40
	ds_write2_b32 v138, v91, v123 offset0:140 offset1:172
	ds_write2_b32 v139, v92, v124 offset0:32 offset1:64
	ds_write2_b32 v139, v93, v125 offset0:164 offset1:196
	ds_write2_b32 v140, v94, v126 offset0:40 offset1:72
	ds_write2_b32 v140, v95, v127 offset0:172 offset1:204

; template <int K, typename Epi>
; DI void gemm_tile_wide(const u16* __restrict__ A, int lda, const u16* __restrict__ Bt, int ldb, int m0, int n0, char* smem, Epi epi) {
;     ...
;   f32x16 acc[2][4];
; #pragma unroll
;   for (int i = 0; i < 2; ++i)
; #pragma unroll
;     for (int j = 0; j < 4; ++j)
; #pragma unroll
;       for (int e = 0; e < 16; ++e) acc[i][j][e] = 0.f;
;   constexpr int NS = K / 32;
;   constexpr int AB = 128 * 64;
;   constexpr int STB = AB + 256 * 64;
;   const int lrow = tid >> 2, cpos = tid & 3;
;   const u16* ap[2]; const u16* bp[4];
; #pragma unroll
;   for (int i = 0; i < 4; ++i) {
;     const int row = lrow + 64 * i;
;     const int sc = cpos ^ ((row >> 2) & 3);
;     if (i < 2) ap[i] = A + (size_t)(m0 + row) * lda + sc * 8;
;     bp[i] = Bt + (size_t)(n0 + row) * ldb + sc * 8;
;   }
;   char* const ldst = smem + tid * 16;
;   int aoff[2][2], boff[4][2];
; #pragma unroll
;   for (int kk = 0; kk < 2; ++kk) {
; #pragma unroll
;     for (int i = 0; i < 2; ++i) { const int ra_ = wm * 64 + i * 32 + r; aoff[i][kk] = ra_ * 64 + (((2 * kk + h) ^ ((ra_ >> 2) & 3)) << 4); }
; #pragma unroll
;     for (int j = 0; j < 4; ++j) { const int rb_ = wn * 128 + j * 32 + r; boff[j][kk] = AB + rb_ * 64 + (((2 * kk + h) ^ ((rb_ >> 2) & 3)) << 4); }
;   }
;   auto issue = [&](int slice, int st) {
; #pragma unroll
;     for (int i = 0; i < 4; ++i) {
;       if (i < 2) __builtin_amdgcn_global_load_lds((const unsigned*)(ap[i] + slice * 32), (unsigned*)(ldst + st + i * 4096), 16, 0, 0);
;       __builtin_amdgcn_global_load_lds((const unsigned*)(bp[i] + slice * 32), (unsigned*)(ldst + st + AB + i * 4096), 16, 0, 0);
;     }
;   };
;   __syncthreads();
;   issue(0, 0);
.LBB0_2050:
	v_mov_b32_e32 v12, v186
	s_lshl_b32 s2, s5, 5
	s_and_b32 s27, s2, 0xffffff80
	v_lshrrev_b32_e32 v15, 4, v12
	v_ashrrev_i32_e32 v14, 2, v12
	v_xor_b32_e32 v0, v15, v12
	v_lshlrev_b32_e32 v0, 4, v0
	v_add_u32_e32 v4, s27, v14
	s_lshl_b32 s2, s5, 8
	v_and_b32_e32 v128, 48, v0
	v_ashrrev_i32_e32 v5, 31, v4
	v_lshlrev_b32_e32 v147, 4, v12
	s_and_b32 s28, s2, 0x300
	v_lshl_add_u64 v[2:3], s[38:39], 0, v[128:129]
	v_lshlrev_b64 v[4:5], 11, v[4:5]
	v_readfirstlane_b32 s2, v147
	v_lshl_add_u64 v[4:5], v[2:3], 0, v[4:5]
	v_add_u32_e32 v6, s28, v14
	v_add_u32_e32 v16, 64, v14
	s_mov_b32 m0, s2
	v_ashrrev_i32_e32 v7, 31, v6
	v_add_u32_e32 v8, s27, v16
	s_barrier
	global_load_lds_dwordx4 v[4:5], off
	v_add_u32_e32 v4, 0x2000, v147
	v_lshl_add_u64 v[0:1], s[6:7], 0, v[128:129]
	v_lshlrev_b64 v[6:7], 11, v[6:7]
	v_ashrrev_i32_e32 v9, 31, v8
	v_readfirstlane_b32 s2, v4
	v_add_u32_e32 v4, 0x1000, v147
	v_lshl_add_u64 v[6:7], v[0:1], 0, v[6:7]
	v_lshlrev_b64 v[8:9], 11, v[8:9]
	s_mov_b32 m0, s2
	v_readfirstlane_b32 s2, v4
	v_lshl_add_u64 v[2:3], v[2:3], 0, v[8:9]
	v_add_u32_e32 v8, s28, v16
	global_load_lds_dwordx4 v[6:7], off
	s_mov_b32 m0, s2
	v_ashrrev_i32_e32 v9, 31, v8
	global_load_lds_dwordx4 v[2:3], off
	v_add_u32_e32 v2, 0x3000, v147
	v_lshlrev_b64 v[8:9], 11, v[8:9]
	v_readfirstlane_b32 s2, v2
	v_lshl_add_u64 v[0:1], v[0:1], 0, v[8:9]
	s_mov_b32 m0, s2
	v_lshl_add_u64 v[8:9], v[6:7], 0, s[16:17]
	global_load_lds_dwordx4 v[0:1], off
	v_add_u32_e32 v0, 0x4000, v147
	v_lshl_add_u64 v[10:11], v[6:7], 0, s[20:21]
	v_readfirstlane_b32 s2, v0
	v_add_u32_e32 v0, 0x5000, v147
	s_mov_b32 m0, s2
	v_readfirstlane_b32 s2, v0
	global_load_lds_dwordx4 v[8:9], off
	s_mov_b32 m0, s2
	s_and_b32 s0, s19, 0xffffff80
	global_load_lds_dwordx4 v[10:11], off
	v_add_u32_e32 v0, s0, v14
	v_ashrrev_i32_e32 v1, 31, v0
	v_bitop3_b32 v2, v15, 3, v12 bitop3:0x48
	v_lshlrev_b64 v[0:1], 11, v[0:1]
	v_lshlrev_b32_e32 v4, 4, v2
	s_and_b32 s1, s24, 0x300
	v_or_b32_e32 v0, v0, v4
	v_lshl_add_u64 v[130:131], s[12:13], 0, v[0:1]
	v_add_u32_e32 v0, s1, v14
	v_ashrrev_i32_e32 v1, 31, v0
	v_lshlrev_b64 v[2:3], 11, v[0:1]
	v_or_b32_e32 v2, v2, v4
	v_lshl_add_u64 v[132:133], s[14:15], 0, v[2:3]
	v_add_u32_e32 v2, s0, v16
	v_ashrrev_i32_e32 v3, 31, v2
	v_lshlrev_b64 v[2:3], 11, v[2:3]
	v_or_b32_e32 v2, v2, v4
	v_lshl_add_u64 v[134:135], s[12:13], 0, v[2:3]
	v_add_u32_e32 v2, s1, v16
	v_ashrrev_i32_e32 v3, 31, v2
	v_lshlrev_b64 v[2:3], 11, v[2:3]
	v_or_b32_e32 v2, v2, v4
	v_lshrrev_b32_e32 v13, 5, v12
	v_bfe_u32 v143, v12, 5, 1
	v_and_b32_e32 v144, 31, v12
	v_bfe_u32 v17, v12, 2, 2
	v_lshl_add_u64 v[136:137], s[14:15], 0, v[2:3]
	v_add_u32_e32 v2, 0x80, v0
	v_add_u32_e32 v0, 0xc0, v0
	v_bfe_u32 v128, v12, 6, 1
	v_lshlrev_b32_e32 v18, 6, v144
	v_bitop3_b32 v13, v13, v17, 1 bitop3:0x6c
	v_bitop3_b32 v17, v143, v17, 2 bitop3:0x36
	v_ashrrev_i32_e32 v3, 31, v2
	v_ashrrev_i32_e32 v1, 31, v0
	v_ashrrev_i32_e32 v142, 7, v12
	v_lshl_or_b32 v19, v128, 13, v18
	v_lshlrev_b32_e32 v13, 4, v13
	v_lshlrev_b32_e32 v17, 4, v17
	v_lshlrev_b64 v[2:3], 11, v[2:3]
	v_lshlrev_b64 v[0:1], 11, v[0:1]
	v_lshl_or_b32 v18, v142, 12, v18
	v_or_b32_e32 v148, v19, v13
	v_or_b32_e32 v150, v17, v19
	v_or_b32_e32 v2, v2, v4
	v_or_b32_e32 v0, v0, v4
	v_or_b32_e32 v145, v13, v18
	v_or_b32_e32 v146, v17, v18
	v_add_u32_e32 v149, 0x2000, v148
	v_or_b32_e32 v151, 0x800, v150
	v_or_b32_e32 v152, 0x1000, v150
	v_or_b32_e32 v153, 0x1800, v150
	v_lshl_add_u64 v[138:139], s[14:15], 0, v[2:3]
	v_lshl_add_u64 v[140:141], s[14:15], 0, v[0:1]
	s_mov_b64 s[0:1], 0
	s_mov_b32 s2, 0
	s_and_b32 s99, s5, 3
	s_lshl_b32 s99, s99, 8
	v_lshrrev_b32_e32 v240, 4, v186
	v_xor_b32_e32 v240, v240, v186
	v_and_b32_e32 v240, 3, v240
	v_lshlrev_b32_e32 v240, 4, v240
	v_lshrrev_b32_e32 v241, 2, v186
	v_add_u32_e32 v241, s99, v241
	v_lshl_add_u32 v240, v241, 6, v240
	v_mov_b32_e32 v241, 0
	s_add_u32 s100, s86, 0x1d5e1000
	s_addc_u32 s101, s87, 0
	v_lshl_add_u64 v[132:133], s[100:101], 0, v[240:241]
	v_add_u32_e32 v240, 0x1000, v240
	v_lshl_add_u64 v[136:137], s[100:101], 0, v[240:241]
	v_add_u32_e32 v240, 0x1000, v240
	v_lshl_add_u64 v[138:139], s[100:101], 0, v[240:241]
	v_add_u32_e32 v240, 0x1000, v240
	v_lshl_add_u64 v[140:141], s[100:101], 0, v[240:241]
	s_mov_b64 s[100:101], 0
	v_mov_b32_e32 v0, 0
	v_mov_b32_e32 v1, v129
	v_mov_b32_e32 v2, v129
	v_mov_b32_e32 v3, v129
	v_mov_b32_e32 v4, v129
	v_mov_b32_e32 v5, v129
	v_mov_b32_e32 v6, v129
	v_mov_b32_e32 v7, v129
	v_mov_b32_e32 v8, v129
	v_mov_b32_e32 v9, v129
	v_mov_b32_e32 v10, v129
	v_mov_b32_e32 v11, v129
	v_mov_b32_e32 v12, v129
	v_mov_b32_e32 v13, v129
	v_mov_b32_e32 v14, v129
	v_mov_b32_e32 v15, v129
	v_mov_b32_e32 v48, 0
	v_mov_b32_e32 v49, v129
	v_mov_b32_e32 v50, v129
	v_mov_b32_e32 v51, v129
	v_mov_b32_e32 v52, v129
	v_mov_b32_e32 v53, v129
	v_mov_b32_e32 v54, v129
	v_mov_b32_e32 v55, v129
	v_mov_b32_e32 v56, v129
	v_mov_b32_e32 v57, v129
	v_mov_b32_e32 v58, v129
	v_mov_b32_e32 v59, v129
	v_mov_b32_e32 v60, v129
	v_mov_b32_e32 v61, v129
	v_mov_b32_e32 v62, v129
	v_mov_b32_e32 v63, v129
	v_mov_b32_e32 v16, 0
	v_mov_b32_e32 v17, v129
	v_mov_b32_e32 v18, v129
	v_mov_b32_e32 v19, v129
	v_mov_b32_e32 v20, v129
	v_mov_b32_e32 v21, v129
	v_mov_b32_e32 v22, v129
	v_mov_b32_e32 v23, v129
	v_mov_b32_e32 v24, v129
	v_mov_b32_e32 v25, v129
	v_mov_b32_e32 v26, v129
	v_mov_b32_e32 v27, v129
	v_mov_b32_e32 v28, v129
	v_mov_b32_e32 v29, v129
	v_mov_b32_e32 v30, v129
	v_mov_b32_e32 v31, v129
	v_mov_b32_e32 v64, 0
	v_mov_b32_e32 v65, v129
	v_mov_b32_e32 v66, v129
	v_mov_b32_e32 v67, v129
	v_mov_b32_e32 v68, v129
	v_mov_b32_e32 v69, v129
	v_mov_b32_e32 v70, v129
	v_mov_b32_e32 v71, v129
; #define MFMA(a, b, c) __builtin_amdgcn_mfma_f32_32x32x16_bf16((a), (b), (c), 0, 0, 0)
; template <int K, typename Epi>
; DI void gemm_tile_wide(const u16* __restrict__ A, int lda, const u16* __restrict__ Bt, int ldb, int m0, int n0, char* smem, Epi epi) {
;     ...
;   for (int kt = 0; kt < NS; ++kt) {
;     asm volatile("s_waitcnt vmcnt(0)" ::: "memory");
;     __syncthreads();
;     const int cur = (kt & 1) * STB;
;     if (kt + 1 < NS) issue(kt + 1, STB - cur);
;     const char* Sg = smem + cur;
;     bf16x8 a[2][2], b[2][4];
; #pragma unroll
;     for (int kk = 0; kk < 2; ++kk) {
; #pragma unroll
;       for (int i = 0; i < 2; ++i) a[kk][i] = *(const bf16x8*)(Sg + aoff[i][kk]);
; #pragma unroll
;       for (int j = 0; j < 4; ++j) b[kk][j] = *(const bf16x8*)(Sg + boff[j][kk]);
;     }
;     __builtin_amdgcn_sched_barrier(0);
;     __builtin_amdgcn_s_setprio(1);
; #pragma unroll
;     for (int kk = 0; kk < 2; ++kk)
; #pragma unroll
;       for (int i = 0; i < 2; ++i)
; #pragma unroll
;         for (int j = 0; j < 4; ++j) acc[i][j] = MFMA(a[kk][i], b[kk][j], acc[i][j]);
;     __builtin_amdgcn_s_setprio(0);
;   }
	v_mov_b32_e32 v72, v129
	v_mov_b32_e32 v73, v129
	v_mov_b32_e32 v74, v129
	v_mov_b32_e32 v75, v129
	v_mov_b32_e32 v76, v129
	v_mov_b32_e32 v77, v129
	v_mov_b32_e32 v78, v129
	v_mov_b32_e32 v79, v129
	v_mov_b32_e32 v32, 0
	v_mov_b32_e32 v33, v129
	v_mov_b32_e32 v34, v129
	v_mov_b32_e32 v35, v129
	v_mov_b32_e32 v36, v129
	v_mov_b32_e32 v37, v129
	v_mov_b32_e32 v38, v129
	v_mov_b32_e32 v39, v129
	v_mov_b32_e32 v40, v129
	v_mov_b32_e32 v41, v129
	v_mov_b32_e32 v42, v129
	v_mov_b32_e32 v43, v129
	v_mov_b32_e32 v44, v129
	v_mov_b32_e32 v45, v129
	v_mov_b32_e32 v46, v129
	v_mov_b32_e32 v47, v129
	v_mov_b32_e32 v96, 0
	v_mov_b32_e32 v97, v129
	v_mov_b32_e32 v98, v129
	v_mov_b32_e32 v99, v129
	v_mov_b32_e32 v100, v129
	v_mov_b32_e32 v101, v129
	v_mov_b32_e32 v102, v129
	v_mov_b32_e32 v103, v129
	v_mov_b32_e32 v104, v129
	v_mov_b32_e32 v105, v129
	v_mov_b32_e32 v106, v129
	v_mov_b32_e32 v107, v129
	v_mov_b32_e32 v108, v129
	v_mov_b32_e32 v109, v129
	v_mov_b32_e32 v110, v129
	v_mov_b32_e32 v111, v129
	v_mov_b32_e32 v80, 0
	v_mov_b32_e32 v81, v129
	v_mov_b32_e32 v82, v129
	v_mov_b32_e32 v83, v129
	v_mov_b32_e32 v84, v129
	v_mov_b32_e32 v85, v129
	v_mov_b32_e32 v86, v129
	v_mov_b32_e32 v87, v129
	v_mov_b32_e32 v88, v129
	v_mov_b32_e32 v89, v129
	v_mov_b32_e32 v90, v129
	v_mov_b32_e32 v91, v129
	v_mov_b32_e32 v92, v129
	v_mov_b32_e32 v93, v129
	v_mov_b32_e32 v94, v129
	v_mov_b32_e32 v95, v129
	v_mov_b32_e32 v112, 0
	v_mov_b32_e32 v113, v129
	v_mov_b32_e32 v114, v129
	v_mov_b32_e32 v115, v129
	v_mov_b32_e32 v116, v129
	v_mov_b32_e32 v117, v129
	v_mov_b32_e32 v118, v129
	v_mov_b32_e32 v119, v129
	v_mov_b32_e32 v120, v129
	v_mov_b32_e32 v121, v129
	v_mov_b32_e32 v122, v129
	v_mov_b32_e32 v123, v129
	v_mov_b32_e32 v124, v129
	v_mov_b32_e32 v125, v129
	v_mov_b32_e32 v126, v129
	v_mov_b32_e32 v127, v129
.LBB0_2051:
	s_bitcmp1_b32 s2, 0
	s_cselect_b32 s3, 0x6000, 0
	v_subrev_u32_e32 v166, s3, v147
	v_add_u32_e32 v167, 0x6000, v166
	v_add_u32_e32 v168, 0x8000, v166
	v_readfirstlane_b32 s29, v167
	v_lshl_add_u64 v[154:155], v[130:131], 0, s[0:1]
	v_add_u32_e32 v169, 0x7000, v166
	v_readfirstlane_b32 s30, v168
	s_mov_b32 m0, s29
	s_waitcnt vmcnt(0)
	s_waitcnt vmcnt(0) lgkmcnt(0)
	s_barrier
	v_lshl_add_u64 v[156:157], v[132:133], 0, s[100:101]
	v_add_u32_e32 v170, 0x9000, v166
	v_readfirstlane_b32 s31, v169
	global_load_lds_dwordx4 v[154:155], off
	s_mov_b32 m0, s30
	v_lshl_add_u64 v[158:159], v[134:135], 0, s[0:1]
	v_add_u32_e32 v171, 0xa000, v166
	v_readfirstlane_b32 s33, v170
	global_load_lds_dwordx4 v[156:157], off
	s_mov_b32 m0, s31
	v_lshl_add_u64 v[160:161], v[136:137], 0, s[100:101]
	v_add_u32_e32 v166, 0xb000, v166
	v_readfirstlane_b32 s34, v171
	global_load_lds_dwordx4 v[158:159], off
	s_mov_b32 m0, s33
	v_lshl_add_u64 v[162:163], v[138:139], 0, s[100:101]
	v_readfirstlane_b32 s35, v166
	global_load_lds_dwordx4 v[160:161], off
	s_mov_b32 m0, s34
	v_lshl_add_u64 v[164:165], v[140:141], 0, s[100:101]
	global_load_lds_dwordx4 v[162:163], off
	s_mov_b32 m0, s35
	v_add_u32_e32 v158, s3, v145
	global_load_lds_dwordx4 v[164:165], off
	v_add_u32_e32 v162, s3, v148
	v_add_u32_e32 v174, s3, v149
	v_add_u32_e32 v182, s3, v146
	v_add_u32_e32 v188, s3, v150
	v_add_u32_e32 v192, s3, v151
	v_add_u32_e32 v196, s3, v152
	v_add_u32_e32 v200, s3, v153
	ds_read_b128 v[154:157], v158
	ds_read_b128 v[158:161], v158 offset:2048
	ds_read_b128 v[162:165], v162 offset:8192
	ds_read_b128 v[166:169], v174 offset:2048
	ds_read_b128 v[170:173], v174 offset:4096
	ds_read_b128 v[174:177], v174 offset:6144
	ds_read_b128 v[178:181], v182
	ds_read_b128 v[182:185], v182 offset:2048
	ds_read_b128 v[188:191], v188 offset:8192
	ds_read_b128 v[192:195], v192 offset:8192
	ds_read_b128 v[196:199], v196 offset:8192
	ds_read_b128 v[200:203], v200 offset:8192
	s_add_i32 s2, s2, 1
	s_setprio 1
	s_waitcnt lgkmcnt(0)
	v_mfma_f32_32x32x16_bf16 v[0:15], v[154:157], v[162:165], v[0:15]
	v_mfma_f32_32x32x16_bf16 v[48:63], v[154:157], v[166:169], v[48:63]
	v_mfma_f32_32x32x16_bf16 v[16:31], v[154:157], v[170:173], v[16:31]
	v_mfma_f32_32x32x16_bf16 v[64:79], v[154:157], v[174:177], v[64:79]
	v_mfma_f32_32x32x16_bf16 v[32:47], v[158:161], v[162:165], v[32:47]
	v_mfma_f32_32x32x16_bf16 v[96:111], v[158:161], v[166:169], v[96:111]
	v_mfma_f32_32x32x16_bf16 v[80:95], v[158:161], v[170:173], v[80:95]
	v_mfma_f32_32x32x16_bf16 v[112:127], v[158:161], v[174:177], v[112:127]
	v_mfma_f32_32x32x16_bf16 v[0:15], v[178:181], v[188:191], v[0:15]
	v_mfma_f32_32x32x16_bf16 v[48:63], v[178:181], v[192:195], v[48:63]
	v_mfma_f32_32x32x16_bf16 v[16:31], v[178:181], v[196:199], v[16:31]
	v_mfma_f32_32x32x16_bf16 v[64:79], v[178:181], v[200:203], v[64:79]
	v_mfma_f32_32x32x16_bf16 v[32:47], v[182:185], v[188:191], v[32:47]
	v_mfma_f32_32x32x16_bf16 v[96:111], v[182:185], v[192:195], v[96:111]
	v_mfma_f32_32x32x16_bf16 v[80:95], v[182:185], v[196:199], v[80:95]
	v_mfma_f32_32x32x16_bf16 v[112:127], v[182:185], v[200:203], v[112:127]
	s_setprio 0
	s_add_u32 s0, s0, 64
	s_addc_u32 s1, s1, 0
	s_add_u32 s100, s100, 0x10000
	s_addc_u32 s101, s101, 0
	s_cmpk_eq_i32 s0, 0x7c0
	s_cbranch_scc0 .LBB0_2051
	s_waitcnt vmcnt(0)
	s_waitcnt vmcnt(0)
	s_barrier
; #define MFMA(a, b, c) __builtin_amdgcn_mfma_f32_32x32x16_bf16((a), (b), (c), 0, 0, 0)
; DI int crow(int reg, int h) { return (reg & 3) + 8 * (reg >> 2) + 4 * h; }
; template <int K, typename Epi>
; DI void gemm_tile_wide(const u16* __restrict__ A, int lda, const u16* __restrict__ Bt, int ldb, int m0, int n0, char* smem, Epi epi) {
;     ...
;     bf16x8 a[2][2], b[2][4];
; #pragma unroll
;     for (int kk = 0; kk < 2; ++kk) {
; #pragma unroll
;       for (int i = 0; i < 2; ++i) a[kk][i] = *(const bf16x8*)(Sg + aoff[i][kk]);
; #pragma unroll
;       for (int j = 0; j < 4; ++j) b[kk][j] = *(const bf16x8*)(Sg + boff[j][kk]);
;     }
;     __builtin_amdgcn_sched_barrier(0);
;     __builtin_amdgcn_s_setprio(1);
; #pragma unroll
;     for (int kk = 0; kk < 2; ++kk)
; #pragma unroll
;       for (int i = 0; i < 2; ++i)
; #pragma unroll
;         for (int j = 0; j < 4; ++j) acc[i][j] = MFMA(a[kk][i], b[kk][j], acc[i][j]);
;     __builtin_amdgcn_s_setprio(0);
;   }
;   float* Cs = (float*)smem;
; #pragma unroll
;   for (int half = 0; half < 2; ++half) {
;     __syncthreads();
;     if (wn == half) {
; #pragma unroll
;       for (int i = 0; i < 2; ++i)
; #pragma unroll
;         for (int j = 0; j < 4; ++j)
; #pragma unroll
;           for (int e = 0; e < 16; ++e) Cs[(wm * 64 + i * 32 + crow(e, h)) * CS_LD + j * 32 + r] = acc[i][j][e];
;     }
	ds_read_b128 v[130:133], v153 offset:32768
	ds_read_b128 v[134:137], v152 offset:32768
	ds_read_b128 v[138:141], v151 offset:32768
	ds_read_b128 v[150:153], v150 offset:32768
	ds_read_b128 v[154:157], v146 offset:26624
	ds_read_b128 v[158:161], v146 offset:24576
	ds_read_b128 v[162:165], v149 offset:30720
	ds_read_b128 v[166:169], v149 offset:28672
	ds_read_b128 v[170:173], v149 offset:26624
	ds_read_b128 v[146:149], v148 offset:32768
	ds_read_b128 v[174:177], v145 offset:26624
	ds_read_b128 v[178:181], v145 offset:24576
	s_setprio 1
	s_waitcnt lgkmcnt(0)
	v_mfma_f32_32x32x16_bf16 v[0:15], v[178:181], v[146:149], v[0:15]
	v_mfma_f32_32x32x16_bf16 v[48:63], v[178:181], v[170:173], v[48:63]
	v_mfma_f32_32x32x16_bf16 v[16:31], v[178:181], v[166:169], v[16:31]
	v_mfma_f32_32x32x16_bf16 v[64:79], v[178:181], v[162:165], v[64:79]
	v_mfma_f32_32x32x16_bf16 v[32:47], v[174:177], v[146:149], v[32:47]
	v_mfma_f32_32x32x16_bf16 v[96:111], v[174:177], v[170:173], v[96:111]
	v_mfma_f32_32x32x16_bf16 v[80:95], v[174:177], v[166:169], v[80:95]
	v_mfma_f32_32x32x16_bf16 v[112:127], v[174:177], v[162:165], v[112:127]
	v_mfma_f32_32x32x16_bf16 v[0:15], v[158:161], v[150:153], v[0:15]
	v_mfma_f32_32x32x16_bf16 v[48:63], v[158:161], v[138:141], v[48:63]
	v_mfma_f32_32x32x16_bf16 v[16:31], v[158:161], v[134:137], v[16:31]
	v_mfma_f32_32x32x16_bf16 v[64:79], v[158:161], v[130:133], v[64:79]
	v_mfma_f32_32x32x16_bf16 v[32:47], v[154:157], v[150:153], v[32:47]
	v_mfma_f32_32x32x16_bf16 v[96:111], v[154:157], v[138:141], v[96:111]
	v_mfma_f32_32x32x16_bf16 v[80:95], v[154:157], v[134:137], v[80:95]
	v_mfma_f32_32x32x16_bf16 v[112:127], v[154:157], v[130:133], v[112:127]
	s_setprio 0
	v_lshlrev_b32_e32 v130, 6, v142
	v_lshl_or_b32 v131, v143, 2, v130
	v_lshlrev_b32_e32 v130, 2, v144
	v_cmp_ne_u32_e32 vcc, 0, v128
	v_cmp_eq_u32_e64 s[0:1], 0, v128
	s_barrier
	s_and_saveexec_b64 s[2:3], s[0:1]
	s_cbranch_execz .LBB0_2054
	v_mad_u64_u32 v[132:133], s[0:1], v131, s26, v[130:131]
	v_add_u32_e32 v128, 0x400, v132
	v_add_u32_e32 v133, 0x1000, v132
	v_add_u32_e32 v134, 0x1400, v132
	v_add_u32_e32 v135, 0x2000, v132
	v_add_u32_e32 v136, 0x2400, v132
	v_add_u32_e32 v138, 0x3200, v132
	ds_write2_b32 v132, v0, v48 offset1:32
	ds_write2_b32 v132, v1, v49 offset0:132 offset1:164
	ds_write2_b32 v128, v2, v50 offset0:8 offset1:40
	ds_write2_b32 v128, v3, v51 offset0:140 offset1:172
	ds_write2_b32 v133, v4, v52 offset0:32 offset1:64
	ds_write2_b32 v133, v5, v53 offset0:164 offset1:196
	ds_write2_b32 v134, v6, v54 offset0:40 offset1:72
	ds_write2_b32 v134, v7, v55 offset0:172 offset1:204
	ds_write2_b32 v135, v8, v56 offset0:64 offset1:96
	ds_write2_b32 v135, v9, v57 offset0:196 offset1:228
	ds_write2_b32 v136, v10, v58 offset0:72 offset1:104
	ds_write2_b32 v136, v11, v59 offset0:204 offset1:236
	v_add_u32_e32 v137, 0x3000, v132
	ds_write2_b32 v138, v13, v61 offset0:100 offset1:132
	v_add_u32_e32 v138, 0x3400, v132
	v_add_u32_e32 v139, 0x3600, v132
	ds_write2_b32 v137, v12, v60 offset0:96 offset1:128
	ds_write2_b32 v138, v14, v62 offset0:104 offset1:136
	ds_write2_b32 v139, v15, v63 offset0:108 offset1:140
	ds_write2_b32 v132, v16, v64 offset0:64 offset1:96
	ds_write2_b32 v132, v17, v65 offset0:196 offset1:228
	ds_write2_b32 v128, v18, v66 offset0:72 offset1:104
	ds_write2_b32 v128, v19, v67 offset0:204 offset1:236
	ds_write2_b32 v133, v20, v68 offset0:96 offset1:128
	v_add_u32_e32 v128, 0x1200, v132
	ds_write2_b32 v128, v21, v69 offset0:100 offset1:132
	ds_write2_b32 v134, v22, v70 offset0:104 offset1:136
	v_add_u32_e32 v128, 0x1600, v132
	ds_write2_b32 v128, v23, v71 offset0:108 offset1:140
	ds_write2_b32 v135, v24, v72 offset0:128 offset1:160
	ds_write2_b32 v136, v25, v73 offset0:4 offset1:36
	ds_write2_b32 v136, v26, v74 offset0:136 offset1:168
	v_add_u32_e32 v128, 0x2800, v132
	ds_write2_b32 v128, v27, v75 offset0:12 offset1:44
	ds_write2_b32 v137, v28, v76 offset0:160 offset1:192
	ds_write2_b32 v138, v29, v77 offset0:36 offset1:68
	ds_write2_b32 v138, v30, v78 offset0:168 offset1:200
	v_add_u32_e32 v128, 0x3800, v132
	ds_write2_b32 v128, v31, v79 offset0:44 offset1:76
	v_add_u32_e32 v128, 0x4000, v132
	v_add_u32_e32 v133, 0x4400, v132
	v_add_u32_e32 v135, 0x5000, v132
	ds_write2_b32 v128, v32, v96 offset0:128 offset1:160
	ds_write2_b32 v133, v33, v97 offset0:4 offset1:36
	ds_write2_b32 v133, v34, v98 offset0:136 offset1:168
	v_add_u32_e32 v134, 0x4800, v132
	ds_write2_b32 v135, v36, v100 offset0:160 offset1:192
	v_add_u32_e32 v135, 0x5400, v132
	v_add_u32_e32 v137, 0x6000, v132
	ds_write2_b32 v134, v35, v99 offset0:12 offset1:44
	ds_write2_b32 v135, v37, v101 offset0:36 offset1:68
	ds_write2_b32 v135, v38, v102 offset0:168 offset1:200
	v_add_u32_e32 v136, 0x5800, v132
	ds_write2_b32 v137, v40, v104 offset0:192 offset1:224
	v_add_u32_e32 v137, 0x6400, v132
	v_add_u32_e32 v139, 0x7200, v132
	v_add_u32_e32 v140, 0x7600, v132
	ds_write2_b32 v136, v39, v103 offset0:44 offset1:76
	ds_write2_b32 v137, v41, v105 offset0:68 offset1:100
	ds_write2_b32 v137, v42, v106 offset0:200 offset1:232
	v_add_u32_e32 v138, 0x6800, v132
	ds_write2_b32 v139, v44, v108 offset0:96 offset1:128
	v_add_u32_e32 v139, 0x7400, v132
	ds_write2_b32 v140, v46, v110 offset0:104 offset1:136
	v_add_u32_e32 v140, 0x7800, v132
	ds_write2_b32 v138, v43, v107 offset0:76 offset1:108
	ds_write2_b32 v139, v45, v109 offset0:100 offset1:132
	ds_write2_b32 v140, v47, v111 offset0:108 offset1:140
	ds_write2_b32 v128, v80, v112 offset0:192 offset1:224
	ds_write2_b32 v133, v81, v113 offset0:68 offset1:100
	ds_write2_b32 v133, v82, v114 offset0:200 offset1:232
	ds_write2_b32 v134, v83, v115 offset0:76 offset1:108
	v_add_u32_e32 v128, 0x5200, v132
	ds_write2_b32 v128, v84, v116 offset0:96 offset1:128
	ds_write2_b32 v135, v85, v117 offset0:100 offset1:132
	v_add_u32_e32 v128, 0x5600, v132
	ds_write2_b32 v128, v86, v118 offset0:104 offset1:136
	ds_write2_b32 v136, v87, v119 offset0:108 offset1:140
	ds_write2_b32 v137, v88, v120 offset1:32
	ds_write2_b32 v137, v89, v121 offset0:132 offset1:164
	ds_write2_b32 v138, v90, v122 offset0:8 offset1:40
	ds_write2_b32 v138, v91, v123 offset0:140 offset1:172
	ds_write2_b32 v139, v92, v124 offset0:32 offset1:64
	ds_write2_b32 v139, v93, v125 offset0:164 offset1:196
	ds_write2_b32 v140, v94, v126 offset0:40 offset1:72
	ds_write2_b32 v140, v95, v127 offset0:172 offset1:204

;   DI u16* y0b() const { return (u16*)(ws + WS_y0b); }
; DI float bflo(unsigned v) { return __uint_as_float(v << 16); }
; DI float bfhi(unsigned v) { return __uint_as_float(v & 0xffff0000u); }
; DI void st_bf4(u16* d, float a, float b, float c, float e) { *(uint2*)d = pack4(a, b, c, e); }
; DI float half_sum(float v) {
;   v += __shfl_xor(v, 16); v += __shfl_xor(v, 8); v += __shfl_xor(v, 4); v += __shfl_xor(v, 2); v += __shfl_xor(v, 1);
;   return v;
; }
; DI float wave_sum(float v) { v = half_sum(v); v += __shfl_xor(v, 32); return v; }
; DI void phase_ln(const Params& p, int layer) {
;     ...
;     float sum = 0.f;
; #pragma unroll
;     for (int i = 0; i < 4; ++i) {
;       typedef __attribute__((ext_vector_type(2))) unsigned u32x2_t;
;       const u32x2_t qq = __builtin_nontemporal_load((const u32x2_t*)(s + lane * 4 + 256 * i));
;       const uint2 q = make_uint2(qq[0], qq[1]);
;       v[i] = make_float4(bflo(q.x), bfhi(q.x), bflo(q.y), bfhi(q.y));
;       sum += v[i].x + v[i].y + v[i].z + v[i].w;
;     }
;     const float mu = wave_sum(sum) * (1.f / 1024.f);
;     float sq = 0.f;
; #pragma unroll
;     for (int i = 0; i < 4; ++i) { v[i].x -= mu; v[i].y -= mu; v[i].z -= mu; v[i].w -= mu; sq += v[i].x * v[i].x + v[i].y * v[i].y + v[i].z * v[i].z + v[i].w * v[i].w; }
;     const float rstd = rsqrtf(wave_sum(sq) * (1.f / 1024.f) + EPS);
; #pragma unroll
;     for (int i = 0; i < 4; ++i) {
;       const int c = lane * 4 + 256 * i;
;       float4 gg = *(const float4*)(g + c), b4 = *(const float4*)(bb + c);
;       float4 y = make_float4(v[i].x * rstd * gg.x + b4.x, v[i].y * rstd * gg.y + b4.y, v[i].z * rstd * gg.z + b4.z, v[i].w * rstd * gg.w + b4.w);
;       if (layer == 0) {
;         st_bf4(p.y0b() + (size_t)row * 1024 + c, y.x, y.y, y.z, y.w);
;       } else {
;         float* d = row < TP ? p.out + OFF_YP + (size_t)row * 1024 + c : p.out + OFF_YS + (size_t)(row - TP) * 1024 + c;
;         st_nt4(d, y);
;       }
.Lln1_nopf:
	v_add_f32_e32 v48, v32, v33
	v_add_f32_e32 v49, v34, v35
	v_add_f32_e32 v50, v36, v37
	v_add_f32_e32 v51, v38, v39
	v_add_f32_e32 v52, v40, v41
	v_add_f32_e32 v53, v42, v43
	v_add_f32_e32 v54, v44, v45
	v_add_f32_e32 v55, v46, v47
	v_add_f32_e32 v48, v48, v49
	v_add_f32_e32 v49, v50, v51
	v_add_f32_e32 v50, v52, v53
	v_add_f32_e32 v51, v54, v55
	v_add_f32_e32 v48, v48, v49
	v_add_f32_e32 v50, v50, v51
	v_add_f32_e32 v48, v48, v50
	s_nop 1
	v_add_f32_dpp v48, v48, v48 row_ror:8 row_mask:0xf bank_mask:0xf
	s_nop 1
	v_add_f32_dpp v48, v48, v48 row_ror:4 row_mask:0xf bank_mask:0xf
	s_nop 1
	v_add_f32_dpp v48, v48, v48 row_ror:2 row_mask:0xf bank_mask:0xf
	s_nop 1
	v_add_f32_dpp v48, v48, v48 row_ror:1 row_mask:0xf bank_mask:0xf
	s_nop 0
	v_readlane_b32 s20, v48, 0
	v_readlane_b32 s21, v48, 16
	v_readlane_b32 s22, v48, 32
	v_readlane_b32 s23, v48, 48
	s_nop 1
	v_mov_b32_e32 v48, s20
	v_add_f32_e32 v48, s21, v48
	v_add_f32_e32 v48, s22, v48
	v_add_f32_e32 v48, s23, v48
	v_mul_f32_e32 v49, 0x3a800000, v48
	v_sub_f32_e32 v32, v32, v49
	v_sub_f32_e32 v33, v33, v49
	v_sub_f32_e32 v34, v34, v49
	v_sub_f32_e32 v35, v35, v49
	v_sub_f32_e32 v36, v36, v49
	v_sub_f32_e32 v37, v37, v49
	v_sub_f32_e32 v38, v38, v49
	v_sub_f32_e32 v39, v39, v49
	v_sub_f32_e32 v40, v40, v49
	v_sub_f32_e32 v41, v41, v49
	v_sub_f32_e32 v42, v42, v49
	v_sub_f32_e32 v43, v43, v49
	v_sub_f32_e32 v44, v44, v49
	v_sub_f32_e32 v45, v45, v49
	v_sub_f32_e32 v46, v46, v49
	v_sub_f32_e32 v47, v47, v49
	v_mul_f32_e32 v50, v32, v32
	v_mul_f32_e32 v51, v33, v33
	v_fmac_f32_e32 v50, v34, v34
	v_fmac_f32_e32 v51, v35, v35
	v_fmac_f32_e32 v50, v36, v36
	v_fmac_f32_e32 v51, v37, v37
	v_fmac_f32_e32 v50, v38, v38
	v_fmac_f32_e32 v51, v39, v39
	v_fmac_f32_e32 v50, v40, v40
	v_fmac_f32_e32 v51, v41, v41
	v_fmac_f32_e32 v50, v42, v42
	v_fmac_f32_e32 v51, v43, v43
	v_fmac_f32_e32 v50, v44, v44
	v_fmac_f32_e32 v51, v45, v45
	v_fmac_f32_e32 v50, v46, v46
	v_fmac_f32_e32 v51, v47, v47
	v_add_f32_e32 v50, v50, v51
	s_nop 1
	v_add_f32_dpp v50, v50, v50 row_ror:8 row_mask:0xf bank_mask:0xf
	s_nop 1
	v_add_f32_dpp v50, v50, v50 row_ror:4 row_mask:0xf bank_mask:0xf
	s_nop 1
	v_add_f32_dpp v50, v50, v50 row_ror:2 row_mask:0xf bank_mask:0xf
	s_nop 1
	v_add_f32_dpp v50, v50, v50 row_ror:1 row_mask:0xf bank_mask:0xf
	s_nop 0
	v_readlane_b32 s20, v50, 0
	v_readlane_b32 s21, v50, 16
	v_readlane_b32 s22, v50, 32
	v_readlane_b32 s23, v50, 48
	s_nop 1
	v_mov_b32_e32 v50, s20
	v_add_f32_e32 v50, s21, v50
	v_add_f32_e32 v50, s22, v50
	v_add_f32_e32 v50, s23, v50
	v_fmamk_f32 v50, v50, 0x3a800000, v18
	v_rsq_f32_e32 v50, v50
	s_nop 0
	v_mul_f32_e32 v32, v32, v50
	v_mul_f32_e32 v33, v33, v50
	v_mul_f32_e32 v34, v34, v50
	v_mul_f32_e32 v35, v35, v50
	v_mul_f32_e32 v36, v36, v50
	v_mul_f32_e32 v37, v37, v50
	v_mul_f32_e32 v38, v38, v50
	v_mul_f32_e32 v39, v39, v50
	v_mul_f32_e32 v40, v40, v50
	v_mul_f32_e32 v41, v41, v50
	v_mul_f32_e32 v42, v42, v50
	v_mul_f32_e32 v43, v43, v50
	v_mul_f32_e32 v44, v44, v50
	v_mul_f32_e32 v45, v45, v50
	v_mul_f32_e32 v46, v46, v50
	v_mul_f32_e32 v47, v47, v50
	v_fma_f32 v96, v32, v64, v80
	v_fma_f32 v97, v33, v65, v81
	v_fma_f32 v98, v34, v66, v82
	v_fma_f32 v99, v35, v67, v83
	v_fma_f32 v100, v36, v68, v84
	v_fma_f32 v101, v37, v69, v85
	v_fma_f32 v102, v38, v70, v86
	v_fma_f32 v103, v39, v71, v87
	v_fma_f32 v104, v40, v72, v88
	v_fma_f32 v105, v41, v73, v89
	v_fma_f32 v106, v42, v74, v90
	v_fma_f32 v107, v43, v75, v91
	v_fma_f32 v108, v44, v76, v92
	v_fma_f32 v109, v45, v77, v93
	v_fma_f32 v110, v46, v78, v94
	v_fma_f32 v111, v47, v79, v95
	v_mov_b32_e32 v4, s6
	v_mov_b32_e32 v5, s7
	v_add_co_u32_e32 v4, vcc, v4, v2
	s_nop 1
	v_addc_co_u32_e32 v5, vcc, 0, v5, vcc
	global_store_dwordx4 v[4:5], v[96:99], off nt
	global_store_dwordx4 v[4:5], v[100:103], off offset:1024 nt
	global_store_dwordx4 v[4:5], v[104:107], off offset:2048 nt
	global_store_dwordx4 v[4:5], v[108:111], off offset:3072 nt
	s_cmp_lg_u32 s9, 0
	s_cbranch_scc1 .Lln1_loop

; __global__ void __launch_bounds__(256, 2) fwd_megakernel(Params p) {
;   __shared__ __attribute__((aligned(16))) char smem[SMEM_TOTAL];
	.amdhsa_kernel _Z14fwd_megakernel6Params
		.amdhsa_group_segment_fixed_size 75840
		.amdhsa_private_segment_fixed_size 0
		.amdhsa_kernarg_size 472
		.amdhsa_user_sgpr_count 2
		.amdhsa_user_sgpr_dispatch_ptr 0
		.amdhsa_user_sgpr_queue_ptr 0
		.amdhsa_user_sgpr_kernarg_segment_ptr 1
		.amdhsa_user_sgpr_dispatch_id 0
		.amdhsa_user_sgpr_kernarg_preload_length 0
		.amdhsa_user_sgpr_kernarg_preload_offset 0
		.amdhsa_user_sgpr_private_segment_size 0
		.amdhsa_uses_dynamic_stack 0
		.amdhsa_enable_private_segment 0
		.amdhsa_system_sgpr_workgroup_id_x 1
		.amdhsa_system_sgpr_workgroup_id_y 0
		.amdhsa_system_sgpr_workgroup_id_z 0
		.amdhsa_system_sgpr_workgroup_info 0
		.amdhsa_system_vgpr_workitem_id 2
		.amdhsa_next_free_vgpr 248
		.amdhsa_next_free_sgpr 102
		.amdhsa_accum_offset 248
		.amdhsa_reserve_vcc 1
		.amdhsa_float_round_mode_32 0
		.amdhsa_float_round_mode_16_64 0
		.amdhsa_float_denorm_mode_32 3
		.amdhsa_float_denorm_mode_16_64 3
		.amdhsa_dx10_clamp 1
		.amdhsa_ieee_mode 1
		.amdhsa_fp16_overflow 0
		.amdhsa_tg_split 0
		.amdhsa_exception_fp_ieee_invalid_op 0
		.amdhsa_exception_fp_denorm_src 0
		.amdhsa_exception_fp_ieee_div_zero 0
		.amdhsa_exception_fp_ieee_overflow 0
		.amdhsa_exception_fp_ieee_underflow 0
		.amdhsa_exception_fp_ieee_inexact 0
		.amdhsa_exception_int_div_zero 0
	.end_amdhsa_kernel

; __global__ void __launch_bounds__(256, 2) fwd_megakernel(Params p) {
;   __shared__ __attribute__((aligned(16))) char smem[SMEM_TOTAL];
amdhsa.kernels:
  - .agpr_count:     0
    .args:
      - .offset:         0
        .size:           216
        .value_kind:     by_value
      - .offset:         216
        .size:           4
        .value_kind:     hidden_block_count_x
      - .offset:         220
        .size:           4
        .value_kind:     hidden_block_count_y
      - .offset:         224
        .size:           4
        .value_kind:     hidden_block_count_z
      - .offset:         228
        .size:           2
        .value_kind:     hidden_group_size_x
      - .offset:         230
        .size:           2
        .value_kind:     hidden_group_size_y
      - .offset:         232
        .size:           2
        .value_kind:     hidden_group_size_z
      - .offset:         234
        .size:           2
        .value_kind:     hidden_remainder_x
      - .offset:         236
        .size:           2
        .value_kind:     hidden_remainder_y
      - .offset:         238
        .size:           2
        .value_kind:     hidden_remainder_z
      - .offset:         256
        .size:           8
        .value_kind:     hidden_global_offset_x
      - .offset:         264
        .size:           8
        .value_kind:     hidden_global_offset_y
      - .offset:         272
        .size:           8
        .value_kind:     hidden_global_offset_z
      - .offset:         280
        .size:           2
        .value_kind:     hidden_grid_dims
      - .offset:         304
        .size:           8
        .value_kind:     hidden_multigrid_sync_arg
    .group_segment_fixed_size: 75840
    .kernarg_segment_align: 8
    .kernarg_segment_size: 472
    .language:       OpenCL C
    .language_version:
      - 2
      - 0
    .max_flat_workgroup_size: 256
    .name:           _Z14fwd_megakernel6Params
    .private_segment_fixed_size: 0
    .sgpr_count:     108
    .sgpr_spill_count: 97
    .symbol:         _Z14fwd_megakernel6Params.kd
    .uniform_work_group_size: 1
    .uses_dynamic_stack: false
    .vgpr_count:     248
    .vgpr_spill_count: 0
    .wavefront_size: 64
